# resid tiles (DN1, OUT, DN2) rewritten by hand: LDS-DMA 2-stage ring, BK=64, XOR-swizzled LDS rows, register double-buffered fragments, 1 barrier per K-step, de-serialised X+=acc epilogue; LDS 65536
# speedup vs baseline: 1.0533x; 1.0533x over previous
.LBB0_99:
	s_cmpk_gt_u32 s11, 0x3bf
	s_cselect_b64 s[2:3], -1, 0
	s_and_b64 vcc, exec, s[2:3]
	s_barrier
	s_waitcnt vmcnt(9)
	ds_write_b128 v192, v[124:127]
	ds_write_b128 v192, v[120:123] offset:4608
	ds_write_b128 v192, v[128:131] offset:9216
	s_waitcnt vmcnt(7)
	ds_write_b128 v192, v[132:135] offset:13824
	ds_write_b128 v192, v[136:139] offset:18432
	s_waitcnt vmcnt(6)
	ds_write_b128 v192, v[140:143] offset:23040
	s_waitcnt vmcnt(5)
	ds_write_b128 v192, v[144:147] offset:27648
	s_waitcnt vmcnt(4)
	ds_write_b128 v192, v[148:151] offset:32256
	s_waitcnt vmcnt(3)
	ds_write_b128 v192, v[152:155] offset:36864
	s_waitcnt vmcnt(2)
	ds_write_b128 v192, v[156:159] offset:41472
	s_waitcnt vmcnt(1)
	ds_write_b128 v192, v[160:163] offset:46080
	s_waitcnt vmcnt(0)
	ds_write_b128 v192, v[164:167] offset:50688
	s_waitcnt lgkmcnt(0)
	s_barrier
	s_cbranch_vccnz .LBB0_98
	v_lshl_add_u64 v[128:129], v[196:197], 0, v[200:201]
	v_add_co_u32_e32 v120, vcc, 0x7650000, v128
	v_lshl_add_u64 v[160:161], v[198:199], 0, v[200:201]
	s_nop 0
	v_addc_co_u32_e32 v121, vcc, 0, v129, vcc
	v_add_co_u32_e32 v122, vcc, 0x7660000, v128
	s_nop 1
	v_addc_co_u32_e32 v123, vcc, 0, v129, vcc
	v_add_co_u32_e32 v130, vcc, 0x7670000, v128
	global_load_dwordx4 v[124:127], v[120:121], off offset:128
	s_nop 0
	global_load_dwordx4 v[120:123], v[122:123], off offset:128
	v_addc_co_u32_e32 v131, vcc, 0, v129, vcc
	v_add_co_u32_e32 v132, vcc, 0x7680000, v128
	s_nop 1
	v_addc_co_u32_e32 v133, vcc, 0, v129, vcc
	v_add_co_u32_e32 v136, vcc, 0x4490000, v160
	global_load_dwordx4 v[128:131], v[130:131], off offset:128
	s_nop 0
	global_load_dwordx4 v[132:135], v[132:133], off offset:128
	v_addc_co_u32_e32 v137, vcc, 0, v161, vcc
	v_add_co_u32_e32 v140, vcc, 0x44a0000, v160
	s_nop 1
	v_addc_co_u32_e32 v141, vcc, 0, v161, vcc
	v_add_co_u32_e32 v144, vcc, 0x44b0000, v160
	global_load_dwordx4 v[136:139], v[136:137], off offset:128
	s_nop 0
	global_load_dwordx4 v[140:143], v[140:141], off offset:128
	v_addc_co_u32_e32 v145, vcc, 0, v161, vcc
	v_add_co_u32_e32 v148, vcc, 0x44c0000, v160
	s_nop 1
	v_addc_co_u32_e32 v149, vcc, 0, v161, vcc
	v_add_co_u32_e32 v152, vcc, 0x44d0000, v160
	global_load_dwordx4 v[144:147], v[144:145], off offset:128
	s_nop 0
	global_load_dwordx4 v[148:151], v[148:149], off offset:128
	v_addc_co_u32_e32 v153, vcc, 0, v161, vcc
	v_add_co_u32_e32 v156, vcc, 0x44e0000, v160
	s_nop 1
	v_addc_co_u32_e32 v157, vcc, 0, v161, vcc
	v_add_co_u32_e32 v162, vcc, 0x44f0000, v160
	global_load_dwordx4 v[152:155], v[152:153], off offset:128
	s_nop 0
	global_load_dwordx4 v[156:159], v[156:157], off offset:128
	v_addc_co_u32_e32 v163, vcc, 0, v161, vcc
	v_add_co_u32_e32 v164, vcc, 0x4500000, v160
	s_nop 1
	v_addc_co_u32_e32 v165, vcc, 0, v161, vcc
	global_load_dwordx4 v[160:163], v[162:163], off offset:128
	s_nop 0
	global_load_dwordx4 v[164:167], v[164:165], off offset:128
	s_branch .LBB0_98
.LBB0_102:
	s_add_i32 s4, s4, s33
	v_readlane_b32 s2, v254, 32
	s_cmp_ge_i32 s4, s2
	s_cbranch_scc1 .LBB0_74

.LBB0_105:
	s_andn2_b64 vcc, exec, s[2:3]
	s_cbranch_vccnz .LBB0_102
	v_and_b32_e32 v128, 63, v216
	v_lshrrev_b32_e32 v129, 6, v216
	v_lshrrev_b32_e32 v130, 3, v128
	v_and_b32_e32 v131, 7, v128
	v_readfirstlane_b32 s12, v129
	v_lshrrev_b32_e32 v132, 1, v130
	v_lshrrev_b32_e32 v133, 2, v130
	v_xor_b32_e32 v134, v132, v133
	v_xor_b32_e32 v135, 5, v134
	v_xor_b32_e32 v134, v131, v134
	v_xor_b32_e32 v135, v131, v135
	v_lshlrev_b32_e32 v134, 4, v134
	v_lshlrev_b32_e32 v135, 4, v135
	v_lshl_add_u32 v136, v129, 5, v130
	v_mul_u32_u24_e32 v137, 0x1600, v136
	v_add_u32_e32 v192, v137, v134
	v_add_u32_e32 v193, v137, v135
	v_add_u32_e32 v193, 0xb000, v193
	v_add_u32_e32 v194, 0x16000, v192
	v_add_u32_e32 v195, 0x16000, v193
	v_and_b32_e32 v138, 15, v128
	v_lshrrev_b32_e32 v139, 4, v128
	v_lshrrev_b32_e32 v140, 1, v138
	v_lshrrev_b32_e32 v141, 2, v138
	v_lshrrev_b32_e32 v142, 3, v138
	v_xor_b32_e32 v141, v141, v142
	v_and_b32_e32 v141, 1, v141
	v_xor_b32_e32 v140, v140, v141
	v_xor_b32_e32 v140, v139, v140
	v_lshlrev_b32_e32 v140, 4, v140
	v_lshl_add_u32 v140, v138, 7, v140
	v_lshrrev_b32_e32 v141, 1, v129
	v_and_b32_e32 v142, 1, v129
	v_lshl_add_u32 v196, v141, 13, v140
	v_xor_b32_e32 v197, 64, v196
	v_lshl_add_u32 v198, v142, 13, v140
	v_xor_b32_e32 v199, 64, v198
	s_lshl_b32 s12, s12, 12
	s_mul_hi_u32 s15, s30, 0xb0000
	s_mul_i32 s14, s30, 0xb0000
	s_add_u32 s2, s28, s14
	s_addc_u32 s3, s29, s15
	s_mul_hi_u32 s15, s31, 0xb0000
	s_mul_i32 s14, s31, 0xb0000
	s_add_u32 s10, s52, s14
	s_addc_u32 s11, s53, s15
	s_add_u32 m0, s12, 0x0
	s_nop 0
	global_load_lds_dwordx4 v192, s[2:3]
	s_add_u32 m0, s12, 0x400
	s_nop 0
	global_load_lds_dwordx4 v193, s[2:3]
	s_add_u32 m0, s12, 0x800
	s_nop 0
	global_load_lds_dwordx4 v194, s[2:3]
	s_add_u32 m0, s12, 0xc00
	s_nop 0
	global_load_lds_dwordx4 v195, s[2:3]
	s_add_u32 m0, s12, 0x4000
	s_nop 0
	global_load_lds_dwordx4 v192, s[10:11]
	s_add_u32 m0, s12, 0x4400
	s_nop 0
	global_load_lds_dwordx4 v193, s[10:11]
	s_add_u32 m0, s12, 0x4800
	s_nop 0
	global_load_lds_dwordx4 v194, s[10:11]
	s_add_u32 m0, s12, 0x4c00
	s_nop 0
	global_load_lds_dwordx4 v195, s[10:11]
	s_add_u32 s2, s2, 0x80
	s_addc_u32 s3, s3, 0
	s_add_u32 s10, s10, 0x80
	s_addc_u32 s11, s11, 0
	v_mov_b32_e32 v0, 0
	v_mov_b32_e32 v1, 0
	v_mov_b32_e32 v2, 0
	v_mov_b32_e32 v3, 0
	v_mov_b32_e32 v4, 0
	v_mov_b32_e32 v5, 0
	v_mov_b32_e32 v6, 0
	v_mov_b32_e32 v7, 0
	v_mov_b32_e32 v8, 0
	v_mov_b32_e32 v9, 0
	v_mov_b32_e32 v10, 0
	v_mov_b32_e32 v11, 0
	v_mov_b32_e32 v12, 0
	v_mov_b32_e32 v13, 0
	v_mov_b32_e32 v14, 0
	v_mov_b32_e32 v15, 0
	v_mov_b32_e32 v16, 0
	v_mov_b32_e32 v17, 0
	v_mov_b32_e32 v18, 0
	v_mov_b32_e32 v19, 0
	v_mov_b32_e32 v20, 0
	v_mov_b32_e32 v21, 0
	v_mov_b32_e32 v22, 0
	v_mov_b32_e32 v23, 0
	v_mov_b32_e32 v24, 0
	v_mov_b32_e32 v25, 0
	v_mov_b32_e32 v26, 0
	v_mov_b32_e32 v27, 0
	v_mov_b32_e32 v28, 0
	v_mov_b32_e32 v29, 0
	v_mov_b32_e32 v30, 0
	v_mov_b32_e32 v31, 0
	v_mov_b32_e32 v32, 0
	v_mov_b32_e32 v33, 0
	v_mov_b32_e32 v34, 0
	v_mov_b32_e32 v35, 0
	v_mov_b32_e32 v36, 0
	v_mov_b32_e32 v37, 0
	v_mov_b32_e32 v38, 0
	v_mov_b32_e32 v39, 0
	v_mov_b32_e32 v40, 0
	v_mov_b32_e32 v41, 0
	v_mov_b32_e32 v42, 0
	v_mov_b32_e32 v43, 0
	v_mov_b32_e32 v44, 0
	v_mov_b32_e32 v45, 0
	v_mov_b32_e32 v46, 0
	v_mov_b32_e32 v47, 0
	v_mov_b32_e32 v48, 0
	v_mov_b32_e32 v49, 0
	v_mov_b32_e32 v50, 0
	v_mov_b32_e32 v51, 0
	v_mov_b32_e32 v52, 0
	v_mov_b32_e32 v53, 0
	v_mov_b32_e32 v54, 0
	v_mov_b32_e32 v55, 0
	v_mov_b32_e32 v56, 0
	v_mov_b32_e32 v57, 0
	v_mov_b32_e32 v58, 0
	v_mov_b32_e32 v59, 0
	v_mov_b32_e32 v60, 0
	v_mov_b32_e32 v61, 0
	v_mov_b32_e32 v62, 0
	v_mov_b32_e32 v63, 0
	s_waitcnt vmcnt(0)
	s_barrier
	s_add_u32 m0, s12, 0x8000
	ds_read_b128 v[64:67], v196 offset:0
	global_load_lds_dwordx4 v192, s[2:3]
	s_add_u32 m0, s12, 0x8400
	ds_read_b128 v[68:71], v196 offset:2048
	global_load_lds_dwordx4 v193, s[2:3]
	s_add_u32 m0, s12, 0x8800
	ds_read_b128 v[72:75], v196 offset:4096
	global_load_lds_dwordx4 v194, s[2:3]
	s_add_u32 m0, s12, 0x8c00
	ds_read_b128 v[76:79], v196 offset:6144
	global_load_lds_dwordx4 v195, s[2:3]
	s_add_u32 m0, s12, 0xc000
	ds_read_b128 v[96:99], v198 offset:16384
	global_load_lds_dwordx4 v192, s[10:11]
	s_add_u32 m0, s12, 0xc400
	ds_read_b128 v[100:103], v198 offset:18432
	global_load_lds_dwordx4 v193, s[10:11]
	s_add_u32 m0, s12, 0xc800
	ds_read_b128 v[104:107], v198 offset:20480
	global_load_lds_dwordx4 v194, s[10:11]
	s_add_u32 m0, s12, 0xcc00
	ds_read_b128 v[108:111], v198 offset:22528
	global_load_lds_dwordx4 v195, s[10:11]
	s_add_u32 s2, s2, 0x80
	s_addc_u32 s3, s3, 0
	s_add_u32 s10, s10, 0x80
	s_addc_u32 s11, s11, 0
	ds_read_b128 v[80:83], v197 offset:0
	ds_read_b128 v[84:87], v197 offset:2048
	ds_read_b128 v[88:91], v197 offset:4096
	ds_read_b128 v[92:95], v197 offset:6144
	ds_read_b128 v[112:115], v199 offset:16384
	ds_read_b128 v[116:119], v199 offset:18432
	ds_read_b128 v[120:123], v199 offset:20480
	ds_read_b128 v[124:127], v199 offset:22528
	s_waitcnt lgkmcnt(0)
	s_mov_b32 s13, 21
.Lrs1_loop:
	s_waitcnt vmcnt(0)
	s_barrier
	v_mfma_f32_16x16x32_bf16 v[0:3], v[96:99], v[64:67], v[0:3]
	s_add_u32 m0, s12, 0x0
	ds_read_b128 v[128:131], v196 offset:32768
	v_mfma_f32_16x16x32_bf16 v[4:7], v[100:103], v[64:67], v[4:7]
	global_load_lds_dwordx4 v192, s[2:3]
	s_add_u32 m0, s12, 0x400
	v_mfma_f32_16x16x32_bf16 v[8:11], v[104:107], v[64:67], v[8:11]
	global_load_lds_dwordx4 v193, s[2:3]
	s_add_u32 m0, s12, 0x800
	ds_read_b128 v[132:135], v196 offset:34816
	v_mfma_f32_16x16x32_bf16 v[12:15], v[108:111], v[64:67], v[12:15]
	global_load_lds_dwordx4 v194, s[2:3]
	s_add_u32 m0, s12, 0xc00
	v_mfma_f32_16x16x32_bf16 v[16:19], v[96:99], v[68:71], v[16:19]
	global_load_lds_dwordx4 v195, s[2:3]
	s_add_u32 m0, s12, 0x4000
	ds_read_b128 v[136:139], v196 offset:36864
	v_mfma_f32_16x16x32_bf16 v[20:23], v[100:103], v[68:71], v[20:23]
	global_load_lds_dwordx4 v192, s[10:11]
	s_add_u32 m0, s12, 0x4400
	v_mfma_f32_16x16x32_bf16 v[24:27], v[104:107], v[68:71], v[24:27]
	global_load_lds_dwordx4 v193, s[10:11]
	s_add_u32 m0, s12, 0x4800
	ds_read_b128 v[140:143], v196 offset:38912
	v_mfma_f32_16x16x32_bf16 v[28:31], v[108:111], v[68:71], v[28:31]
	global_load_lds_dwordx4 v194, s[10:11]
	s_add_u32 m0, s12, 0x4c00
	v_mfma_f32_16x16x32_bf16 v[32:35], v[96:99], v[72:75], v[32:35]
	global_load_lds_dwordx4 v195, s[10:11]
	ds_read_b128 v[160:163], v198 offset:49152
	v_mfma_f32_16x16x32_bf16 v[36:39], v[100:103], v[72:75], v[36:39]
	s_add_u32 s2, s2, 0x80
	s_addc_u32 s3, s3, 0
	v_mfma_f32_16x16x32_bf16 v[40:43], v[104:107], v[72:75], v[40:43]
	s_add_u32 s10, s10, 0x80
	s_addc_u32 s11, s11, 0
	ds_read_b128 v[164:167], v198 offset:51200
	v_mfma_f32_16x16x32_bf16 v[44:47], v[108:111], v[72:75], v[44:47]
	v_mfma_f32_16x16x32_bf16 v[48:51], v[96:99], v[76:79], v[48:51]
	ds_read_b128 v[168:171], v198 offset:53248
	v_mfma_f32_16x16x32_bf16 v[52:55], v[100:103], v[76:79], v[52:55]
	v_mfma_f32_16x16x32_bf16 v[56:59], v[104:107], v[76:79], v[56:59]
	ds_read_b128 v[172:175], v198 offset:55296
	v_mfma_f32_16x16x32_bf16 v[60:63], v[108:111], v[76:79], v[60:63]
	v_mfma_f32_16x16x32_bf16 v[0:3], v[112:115], v[80:83], v[0:3]
	ds_read_b128 v[144:147], v197 offset:32768
	v_mfma_f32_16x16x32_bf16 v[4:7], v[116:119], v[80:83], v[4:7]
	v_mfma_f32_16x16x32_bf16 v[8:11], v[120:123], v[80:83], v[8:11]
	ds_read_b128 v[148:151], v197 offset:34816
	v_mfma_f32_16x16x32_bf16 v[12:15], v[124:127], v[80:83], v[12:15]
	v_mfma_f32_16x16x32_bf16 v[16:19], v[112:115], v[84:87], v[16:19]
	ds_read_b128 v[152:155], v197 offset:36864
	v_mfma_f32_16x16x32_bf16 v[20:23], v[116:119], v[84:87], v[20:23]
	v_mfma_f32_16x16x32_bf16 v[24:27], v[120:123], v[84:87], v[24:27]
	ds_read_b128 v[156:159], v197 offset:38912
	v_mfma_f32_16x16x32_bf16 v[28:31], v[124:127], v[84:87], v[28:31]
	v_mfma_f32_16x16x32_bf16 v[32:35], v[112:115], v[88:91], v[32:35]
	ds_read_b128 v[176:179], v199 offset:49152
	v_mfma_f32_16x16x32_bf16 v[36:39], v[116:119], v[88:91], v[36:39]
	v_mfma_f32_16x16x32_bf16 v[40:43], v[120:123], v[88:91], v[40:43]
	ds_read_b128 v[180:183], v199 offset:51200
	v_mfma_f32_16x16x32_bf16 v[44:47], v[124:127], v[88:91], v[44:47]
	v_mfma_f32_16x16x32_bf16 v[48:51], v[112:115], v[92:95], v[48:51]
	ds_read_b128 v[184:187], v199 offset:53248
	v_mfma_f32_16x16x32_bf16 v[52:55], v[116:119], v[92:95], v[52:55]
	v_mfma_f32_16x16x32_bf16 v[56:59], v[120:123], v[92:95], v[56:59]
	ds_read_b128 v[188:191], v199 offset:55296
	v_mfma_f32_16x16x32_bf16 v[60:63], v[124:127], v[92:95], v[60:63]
	s_waitcnt lgkmcnt(0)
	s_waitcnt vmcnt(0)
	s_barrier
	v_mfma_f32_16x16x32_bf16 v[0:3], v[160:163], v[128:131], v[0:3]
	s_add_u32 m0, s12, 0x8000
	ds_read_b128 v[64:67], v196 offset:0
	v_mfma_f32_16x16x32_bf16 v[4:7], v[164:167], v[128:131], v[4:7]
	global_load_lds_dwordx4 v192, s[2:3]
	s_add_u32 m0, s12, 0x8400
	v_mfma_f32_16x16x32_bf16 v[8:11], v[168:171], v[128:131], v[8:11]
	global_load_lds_dwordx4 v193, s[2:3]
	s_add_u32 m0, s12, 0x8800
	ds_read_b128 v[68:71], v196 offset:2048
	v_mfma_f32_16x16x32_bf16 v[12:15], v[172:175], v[128:131], v[12:15]
	global_load_lds_dwordx4 v194, s[2:3]
	s_add_u32 m0, s12, 0x8c00
	v_mfma_f32_16x16x32_bf16 v[16:19], v[160:163], v[132:135], v[16:19]
	global_load_lds_dwordx4 v195, s[2:3]
	s_add_u32 m0, s12, 0xc000
	ds_read_b128 v[72:75], v196 offset:4096
	v_mfma_f32_16x16x32_bf16 v[20:23], v[164:167], v[132:135], v[20:23]
	global_load_lds_dwordx4 v192, s[10:11]
	s_add_u32 m0, s12, 0xc400
	v_mfma_f32_16x16x32_bf16 v[24:27], v[168:171], v[132:135], v[24:27]
	global_load_lds_dwordx4 v193, s[10:11]
	s_add_u32 m0, s12, 0xc800
	ds_read_b128 v[76:79], v196 offset:6144
	v_mfma_f32_16x16x32_bf16 v[28:31], v[172:175], v[132:135], v[28:31]
	global_load_lds_dwordx4 v194, s[10:11]
	s_add_u32 m0, s12, 0xcc00
	v_mfma_f32_16x16x32_bf16 v[32:35], v[160:163], v[136:139], v[32:35]
	global_load_lds_dwordx4 v195, s[10:11]
	ds_read_b128 v[96:99], v198 offset:16384
	v_mfma_f32_16x16x32_bf16 v[36:39], v[164:167], v[136:139], v[36:39]
	s_add_u32 s2, s2, 0x80
	s_addc_u32 s3, s3, 0
	v_mfma_f32_16x16x32_bf16 v[40:43], v[168:171], v[136:139], v[40:43]
	s_add_u32 s10, s10, 0x80
	s_addc_u32 s11, s11, 0
	ds_read_b128 v[100:103], v198 offset:18432
	v_mfma_f32_16x16x32_bf16 v[44:47], v[172:175], v[136:139], v[44:47]
	v_mfma_f32_16x16x32_bf16 v[48:51], v[160:163], v[140:143], v[48:51]
	ds_read_b128 v[104:107], v198 offset:20480
	v_mfma_f32_16x16x32_bf16 v[52:55], v[164:167], v[140:143], v[52:55]
	v_mfma_f32_16x16x32_bf16 v[56:59], v[168:171], v[140:143], v[56:59]
	ds_read_b128 v[108:111], v198 offset:22528
	v_mfma_f32_16x16x32_bf16 v[60:63], v[172:175], v[140:143], v[60:63]
	v_mfma_f32_16x16x32_bf16 v[0:3], v[176:179], v[144:147], v[0:3]
	ds_read_b128 v[80:83], v197 offset:0
	v_mfma_f32_16x16x32_bf16 v[4:7], v[180:183], v[144:147], v[4:7]
	v_mfma_f32_16x16x32_bf16 v[8:11], v[184:187], v[144:147], v[8:11]
	ds_read_b128 v[84:87], v197 offset:2048
	v_mfma_f32_16x16x32_bf16 v[12:15], v[188:191], v[144:147], v[12:15]
	v_mfma_f32_16x16x32_bf16 v[16:19], v[176:179], v[148:151], v[16:19]
	ds_read_b128 v[88:91], v197 offset:4096
	v_mfma_f32_16x16x32_bf16 v[20:23], v[180:183], v[148:151], v[20:23]
	v_mfma_f32_16x16x32_bf16 v[24:27], v[184:187], v[148:151], v[24:27]
	ds_read_b128 v[92:95], v197 offset:6144
	v_mfma_f32_16x16x32_bf16 v[28:31], v[188:191], v[148:151], v[28:31]
	v_mfma_f32_16x16x32_bf16 v[32:35], v[176:179], v[152:155], v[32:35]
	ds_read_b128 v[112:115], v199 offset:16384
	v_mfma_f32_16x16x32_bf16 v[36:39], v[180:183], v[152:155], v[36:39]
	v_mfma_f32_16x16x32_bf16 v[40:43], v[184:187], v[152:155], v[40:43]
	ds_read_b128 v[116:119], v199 offset:18432
	v_mfma_f32_16x16x32_bf16 v[44:47], v[188:191], v[152:155], v[44:47]
	v_mfma_f32_16x16x32_bf16 v[48:51], v[176:179], v[156:159], v[48:51]
	ds_read_b128 v[120:123], v199 offset:20480
	v_mfma_f32_16x16x32_bf16 v[52:55], v[180:183], v[156:159], v[52:55]
	v_mfma_f32_16x16x32_bf16 v[56:59], v[184:187], v[156:159], v[56:59]
	ds_read_b128 v[124:127], v199 offset:22528
	v_mfma_f32_16x16x32_bf16 v[60:63], v[188:191], v[156:159], v[60:63]
	s_waitcnt lgkmcnt(0)
	s_sub_u32 s13, s13, 1
	s_cmp_lg_u32 s13, 0
	s_cbranch_scc1 .Lrs1_loop
	s_waitcnt vmcnt(0)
	s_barrier
	v_mfma_f32_16x16x32_bf16 v[0:3], v[96:99], v[64:67], v[0:3]
	ds_read_b128 v[128:131], v196 offset:32768
	v_mfma_f32_16x16x32_bf16 v[4:7], v[100:103], v[64:67], v[4:7]
	v_mfma_f32_16x16x32_bf16 v[8:11], v[104:107], v[64:67], v[8:11]
	ds_read_b128 v[132:135], v196 offset:34816
	v_mfma_f32_16x16x32_bf16 v[12:15], v[108:111], v[64:67], v[12:15]
	v_mfma_f32_16x16x32_bf16 v[16:19], v[96:99], v[68:71], v[16:19]
	ds_read_b128 v[136:139], v196 offset:36864
	v_mfma_f32_16x16x32_bf16 v[20:23], v[100:103], v[68:71], v[20:23]
	v_mfma_f32_16x16x32_bf16 v[24:27], v[104:107], v[68:71], v[24:27]
	ds_read_b128 v[140:143], v196 offset:38912
	v_mfma_f32_16x16x32_bf16 v[28:31], v[108:111], v[68:71], v[28:31]
	v_mfma_f32_16x16x32_bf16 v[32:35], v[96:99], v[72:75], v[32:35]
	ds_read_b128 v[160:163], v198 offset:49152
	v_mfma_f32_16x16x32_bf16 v[36:39], v[100:103], v[72:75], v[36:39]
	v_mfma_f32_16x16x32_bf16 v[40:43], v[104:107], v[72:75], v[40:43]
	ds_read_b128 v[164:167], v198 offset:51200
	v_mfma_f32_16x16x32_bf16 v[44:47], v[108:111], v[72:75], v[44:47]
	v_mfma_f32_16x16x32_bf16 v[48:51], v[96:99], v[76:79], v[48:51]
	ds_read_b128 v[168:171], v198 offset:53248
	v_mfma_f32_16x16x32_bf16 v[52:55], v[100:103], v[76:79], v[52:55]
	v_mfma_f32_16x16x32_bf16 v[56:59], v[104:107], v[76:79], v[56:59]
	ds_read_b128 v[172:175], v198 offset:55296
	v_mfma_f32_16x16x32_bf16 v[60:63], v[108:111], v[76:79], v[60:63]
	v_mfma_f32_16x16x32_bf16 v[0:3], v[112:115], v[80:83], v[0:3]
	ds_read_b128 v[144:147], v197 offset:32768
	v_mfma_f32_16x16x32_bf16 v[4:7], v[116:119], v[80:83], v[4:7]
	v_mfma_f32_16x16x32_bf16 v[8:11], v[120:123], v[80:83], v[8:11]
	ds_read_b128 v[148:151], v197 offset:34816
	v_mfma_f32_16x16x32_bf16 v[12:15], v[124:127], v[80:83], v[12:15]
	v_mfma_f32_16x16x32_bf16 v[16:19], v[112:115], v[84:87], v[16:19]
	ds_read_b128 v[152:155], v197 offset:36864
	v_mfma_f32_16x16x32_bf16 v[20:23], v[116:119], v[84:87], v[20:23]
	v_mfma_f32_16x16x32_bf16 v[24:27], v[120:123], v[84:87], v[24:27]
	ds_read_b128 v[156:159], v197 offset:38912
	v_mfma_f32_16x16x32_bf16 v[28:31], v[124:127], v[84:87], v[28:31]
	v_mfma_f32_16x16x32_bf16 v[32:35], v[112:115], v[88:91], v[32:35]
	ds_read_b128 v[176:179], v199 offset:49152
	v_mfma_f32_16x16x32_bf16 v[36:39], v[116:119], v[88:91], v[36:39]
	v_mfma_f32_16x16x32_bf16 v[40:43], v[120:123], v[88:91], v[40:43]
	ds_read_b128 v[180:183], v199 offset:51200
	v_mfma_f32_16x16x32_bf16 v[44:47], v[124:127], v[88:91], v[44:47]
	v_mfma_f32_16x16x32_bf16 v[48:51], v[112:115], v[92:95], v[48:51]
	ds_read_b128 v[184:187], v199 offset:53248
	v_mfma_f32_16x16x32_bf16 v[52:55], v[116:119], v[92:95], v[52:55]
	v_mfma_f32_16x16x32_bf16 v[56:59], v[120:123], v[92:95], v[56:59]
	ds_read_b128 v[188:191], v199 offset:55296
	v_mfma_f32_16x16x32_bf16 v[60:63], v[124:127], v[92:95], v[60:63]
	s_waitcnt lgkmcnt(0)
	v_readlane_b32 s2, v253, 6
	v_readlane_b32 s3, v253, 7
	s_lshl_b32 s14, s30, 19
	s_lshl_b32 s10, s31, 9
	s_add_u32 s14, s14, s10
	s_add_u32 s2, s2, s14
	s_addc_u32 s3, s3, 0
	v_and_b32_e32 v196, 63, v216
	v_lshrrev_b32_e32 v197, 6, v216
	v_and_b32_e32 v198, 15, v196
	v_lshrrev_b32_e32 v196, 4, v196
	v_lshlrev_b32_e32 v196, 4, v196
	v_lshl_add_u32 v196, v198, 12, v196
	v_and_b32_e32 v198, 1, v197
	v_lshl_add_u32 v196, v198, 8, v196
	v_lshrrev_b32_e32 v197, 1, v197
	v_lshl_add_u32 v192, v197, 18, v196
	v_add_u32_e32 v193, 0x10000, v192
	v_add_u32_e32 v194, 0x20000, v192
	v_add_u32_e32 v195, 0x30000, v192
	s_nop 1
	global_load_dwordx4 v[64:67], v192, s[2:3]
	global_load_dwordx4 v[68:71], v192, s[2:3] offset:64
	global_load_dwordx4 v[72:75], v192, s[2:3] offset:128
	global_load_dwordx4 v[76:79], v192, s[2:3] offset:192
	global_load_dwordx4 v[80:83], v193, s[2:3]
	global_load_dwordx4 v[84:87], v193, s[2:3] offset:64
	global_load_dwordx4 v[88:91], v193, s[2:3] offset:128
	global_load_dwordx4 v[92:95], v193, s[2:3] offset:192
	global_load_dwordx4 v[96:99], v194, s[2:3]
	global_load_dwordx4 v[100:103], v194, s[2:3] offset:64
	global_load_dwordx4 v[104:107], v194, s[2:3] offset:128
	global_load_dwordx4 v[108:111], v194, s[2:3] offset:192
	global_load_dwordx4 v[112:115], v195, s[2:3]
	global_load_dwordx4 v[116:119], v195, s[2:3] offset:64
	global_load_dwordx4 v[120:123], v195, s[2:3] offset:128
	global_load_dwordx4 v[124:127], v195, s[2:3] offset:192
	v_mfma_f32_16x16x32_bf16 v[0:3], v[160:163], v[128:131], v[0:3]
	v_mfma_f32_16x16x32_bf16 v[4:7], v[164:167], v[128:131], v[4:7]
	v_mfma_f32_16x16x32_bf16 v[8:11], v[168:171], v[128:131], v[8:11]
	v_mfma_f32_16x16x32_bf16 v[12:15], v[172:175], v[128:131], v[12:15]
	v_mfma_f32_16x16x32_bf16 v[16:19], v[160:163], v[132:135], v[16:19]
	v_mfma_f32_16x16x32_bf16 v[20:23], v[164:167], v[132:135], v[20:23]
	v_mfma_f32_16x16x32_bf16 v[24:27], v[168:171], v[132:135], v[24:27]
	v_mfma_f32_16x16x32_bf16 v[28:31], v[172:175], v[132:135], v[28:31]
	v_mfma_f32_16x16x32_bf16 v[32:35], v[160:163], v[136:139], v[32:35]
	v_mfma_f32_16x16x32_bf16 v[36:39], v[164:167], v[136:139], v[36:39]
	v_mfma_f32_16x16x32_bf16 v[40:43], v[168:171], v[136:139], v[40:43]
	v_mfma_f32_16x16x32_bf16 v[44:47], v[172:175], v[136:139], v[44:47]
	v_mfma_f32_16x16x32_bf16 v[48:51], v[160:163], v[140:143], v[48:51]
	v_mfma_f32_16x16x32_bf16 v[52:55], v[164:167], v[140:143], v[52:55]
	v_mfma_f32_16x16x32_bf16 v[56:59], v[168:171], v[140:143], v[56:59]
	v_mfma_f32_16x16x32_bf16 v[60:63], v[172:175], v[140:143], v[60:63]
	v_mfma_f32_16x16x32_bf16 v[0:3], v[176:179], v[144:147], v[0:3]
	v_mfma_f32_16x16x32_bf16 v[4:7], v[180:183], v[144:147], v[4:7]
	v_mfma_f32_16x16x32_bf16 v[8:11], v[184:187], v[144:147], v[8:11]
	v_mfma_f32_16x16x32_bf16 v[12:15], v[188:191], v[144:147], v[12:15]
	v_mfma_f32_16x16x32_bf16 v[16:19], v[176:179], v[148:151], v[16:19]
	v_mfma_f32_16x16x32_bf16 v[20:23], v[180:183], v[148:151], v[20:23]
	v_mfma_f32_16x16x32_bf16 v[24:27], v[184:187], v[148:151], v[24:27]
	v_mfma_f32_16x16x32_bf16 v[28:31], v[188:191], v[148:151], v[28:31]
	v_mfma_f32_16x16x32_bf16 v[32:35], v[176:179], v[152:155], v[32:35]
	v_mfma_f32_16x16x32_bf16 v[36:39], v[180:183], v[152:155], v[36:39]
	v_mfma_f32_16x16x32_bf16 v[40:43], v[184:187], v[152:155], v[40:43]
	v_mfma_f32_16x16x32_bf16 v[44:47], v[188:191], v[152:155], v[44:47]
	v_mfma_f32_16x16x32_bf16 v[48:51], v[176:179], v[156:159], v[48:51]
	v_mfma_f32_16x16x32_bf16 v[52:55], v[180:183], v[156:159], v[52:55]
	v_mfma_f32_16x16x32_bf16 v[56:59], v[184:187], v[156:159], v[56:59]
	v_mfma_f32_16x16x32_bf16 v[60:63], v[188:191], v[156:159], v[60:63]
	s_nop 7
	s_nop 7
	s_waitcnt vmcnt(15)
	v_pk_fma_f32 v[66:67], v[2:3], 0.5, v[66:67] op_sel_hi:[1,0,1]
	v_pk_fma_f32 v[64:65], v[0:1], 0.5, v[64:65] op_sel_hi:[1,0,1]
	global_store_dwordx4 v192, v[64:67], s[2:3]
	s_waitcnt vmcnt(15)
	v_pk_fma_f32 v[70:71], v[6:7], 0.5, v[70:71] op_sel_hi:[1,0,1]
	v_pk_fma_f32 v[68:69], v[4:5], 0.5, v[68:69] op_sel_hi:[1,0,1]
	global_store_dwordx4 v192, v[68:71], s[2:3] offset:64
	s_waitcnt vmcnt(15)
	v_pk_fma_f32 v[74:75], v[10:11], 0.5, v[74:75] op_sel_hi:[1,0,1]
	v_pk_fma_f32 v[72:73], v[8:9], 0.5, v[72:73] op_sel_hi:[1,0,1]
	global_store_dwordx4 v192, v[72:75], s[2:3] offset:128
	s_waitcnt vmcnt(15)
	v_pk_fma_f32 v[78:79], v[14:15], 0.5, v[78:79] op_sel_hi:[1,0,1]
	v_pk_fma_f32 v[76:77], v[12:13], 0.5, v[76:77] op_sel_hi:[1,0,1]
	global_store_dwordx4 v192, v[76:79], s[2:3] offset:192
	s_waitcnt vmcnt(15)
	v_pk_fma_f32 v[82:83], v[18:19], 0.5, v[82:83] op_sel_hi:[1,0,1]
	v_pk_fma_f32 v[80:81], v[16:17], 0.5, v[80:81] op_sel_hi:[1,0,1]
	global_store_dwordx4 v193, v[80:83], s[2:3]
	s_waitcnt vmcnt(15)
	v_pk_fma_f32 v[86:87], v[22:23], 0.5, v[86:87] op_sel_hi:[1,0,1]
	v_pk_fma_f32 v[84:85], v[20:21], 0.5, v[84:85] op_sel_hi:[1,0,1]
	global_store_dwordx4 v193, v[84:87], s[2:3] offset:64
	s_waitcnt vmcnt(15)
	v_pk_fma_f32 v[90:91], v[26:27], 0.5, v[90:91] op_sel_hi:[1,0,1]
	v_pk_fma_f32 v[88:89], v[24:25], 0.5, v[88:89] op_sel_hi:[1,0,1]
	global_store_dwordx4 v193, v[88:91], s[2:3] offset:128
	s_waitcnt vmcnt(15)
	v_pk_fma_f32 v[94:95], v[30:31], 0.5, v[94:95] op_sel_hi:[1,0,1]
	v_pk_fma_f32 v[92:93], v[28:29], 0.5, v[92:93] op_sel_hi:[1,0,1]
	global_store_dwordx4 v193, v[92:95], s[2:3] offset:192
	s_waitcnt vmcnt(15)
	v_pk_fma_f32 v[98:99], v[34:35], 0.5, v[98:99] op_sel_hi:[1,0,1]
	v_pk_fma_f32 v[96:97], v[32:33], 0.5, v[96:97] op_sel_hi:[1,0,1]
	global_store_dwordx4 v194, v[96:99], s[2:3]
	s_waitcnt vmcnt(15)
	v_pk_fma_f32 v[102:103], v[38:39], 0.5, v[102:103] op_sel_hi:[1,0,1]
	v_pk_fma_f32 v[100:101], v[36:37], 0.5, v[100:101] op_sel_hi:[1,0,1]
	global_store_dwordx4 v194, v[100:103], s[2:3] offset:64
	s_waitcnt vmcnt(15)
	v_pk_fma_f32 v[106:107], v[42:43], 0.5, v[106:107] op_sel_hi:[1,0,1]
	v_pk_fma_f32 v[104:105], v[40:41], 0.5, v[104:105] op_sel_hi:[1,0,1]
	global_store_dwordx4 v194, v[104:107], s[2:3] offset:128
	s_waitcnt vmcnt(15)
	v_pk_fma_f32 v[110:111], v[46:47], 0.5, v[110:111] op_sel_hi:[1,0,1]
	v_pk_fma_f32 v[108:109], v[44:45], 0.5, v[108:109] op_sel_hi:[1,0,1]
	global_store_dwordx4 v194, v[108:111], s[2:3] offset:192
	s_waitcnt vmcnt(15)
	v_pk_fma_f32 v[114:115], v[50:51], 0.5, v[114:115] op_sel_hi:[1,0,1]
	v_pk_fma_f32 v[112:113], v[48:49], 0.5, v[112:113] op_sel_hi:[1,0,1]
	global_store_dwordx4 v195, v[112:115], s[2:3]
	s_waitcnt vmcnt(15)
	v_pk_fma_f32 v[118:119], v[54:55], 0.5, v[118:119] op_sel_hi:[1,0,1]
	v_pk_fma_f32 v[116:117], v[52:53], 0.5, v[116:117] op_sel_hi:[1,0,1]
	global_store_dwordx4 v195, v[116:119], s[2:3] offset:64
	s_waitcnt vmcnt(15)
	v_pk_fma_f32 v[122:123], v[58:59], 0.5, v[122:123] op_sel_hi:[1,0,1]
	v_pk_fma_f32 v[120:121], v[56:57], 0.5, v[120:121] op_sel_hi:[1,0,1]
	global_store_dwordx4 v195, v[120:123], s[2:3] offset:128
	s_waitcnt vmcnt(15)
	v_pk_fma_f32 v[126:127], v[62:63], 0.5, v[126:127] op_sel_hi:[1,0,1]
	v_pk_fma_f32 v[124:125], v[60:61], 0.5, v[124:125] op_sel_hi:[1,0,1]
	global_store_dwordx4 v195, v[124:127], s[2:3] offset:192
	s_branch .LBB0_102

.LBB0_876:
	v_mov_b32_e32 v6, v216
	s_add_u32 s20, s50, s14
	v_ashrrev_i32_e32 v0, 3, v6
	v_ashrrev_i32_e32 v1, 31, v0
	v_lshlrev_b64 v[2:3], 11, v[0:1]
	v_lshlrev_b32_e32 v1, 4, v6
	v_lshl_add_u64 v[4:5], s[10:11], 0, v[2:3]
	v_and_b32_e32 v200, 0x70, v1
	v_lshl_add_u64 v[84:85], v[4:5], 0, v[200:201]
	v_and_b32_e32 v1, 7, v6
	v_lshl_or_b32 v2, v1, 4, v2
	s_addc_u32 s21, s51, s15
	v_add_co_u32_e32 v86, vcc, s5, v84
	s_waitcnt vmcnt(26)
	v_lshl_add_u64 v[20:21], s[20:21], 0, v[2:3]
	v_and_b32_e32 v1, 15, v6
	v_lshrrev_b32_e32 v2, 1, v6
	v_addc_co_u32_e32 v87, vcc, 0, v85, vcc
	v_mad_u64_u32 v[82:83], s[20:21], v0, s72, v[200:201]
	v_and_or_b32 v3, v2, s73, v1
	v_and_b32_e32 v0, 48, v6
	v_add_co_u32_e32 v88, vcc, s17, v84
	v_mad_u64_u32 v[80:81], s[20:21], v3, s72, v[0:1]
	v_and_or_b32 v1, v2, 32, v1
	v_addc_co_u32_e32 v89, vcc, 0, v85, vcc
	v_mad_u32_u24 v81, v1, s72, v0
	global_load_dwordx4 v[0:3], v[84:85], off
	global_load_dwordx4 v[4:7], v[86:87], off
	v_add_co_u32_e32 v90, vcc, s30, v84
	s_mov_b32 s3, 0x5990000
	s_nop 0
	v_addc_co_u32_e32 v91, vcc, 0, v85, vcc
	global_load_dwordx4 v[8:11], v[88:89], off
	global_load_dwordx4 v[12:15], v[90:91], off
	v_add_co_u32_e32 v92, vcc, s3, v20
	s_mov_b32 s3, 0x59a0000
	s_nop 0
	v_addc_co_u32_e32 v93, vcc, 0, v21, vcc
	global_load_dwordx4 v[16:19], v[92:93], off
	v_add_co_u32_e32 v94, vcc, s3, v20
	s_mov_b32 s3, 0xe629000
	s_nop 0
	v_addc_co_u32_e32 v95, vcc, 0, v21, vcc
	global_load_dwordx4 v[20:23], v[94:95], off
	global_load_dwordx4 v[24:27], v[94:95], off offset:128
	global_load_dwordx4 v[28:31], v[92:93], off offset:128
	global_load_dwordx4 v[32:35], v[90:91], off offset:128
	global_load_dwordx4 v[36:39], v[88:89], off offset:128
	global_load_dwordx4 v[40:43], v[86:87], off offset:128
	global_load_dwordx4 v[44:47], v[84:85], off offset:128
	s_barrier
	s_waitcnt vmcnt(11)
	ds_write_b128 v82, v[0:3]
	s_waitcnt vmcnt(10)
	ds_write_b128 v82, v[4:7] offset:4608
	s_waitcnt vmcnt(9)
	ds_write_b128 v82, v[8:11] offset:9216
	s_waitcnt vmcnt(8)
	ds_write_b128 v82, v[12:15] offset:13824
	s_waitcnt vmcnt(7)
	ds_write_b128 v82, v[16:19] offset:18432
	s_waitcnt vmcnt(6)
	ds_write_b128 v82, v[20:23] offset:23040
	s_waitcnt lgkmcnt(0)
	s_barrier
	global_load_dwordx4 v[0:3], v[84:85], off offset:256
	global_load_dwordx4 v[4:7], v[86:87], off offset:256
	global_load_dwordx4 v[8:11], v[88:89], off offset:256
	global_load_dwordx4 v[12:15], v[90:91], off offset:256
	global_load_dwordx4 v[16:19], v[92:93], off offset:256
	global_load_dwordx4 v[20:23], v[94:95], off offset:256
	ds_read_b128 v[96:99], v80
	ds_read_b128 v[100:103], v80 offset:2304
	ds_read_b128 v[104:107], v80 offset:4608
	ds_read_b128 v[108:111], v80 offset:6912
	ds_read_b128 v[112:115], v81 offset:18432
	ds_read_b128 v[116:119], v81 offset:20736
	s_waitcnt lgkmcnt(1)
	v_mfma_f32_16x16x32_bf16 v[120:123], v[112:115], v[96:99], 0
	s_waitcnt lgkmcnt(0)
	v_mfma_f32_16x16x32_bf16 v[96:99], v[116:119], v[96:99], 0
	v_mfma_f32_16x16x32_bf16 v[124:127], v[112:115], v[100:103], 0
	v_mfma_f32_16x16x32_bf16 v[100:103], v[116:119], v[100:103], 0
	v_mfma_f32_16x16x32_bf16 v[128:131], v[112:115], v[104:107], 0
	v_mfma_f32_16x16x32_bf16 v[104:107], v[116:119], v[104:107], 0
	v_mfma_f32_16x16x32_bf16 v[112:115], v[112:115], v[108:111], 0
	v_mfma_f32_16x16x32_bf16 v[108:111], v[116:119], v[108:111], 0
	ds_read_b128 v[116:119], v80 offset:64
	ds_read_b128 v[132:135], v80 offset:2368
	ds_read_b128 v[136:139], v80 offset:4672
	ds_read_b128 v[140:143], v80 offset:6976
	ds_read_b128 v[144:147], v81 offset:18496
	ds_read_b128 v[148:151], v81 offset:20800
	s_waitcnt lgkmcnt(0)
	s_barrier
	s_waitcnt vmcnt(6)
	ds_write_b128 v82, v[44:47]
	ds_write_b128 v82, v[40:43] offset:4608
	ds_write_b128 v82, v[36:39] offset:9216
	ds_write_b128 v82, v[32:35] offset:13824
	ds_write_b128 v82, v[28:31] offset:18432
	ds_write_b128 v82, v[24:27] offset:23040
	s_waitcnt lgkmcnt(0)
	s_barrier
	global_load_dwordx4 v[36:39], v[84:85], off offset:384
	global_load_dwordx4 v[40:43], v[86:87], off offset:384
	global_load_dwordx4 v[44:47], v[88:89], off offset:384
	global_load_dwordx4 v[24:27], v[90:91], off offset:384
	global_load_dwordx4 v[28:31], v[92:93], off offset:384
	global_load_dwordx4 v[32:35], v[94:95], off offset:384
	v_mfma_f32_16x16x32_bf16 v[120:123], v[144:147], v[116:119], v[120:123]
	v_mfma_f32_16x16x32_bf16 v[96:99], v[148:151], v[116:119], v[96:99]
	v_mfma_f32_16x16x32_bf16 v[116:119], v[144:147], v[132:135], v[124:127]
	v_mfma_f32_16x16x32_bf16 v[100:103], v[148:151], v[132:135], v[100:103]
	v_mfma_f32_16x16x32_bf16 v[124:127], v[144:147], v[136:139], v[128:131]
	v_mfma_f32_16x16x32_bf16 v[104:107], v[148:151], v[136:139], v[104:107]
	v_mfma_f32_16x16x32_bf16 v[112:115], v[144:147], v[140:143], v[112:115]
	v_mfma_f32_16x16x32_bf16 v[108:111], v[148:151], v[140:143], v[108:111]
	ds_read_b128 v[128:131], v80
	ds_read_b128 v[132:135], v80 offset:2304
	ds_read_b128 v[136:139], v80 offset:4608
	ds_read_b128 v[140:143], v80 offset:6912
	ds_read_b128 v[144:147], v81 offset:18432
	ds_read_b128 v[148:151], v81 offset:20736
	s_waitcnt lgkmcnt(1)
	v_mfma_f32_16x16x32_bf16 v[120:123], v[144:147], v[128:131], v[120:123]
	s_waitcnt lgkmcnt(0)
	v_mfma_f32_16x16x32_bf16 v[96:99], v[148:151], v[128:131], v[96:99]
	v_mfma_f32_16x16x32_bf16 v[116:119], v[144:147], v[132:135], v[116:119]
	v_mfma_f32_16x16x32_bf16 v[100:103], v[148:151], v[132:135], v[100:103]
	v_mfma_f32_16x16x32_bf16 v[124:127], v[144:147], v[136:139], v[124:127]
	v_mfma_f32_16x16x32_bf16 v[104:107], v[148:151], v[136:139], v[104:107]
	v_mfma_f32_16x16x32_bf16 v[112:115], v[144:147], v[140:143], v[112:115]
	v_mfma_f32_16x16x32_bf16 v[108:111], v[148:151], v[140:143], v[108:111]
	ds_read_b128 v[128:131], v80 offset:64
	ds_read_b128 v[132:135], v80 offset:2368
	ds_read_b128 v[136:139], v80 offset:4672
	ds_read_b128 v[140:143], v80 offset:6976
	ds_read_b128 v[144:147], v81 offset:18496
	ds_read_b128 v[148:151], v81 offset:20800
	s_waitcnt lgkmcnt(0)
	s_barrier
	s_waitcnt vmcnt(11)
	ds_write_b128 v82, v[0:3]
	s_waitcnt vmcnt(10)
	ds_write_b128 v82, v[4:7] offset:4608
	s_waitcnt vmcnt(9)
	ds_write_b128 v82, v[8:11] offset:9216
	s_waitcnt vmcnt(8)
	ds_write_b128 v82, v[12:15] offset:13824
	s_waitcnt vmcnt(7)
	ds_write_b128 v82, v[16:19] offset:18432
	s_waitcnt vmcnt(6)
	ds_write_b128 v82, v[20:23] offset:23040
	s_waitcnt lgkmcnt(0)
	s_barrier
	global_load_dwordx4 v[0:3], v[84:85], off offset:512
	global_load_dwordx4 v[4:7], v[86:87], off offset:512
	global_load_dwordx4 v[8:11], v[88:89], off offset:512
	global_load_dwordx4 v[12:15], v[90:91], off offset:512
	global_load_dwordx4 v[16:19], v[92:93], off offset:512
	global_load_dwordx4 v[20:23], v[94:95], off offset:512
	v_mfma_f32_16x16x32_bf16 v[120:123], v[144:147], v[128:131], v[120:123]
	v_mfma_f32_16x16x32_bf16 v[96:99], v[148:151], v[128:131], v[96:99]
	v_mfma_f32_16x16x32_bf16 v[116:119], v[144:147], v[132:135], v[116:119]
	v_mfma_f32_16x16x32_bf16 v[100:103], v[148:151], v[132:135], v[100:103]
	v_mfma_f32_16x16x32_bf16 v[124:127], v[144:147], v[136:139], v[124:127]
	v_mfma_f32_16x16x32_bf16 v[104:107], v[148:151], v[136:139], v[104:107]
	v_mfma_f32_16x16x32_bf16 v[112:115], v[144:147], v[140:143], v[112:115]
	v_mfma_f32_16x16x32_bf16 v[108:111], v[148:151], v[140:143], v[108:111]
	ds_read_b128 v[128:131], v80
	ds_read_b128 v[132:135], v80 offset:2304
	ds_read_b128 v[136:139], v80 offset:4608
	ds_read_b128 v[140:143], v80 offset:6912
	ds_read_b128 v[144:147], v81 offset:18432
	ds_read_b128 v[148:151], v81 offset:20736
	s_waitcnt lgkmcnt(1)
	v_mfma_f32_16x16x32_bf16 v[120:123], v[144:147], v[128:131], v[120:123]
	s_waitcnt lgkmcnt(0)
	v_mfma_f32_16x16x32_bf16 v[96:99], v[148:151], v[128:131], v[96:99]
	v_mfma_f32_16x16x32_bf16 v[116:119], v[144:147], v[132:135], v[116:119]
	v_mfma_f32_16x16x32_bf16 v[100:103], v[148:151], v[132:135], v[100:103]
	v_mfma_f32_16x16x32_bf16 v[124:127], v[144:147], v[136:139], v[124:127]
	v_mfma_f32_16x16x32_bf16 v[104:107], v[148:151], v[136:139], v[104:107]
	v_mfma_f32_16x16x32_bf16 v[112:115], v[144:147], v[140:143], v[112:115]
	v_mfma_f32_16x16x32_bf16 v[108:111], v[148:151], v[140:143], v[108:111]
	ds_read_b128 v[128:131], v80 offset:64
	ds_read_b128 v[132:135], v80 offset:2368
	ds_read_b128 v[136:139], v80 offset:4672
	ds_read_b128 v[140:143], v80 offset:6976
	ds_read_b128 v[144:147], v81 offset:18496
	ds_read_b128 v[148:151], v81 offset:20800
	s_waitcnt lgkmcnt(0)
	s_barrier
	s_waitcnt vmcnt(11)
	ds_write_b128 v82, v[36:39]
	s_waitcnt vmcnt(10)
	ds_write_b128 v82, v[40:43] offset:4608
	s_waitcnt vmcnt(9)
	ds_write_b128 v82, v[44:47] offset:9216
	s_waitcnt vmcnt(8)
	ds_write_b128 v82, v[24:27] offset:13824
	s_waitcnt vmcnt(7)
	ds_write_b128 v82, v[28:31] offset:18432
	s_waitcnt vmcnt(6)
	ds_write_b128 v82, v[32:35] offset:23040
	s_waitcnt lgkmcnt(0)
	s_barrier
	global_load_dwordx4 v[36:39], v[84:85], off offset:640
	global_load_dwordx4 v[40:43], v[86:87], off offset:640
	global_load_dwordx4 v[44:47], v[88:89], off offset:640
	global_load_dwordx4 v[24:27], v[90:91], off offset:640
	global_load_dwordx4 v[28:31], v[92:93], off offset:640
	global_load_dwordx4 v[32:35], v[94:95], off offset:640
	v_mfma_f32_16x16x32_bf16 v[120:123], v[144:147], v[128:131], v[120:123]
	v_mfma_f32_16x16x32_bf16 v[96:99], v[148:151], v[128:131], v[96:99]
	v_mfma_f32_16x16x32_bf16 v[116:119], v[144:147], v[132:135], v[116:119]
	v_mfma_f32_16x16x32_bf16 v[100:103], v[148:151], v[132:135], v[100:103]
	v_mfma_f32_16x16x32_bf16 v[124:127], v[144:147], v[136:139], v[124:127]
	v_mfma_f32_16x16x32_bf16 v[104:107], v[148:151], v[136:139], v[104:107]
	v_mfma_f32_16x16x32_bf16 v[112:115], v[144:147], v[140:143], v[112:115]
	v_mfma_f32_16x16x32_bf16 v[108:111], v[148:151], v[140:143], v[108:111]
	ds_read_b128 v[128:131], v80
	ds_read_b128 v[132:135], v80 offset:2304
	ds_read_b128 v[136:139], v80 offset:4608
	ds_read_b128 v[140:143], v80 offset:6912
	ds_read_b128 v[144:147], v81 offset:18432
	ds_read_b128 v[148:151], v81 offset:20736
	s_waitcnt lgkmcnt(1)
	v_mfma_f32_16x16x32_bf16 v[120:123], v[144:147], v[128:131], v[120:123]
	s_waitcnt lgkmcnt(0)
	v_mfma_f32_16x16x32_bf16 v[96:99], v[148:151], v[128:131], v[96:99]
	v_mfma_f32_16x16x32_bf16 v[116:119], v[144:147], v[132:135], v[116:119]
	v_mfma_f32_16x16x32_bf16 v[100:103], v[148:151], v[132:135], v[100:103]
	v_mfma_f32_16x16x32_bf16 v[124:127], v[144:147], v[136:139], v[124:127]
	v_mfma_f32_16x16x32_bf16 v[104:107], v[148:151], v[136:139], v[104:107]
	v_mfma_f32_16x16x32_bf16 v[112:115], v[144:147], v[140:143], v[112:115]
	v_mfma_f32_16x16x32_bf16 v[108:111], v[148:151], v[140:143], v[108:111]
	ds_read_b128 v[128:131], v80 offset:64
	ds_read_b128 v[132:135], v80 offset:2368
	ds_read_b128 v[136:139], v80 offset:4672
	ds_read_b128 v[140:143], v80 offset:6976
	ds_read_b128 v[144:147], v81 offset:18496
	ds_read_b128 v[148:151], v81 offset:20800
	s_waitcnt lgkmcnt(0)
	s_barrier
	s_waitcnt vmcnt(11)
	ds_write_b128 v82, v[0:3]
	s_waitcnt vmcnt(10)
	ds_write_b128 v82, v[4:7] offset:4608
	s_waitcnt vmcnt(9)
	ds_write_b128 v82, v[8:11] offset:9216
	s_waitcnt vmcnt(8)
	ds_write_b128 v82, v[12:15] offset:13824
	s_waitcnt vmcnt(7)
	ds_write_b128 v82, v[16:19] offset:18432
	s_waitcnt vmcnt(6)
	ds_write_b128 v82, v[20:23] offset:23040
	s_waitcnt lgkmcnt(0)
	s_barrier
	global_load_dwordx4 v[0:3], v[84:85], off offset:768
	global_load_dwordx4 v[4:7], v[86:87], off offset:768
	global_load_dwordx4 v[8:11], v[88:89], off offset:768
	global_load_dwordx4 v[12:15], v[90:91], off offset:768
	global_load_dwordx4 v[16:19], v[92:93], off offset:768
	global_load_dwordx4 v[20:23], v[94:95], off offset:768
	v_mfma_f32_16x16x32_bf16 v[120:123], v[144:147], v[128:131], v[120:123]
	v_mfma_f32_16x16x32_bf16 v[96:99], v[148:151], v[128:131], v[96:99]
	v_mfma_f32_16x16x32_bf16 v[116:119], v[144:147], v[132:135], v[116:119]
	v_mfma_f32_16x16x32_bf16 v[100:103], v[148:151], v[132:135], v[100:103]
	v_mfma_f32_16x16x32_bf16 v[124:127], v[144:147], v[136:139], v[124:127]
	v_mfma_f32_16x16x32_bf16 v[104:107], v[148:151], v[136:139], v[104:107]
	v_mfma_f32_16x16x32_bf16 v[112:115], v[144:147], v[140:143], v[112:115]
	v_mfma_f32_16x16x32_bf16 v[108:111], v[148:151], v[140:143], v[108:111]
	ds_read_b128 v[128:131], v80
	ds_read_b128 v[132:135], v80 offset:2304
	ds_read_b128 v[136:139], v80 offset:4608
	ds_read_b128 v[140:143], v80 offset:6912
	ds_read_b128 v[144:147], v81 offset:18432
	ds_read_b128 v[148:151], v81 offset:20736
	s_waitcnt lgkmcnt(1)
	v_mfma_f32_16x16x32_bf16 v[120:123], v[144:147], v[128:131], v[120:123]
	s_waitcnt lgkmcnt(0)
	v_mfma_f32_16x16x32_bf16 v[96:99], v[148:151], v[128:131], v[96:99]
	v_mfma_f32_16x16x32_bf16 v[116:119], v[144:147], v[132:135], v[116:119]
	v_mfma_f32_16x16x32_bf16 v[100:103], v[148:151], v[132:135], v[100:103]
	v_mfma_f32_16x16x32_bf16 v[124:127], v[144:147], v[136:139], v[124:127]
	v_mfma_f32_16x16x32_bf16 v[104:107], v[148:151], v[136:139], v[104:107]
	v_mfma_f32_16x16x32_bf16 v[112:115], v[144:147], v[140:143], v[112:115]
	v_mfma_f32_16x16x32_bf16 v[108:111], v[148:151], v[140:143], v[108:111]
	ds_read_b128 v[128:131], v80 offset:64
	ds_read_b128 v[132:135], v80 offset:2368
	ds_read_b128 v[136:139], v80 offset:4672
	ds_read_b128 v[140:143], v80 offset:6976
	ds_read_b128 v[144:147], v81 offset:18496
	ds_read_b128 v[148:151], v81 offset:20800
	s_waitcnt lgkmcnt(0)
	s_barrier
	s_waitcnt vmcnt(11)
	ds_write_b128 v82, v[36:39]
	s_waitcnt vmcnt(10)
	ds_write_b128 v82, v[40:43] offset:4608
	s_waitcnt vmcnt(9)
	ds_write_b128 v82, v[44:47] offset:9216
	s_waitcnt vmcnt(8)
	ds_write_b128 v82, v[24:27] offset:13824
	s_waitcnt vmcnt(7)
	ds_write_b128 v82, v[28:31] offset:18432
	s_waitcnt vmcnt(6)
	ds_write_b128 v82, v[32:35] offset:23040
	s_waitcnt lgkmcnt(0)
	s_barrier
	global_load_dwordx4 v[36:39], v[84:85], off offset:896
	global_load_dwordx4 v[40:43], v[86:87], off offset:896
	global_load_dwordx4 v[44:47], v[88:89], off offset:896
	global_load_dwordx4 v[24:27], v[90:91], off offset:896
	global_load_dwordx4 v[28:31], v[92:93], off offset:896
	global_load_dwordx4 v[32:35], v[94:95], off offset:896
	v_mfma_f32_16x16x32_bf16 v[120:123], v[144:147], v[128:131], v[120:123]
	v_mfma_f32_16x16x32_bf16 v[96:99], v[148:151], v[128:131], v[96:99]
	v_mfma_f32_16x16x32_bf16 v[116:119], v[144:147], v[132:135], v[116:119]
	v_mfma_f32_16x16x32_bf16 v[100:103], v[148:151], v[132:135], v[100:103]
	v_mfma_f32_16x16x32_bf16 v[124:127], v[144:147], v[136:139], v[124:127]
	v_mfma_f32_16x16x32_bf16 v[104:107], v[148:151], v[136:139], v[104:107]
	v_mfma_f32_16x16x32_bf16 v[112:115], v[144:147], v[140:143], v[112:115]
	v_mfma_f32_16x16x32_bf16 v[108:111], v[148:151], v[140:143], v[108:111]
	ds_read_b128 v[128:131], v80
	ds_read_b128 v[132:135], v80 offset:2304
	ds_read_b128 v[136:139], v80 offset:4608
	ds_read_b128 v[140:143], v80 offset:6912
	ds_read_b128 v[144:147], v81 offset:18432
	ds_read_b128 v[148:151], v81 offset:20736
	s_waitcnt lgkmcnt(1)
	v_mfma_f32_16x16x32_bf16 v[120:123], v[144:147], v[128:131], v[120:123]
	s_waitcnt lgkmcnt(0)
	v_mfma_f32_16x16x32_bf16 v[96:99], v[148:151], v[128:131], v[96:99]
	v_mfma_f32_16x16x32_bf16 v[116:119], v[144:147], v[132:135], v[116:119]
	v_mfma_f32_16x16x32_bf16 v[100:103], v[148:151], v[132:135], v[100:103]
	v_mfma_f32_16x16x32_bf16 v[124:127], v[144:147], v[136:139], v[124:127]
	v_mfma_f32_16x16x32_bf16 v[104:107], v[148:151], v[136:139], v[104:107]
	v_mfma_f32_16x16x32_bf16 v[112:115], v[144:147], v[140:143], v[112:115]
	v_mfma_f32_16x16x32_bf16 v[108:111], v[148:151], v[140:143], v[108:111]
	ds_read_b128 v[128:131], v80 offset:64
	ds_read_b128 v[132:135], v80 offset:2368
	ds_read_b128 v[136:139], v80 offset:4672
	ds_read_b128 v[140:143], v80 offset:6976
	ds_read_b128 v[144:147], v81 offset:18496
	ds_read_b128 v[148:151], v81 offset:20800
	s_waitcnt lgkmcnt(0)
	s_barrier
	s_waitcnt vmcnt(11)
	ds_write_b128 v82, v[0:3]
	s_waitcnt vmcnt(10)
	ds_write_b128 v82, v[4:7] offset:4608
	s_waitcnt vmcnt(9)
	ds_write_b128 v82, v[8:11] offset:9216
	s_waitcnt vmcnt(8)
	ds_write_b128 v82, v[12:15] offset:13824
	s_waitcnt vmcnt(7)
	ds_write_b128 v82, v[16:19] offset:18432
	s_waitcnt vmcnt(6)
	ds_write_b128 v82, v[20:23] offset:23040
	s_waitcnt lgkmcnt(0)
	s_barrier
	global_load_dwordx4 v[0:3], v[84:85], off offset:1024
	global_load_dwordx4 v[4:7], v[86:87], off offset:1024
	global_load_dwordx4 v[8:11], v[88:89], off offset:1024
	global_load_dwordx4 v[12:15], v[90:91], off offset:1024
	global_load_dwordx4 v[16:19], v[92:93], off offset:1024
	global_load_dwordx4 v[20:23], v[94:95], off offset:1024
	v_mfma_f32_16x16x32_bf16 v[120:123], v[144:147], v[128:131], v[120:123]
	v_mfma_f32_16x16x32_bf16 v[96:99], v[148:151], v[128:131], v[96:99]
	v_mfma_f32_16x16x32_bf16 v[116:119], v[144:147], v[132:135], v[116:119]
	v_mfma_f32_16x16x32_bf16 v[100:103], v[148:151], v[132:135], v[100:103]
	v_mfma_f32_16x16x32_bf16 v[124:127], v[144:147], v[136:139], v[124:127]
	v_mfma_f32_16x16x32_bf16 v[104:107], v[148:151], v[136:139], v[104:107]
	v_mfma_f32_16x16x32_bf16 v[112:115], v[144:147], v[140:143], v[112:115]
	v_mfma_f32_16x16x32_bf16 v[108:111], v[148:151], v[140:143], v[108:111]
	ds_read_b128 v[128:131], v80
	ds_read_b128 v[132:135], v80 offset:2304
	ds_read_b128 v[136:139], v80 offset:4608
	ds_read_b128 v[140:143], v80 offset:6912
	ds_read_b128 v[144:147], v81 offset:18432
	ds_read_b128 v[148:151], v81 offset:20736
	s_waitcnt lgkmcnt(1)
	v_mfma_f32_16x16x32_bf16 v[120:123], v[144:147], v[128:131], v[120:123]
	s_waitcnt lgkmcnt(0)
	v_mfma_f32_16x16x32_bf16 v[96:99], v[148:151], v[128:131], v[96:99]
	v_mfma_f32_16x16x32_bf16 v[116:119], v[144:147], v[132:135], v[116:119]
	v_mfma_f32_16x16x32_bf16 v[100:103], v[148:151], v[132:135], v[100:103]
	v_mfma_f32_16x16x32_bf16 v[124:127], v[144:147], v[136:139], v[124:127]
	v_mfma_f32_16x16x32_bf16 v[104:107], v[148:151], v[136:139], v[104:107]
	v_mfma_f32_16x16x32_bf16 v[112:115], v[144:147], v[140:143], v[112:115]
	v_mfma_f32_16x16x32_bf16 v[108:111], v[148:151], v[140:143], v[108:111]
	ds_read_b128 v[128:131], v80 offset:64
	ds_read_b128 v[132:135], v80 offset:2368
	ds_read_b128 v[136:139], v80 offset:4672
	ds_read_b128 v[140:143], v80 offset:6976
	ds_read_b128 v[144:147], v81 offset:18496
	ds_read_b128 v[148:151], v81 offset:20800
	s_waitcnt lgkmcnt(0)
	s_barrier
	s_waitcnt vmcnt(11)
	ds_write_b128 v82, v[36:39]
	s_waitcnt vmcnt(10)
	ds_write_b128 v82, v[40:43] offset:4608
	s_waitcnt vmcnt(9)
	ds_write_b128 v82, v[44:47] offset:9216
	s_waitcnt vmcnt(8)
	ds_write_b128 v82, v[24:27] offset:13824
	s_waitcnt vmcnt(7)
	ds_write_b128 v82, v[28:31] offset:18432
	s_waitcnt vmcnt(6)
	ds_write_b128 v82, v[32:35] offset:23040
	s_waitcnt lgkmcnt(0)
	s_barrier
	global_load_dwordx4 v[36:39], v[84:85], off offset:1152
	global_load_dwordx4 v[40:43], v[86:87], off offset:1152
	global_load_dwordx4 v[44:47], v[88:89], off offset:1152
	global_load_dwordx4 v[24:27], v[90:91], off offset:1152
	global_load_dwordx4 v[28:31], v[92:93], off offset:1152
	global_load_dwordx4 v[32:35], v[94:95], off offset:1152
	v_mfma_f32_16x16x32_bf16 v[120:123], v[144:147], v[128:131], v[120:123]
	v_mfma_f32_16x16x32_bf16 v[96:99], v[148:151], v[128:131], v[96:99]
	v_mfma_f32_16x16x32_bf16 v[116:119], v[144:147], v[132:135], v[116:119]
	v_mfma_f32_16x16x32_bf16 v[100:103], v[148:151], v[132:135], v[100:103]
	v_mfma_f32_16x16x32_bf16 v[124:127], v[144:147], v[136:139], v[124:127]
	v_mfma_f32_16x16x32_bf16 v[104:107], v[148:151], v[136:139], v[104:107]
	v_mfma_f32_16x16x32_bf16 v[112:115], v[144:147], v[140:143], v[112:115]
	v_mfma_f32_16x16x32_bf16 v[108:111], v[148:151], v[140:143], v[108:111]
	ds_read_b128 v[128:131], v80
	ds_read_b128 v[132:135], v80 offset:2304
	ds_read_b128 v[136:139], v80 offset:4608
	ds_read_b128 v[140:143], v80 offset:6912
	ds_read_b128 v[144:147], v81 offset:18432
	ds_read_b128 v[148:151], v81 offset:20736
	s_waitcnt lgkmcnt(1)
	v_mfma_f32_16x16x32_bf16 v[120:123], v[144:147], v[128:131], v[120:123]
	s_waitcnt lgkmcnt(0)
	v_mfma_f32_16x16x32_bf16 v[96:99], v[148:151], v[128:131], v[96:99]
	v_mfma_f32_16x16x32_bf16 v[116:119], v[144:147], v[132:135], v[116:119]
	v_mfma_f32_16x16x32_bf16 v[100:103], v[148:151], v[132:135], v[100:103]
	v_mfma_f32_16x16x32_bf16 v[124:127], v[144:147], v[136:139], v[124:127]
	v_mfma_f32_16x16x32_bf16 v[104:107], v[148:151], v[136:139], v[104:107]
	v_mfma_f32_16x16x32_bf16 v[112:115], v[144:147], v[140:143], v[112:115]
	v_mfma_f32_16x16x32_bf16 v[108:111], v[148:151], v[140:143], v[108:111]
	ds_read_b128 v[128:131], v80 offset:64
	ds_read_b128 v[132:135], v80 offset:2368
	ds_read_b128 v[136:139], v80 offset:4672
	ds_read_b128 v[140:143], v80 offset:6976
	ds_read_b128 v[144:147], v81 offset:18496
	ds_read_b128 v[148:151], v81 offset:20800
	s_waitcnt lgkmcnt(0)
	s_barrier
	s_waitcnt vmcnt(11)
	ds_write_b128 v82, v[0:3]
	s_waitcnt vmcnt(10)
	ds_write_b128 v82, v[4:7] offset:4608
	s_waitcnt vmcnt(9)
	ds_write_b128 v82, v[8:11] offset:9216
	s_waitcnt vmcnt(8)
	ds_write_b128 v82, v[12:15] offset:13824
	s_waitcnt vmcnt(7)
	ds_write_b128 v82, v[16:19] offset:18432
	s_waitcnt vmcnt(6)
	ds_write_b128 v82, v[20:23] offset:23040
	s_waitcnt lgkmcnt(0)
	s_barrier
	global_load_dwordx4 v[0:3], v[84:85], off offset:1280
	global_load_dwordx4 v[4:7], v[86:87], off offset:1280
	global_load_dwordx4 v[8:11], v[88:89], off offset:1280
	global_load_dwordx4 v[12:15], v[90:91], off offset:1280
	global_load_dwordx4 v[16:19], v[92:93], off offset:1280
	global_load_dwordx4 v[20:23], v[94:95], off offset:1280
	v_mfma_f32_16x16x32_bf16 v[120:123], v[144:147], v[128:131], v[120:123]
	v_mfma_f32_16x16x32_bf16 v[96:99], v[148:151], v[128:131], v[96:99]
	v_mfma_f32_16x16x32_bf16 v[116:119], v[144:147], v[132:135], v[116:119]
	v_mfma_f32_16x16x32_bf16 v[100:103], v[148:151], v[132:135], v[100:103]
	v_mfma_f32_16x16x32_bf16 v[124:127], v[144:147], v[136:139], v[124:127]
	v_mfma_f32_16x16x32_bf16 v[104:107], v[148:151], v[136:139], v[104:107]
	v_mfma_f32_16x16x32_bf16 v[112:115], v[144:147], v[140:143], v[112:115]
	v_mfma_f32_16x16x32_bf16 v[108:111], v[148:151], v[140:143], v[108:111]
	ds_read_b128 v[128:131], v80
	ds_read_b128 v[132:135], v80 offset:2304
	ds_read_b128 v[136:139], v80 offset:4608
	ds_read_b128 v[140:143], v80 offset:6912
	ds_read_b128 v[144:147], v81 offset:18432
	ds_read_b128 v[148:151], v81 offset:20736
	s_waitcnt lgkmcnt(1)
	v_mfma_f32_16x16x32_bf16 v[120:123], v[144:147], v[128:131], v[120:123]
	s_waitcnt lgkmcnt(0)
	v_mfma_f32_16x16x32_bf16 v[96:99], v[148:151], v[128:131], v[96:99]
	v_mfma_f32_16x16x32_bf16 v[116:119], v[144:147], v[132:135], v[116:119]
	v_mfma_f32_16x16x32_bf16 v[100:103], v[148:151], v[132:135], v[100:103]
	v_mfma_f32_16x16x32_bf16 v[124:127], v[144:147], v[136:139], v[124:127]
	v_mfma_f32_16x16x32_bf16 v[104:107], v[148:151], v[136:139], v[104:107]
	v_mfma_f32_16x16x32_bf16 v[112:115], v[144:147], v[140:143], v[112:115]
	v_mfma_f32_16x16x32_bf16 v[108:111], v[148:151], v[140:143], v[108:111]
	ds_read_b128 v[128:131], v80 offset:64
	ds_read_b128 v[132:135], v80 offset:2368
	ds_read_b128 v[136:139], v80 offset:4672
	ds_read_b128 v[140:143], v80 offset:6976
	ds_read_b128 v[144:147], v81 offset:18496
	ds_read_b128 v[148:151], v81 offset:20800
	s_waitcnt lgkmcnt(0)
	s_barrier
	s_waitcnt vmcnt(11)
	ds_write_b128 v82, v[36:39]
	s_waitcnt vmcnt(10)
	ds_write_b128 v82, v[40:43] offset:4608
	s_waitcnt vmcnt(9)
	ds_write_b128 v82, v[44:47] offset:9216
	s_waitcnt vmcnt(8)
	ds_write_b128 v82, v[24:27] offset:13824
	s_waitcnt vmcnt(7)
	ds_write_b128 v82, v[28:31] offset:18432
	s_waitcnt vmcnt(6)
	ds_write_b128 v82, v[32:35] offset:23040
	s_waitcnt lgkmcnt(0)
	s_barrier
	global_load_dwordx4 v[36:39], v[84:85], off offset:1408
	global_load_dwordx4 v[40:43], v[86:87], off offset:1408
	global_load_dwordx4 v[44:47], v[88:89], off offset:1408
	global_load_dwordx4 v[24:27], v[90:91], off offset:1408
	global_load_dwordx4 v[28:31], v[92:93], off offset:1408
	global_load_dwordx4 v[32:35], v[94:95], off offset:1408
	v_mfma_f32_16x16x32_bf16 v[120:123], v[144:147], v[128:131], v[120:123]
	v_mfma_f32_16x16x32_bf16 v[96:99], v[148:151], v[128:131], v[96:99]
	v_mfma_f32_16x16x32_bf16 v[116:119], v[144:147], v[132:135], v[116:119]
	v_mfma_f32_16x16x32_bf16 v[100:103], v[148:151], v[132:135], v[100:103]
	v_mfma_f32_16x16x32_bf16 v[124:127], v[144:147], v[136:139], v[124:127]
	v_mfma_f32_16x16x32_bf16 v[104:107], v[148:151], v[136:139], v[104:107]
	v_mfma_f32_16x16x32_bf16 v[112:115], v[144:147], v[140:143], v[112:115]
	v_mfma_f32_16x16x32_bf16 v[108:111], v[148:151], v[140:143], v[108:111]
	ds_read_b128 v[128:131], v80
	ds_read_b128 v[132:135], v80 offset:2304
	ds_read_b128 v[136:139], v80 offset:4608
	ds_read_b128 v[140:143], v80 offset:6912
	ds_read_b128 v[144:147], v81 offset:18432
	ds_read_b128 v[148:151], v81 offset:20736
	s_waitcnt lgkmcnt(1)
	v_mfma_f32_16x16x32_bf16 v[120:123], v[144:147], v[128:131], v[120:123]
	s_waitcnt lgkmcnt(0)
	v_mfma_f32_16x16x32_bf16 v[96:99], v[148:151], v[128:131], v[96:99]
	v_mfma_f32_16x16x32_bf16 v[116:119], v[144:147], v[132:135], v[116:119]
	v_mfma_f32_16x16x32_bf16 v[100:103], v[148:151], v[132:135], v[100:103]
	v_mfma_f32_16x16x32_bf16 v[124:127], v[144:147], v[136:139], v[124:127]
	v_mfma_f32_16x16x32_bf16 v[104:107], v[148:151], v[136:139], v[104:107]
	v_mfma_f32_16x16x32_bf16 v[112:115], v[144:147], v[140:143], v[112:115]
	v_mfma_f32_16x16x32_bf16 v[108:111], v[148:151], v[140:143], v[108:111]
	ds_read_b128 v[128:131], v80 offset:64
	ds_read_b128 v[132:135], v80 offset:2368
	ds_read_b128 v[136:139], v80 offset:4672
	ds_read_b128 v[140:143], v80 offset:6976
	ds_read_b128 v[144:147], v81 offset:18496
	ds_read_b128 v[148:151], v81 offset:20800
	s_waitcnt lgkmcnt(0)
	s_barrier
	s_waitcnt vmcnt(11)
	ds_write_b128 v82, v[0:3]
	s_waitcnt vmcnt(10)
	ds_write_b128 v82, v[4:7] offset:4608
	s_waitcnt vmcnt(9)
	ds_write_b128 v82, v[8:11] offset:9216
	s_waitcnt vmcnt(8)
	ds_write_b128 v82, v[12:15] offset:13824
	s_waitcnt vmcnt(7)
	ds_write_b128 v82, v[16:19] offset:18432
	s_waitcnt vmcnt(6)
	ds_write_b128 v82, v[20:23] offset:23040
	s_waitcnt lgkmcnt(0)
	s_barrier
	global_load_dwordx4 v[0:3], v[84:85], off offset:1536
	global_load_dwordx4 v[4:7], v[86:87], off offset:1536
	global_load_dwordx4 v[8:11], v[88:89], off offset:1536
	global_load_dwordx4 v[12:15], v[90:91], off offset:1536
	global_load_dwordx4 v[16:19], v[92:93], off offset:1536
	global_load_dwordx4 v[20:23], v[94:95], off offset:1536
	v_mfma_f32_16x16x32_bf16 v[120:123], v[144:147], v[128:131], v[120:123]
	v_mfma_f32_16x16x32_bf16 v[96:99], v[148:151], v[128:131], v[96:99]
	v_mfma_f32_16x16x32_bf16 v[116:119], v[144:147], v[132:135], v[116:119]
	v_mfma_f32_16x16x32_bf16 v[100:103], v[148:151], v[132:135], v[100:103]
	v_mfma_f32_16x16x32_bf16 v[124:127], v[144:147], v[136:139], v[124:127]
	v_mfma_f32_16x16x32_bf16 v[104:107], v[148:151], v[136:139], v[104:107]
	v_mfma_f32_16x16x32_bf16 v[112:115], v[144:147], v[140:143], v[112:115]
	v_mfma_f32_16x16x32_bf16 v[108:111], v[148:151], v[140:143], v[108:111]
	ds_read_b128 v[128:131], v80
	ds_read_b128 v[132:135], v80 offset:2304
	ds_read_b128 v[136:139], v80 offset:4608
	ds_read_b128 v[140:143], v80 offset:6912
	ds_read_b128 v[144:147], v81 offset:18432
	ds_read_b128 v[148:151], v81 offset:20736
	s_waitcnt lgkmcnt(1)
	v_mfma_f32_16x16x32_bf16 v[120:123], v[144:147], v[128:131], v[120:123]
	s_waitcnt lgkmcnt(0)
	v_mfma_f32_16x16x32_bf16 v[96:99], v[148:151], v[128:131], v[96:99]
	v_mfma_f32_16x16x32_bf16 v[116:119], v[144:147], v[132:135], v[116:119]
	v_mfma_f32_16x16x32_bf16 v[100:103], v[148:151], v[132:135], v[100:103]
	v_mfma_f32_16x16x32_bf16 v[124:127], v[144:147], v[136:139], v[124:127]
	v_mfma_f32_16x16x32_bf16 v[104:107], v[148:151], v[136:139], v[104:107]
	v_mfma_f32_16x16x32_bf16 v[112:115], v[144:147], v[140:143], v[112:115]
	v_mfma_f32_16x16x32_bf16 v[108:111], v[148:151], v[140:143], v[108:111]
	ds_read_b128 v[128:131], v80 offset:64
	ds_read_b128 v[132:135], v80 offset:2368
	ds_read_b128 v[136:139], v80 offset:4672
	ds_read_b128 v[140:143], v80 offset:6976
	ds_read_b128 v[144:147], v81 offset:18496
	ds_read_b128 v[148:151], v81 offset:20800
	s_waitcnt lgkmcnt(0)
	s_barrier
	s_waitcnt vmcnt(11)
	ds_write_b128 v82, v[36:39]
	s_waitcnt vmcnt(10)
	ds_write_b128 v82, v[40:43] offset:4608
	s_waitcnt vmcnt(9)
	ds_write_b128 v82, v[44:47] offset:9216
	s_waitcnt vmcnt(8)
	ds_write_b128 v82, v[24:27] offset:13824
	s_waitcnt vmcnt(7)
	ds_write_b128 v82, v[28:31] offset:18432
	s_waitcnt vmcnt(6)
	ds_write_b128 v82, v[32:35] offset:23040
	s_waitcnt lgkmcnt(0)
	s_barrier
	global_load_dwordx4 v[36:39], v[84:85], off offset:1664
	global_load_dwordx4 v[40:43], v[86:87], off offset:1664
	global_load_dwordx4 v[44:47], v[88:89], off offset:1664
	global_load_dwordx4 v[24:27], v[90:91], off offset:1664
	global_load_dwordx4 v[28:31], v[92:93], off offset:1664
	global_load_dwordx4 v[32:35], v[94:95], off offset:1664
	v_mfma_f32_16x16x32_bf16 v[120:123], v[144:147], v[128:131], v[120:123]
	v_mfma_f32_16x16x32_bf16 v[96:99], v[148:151], v[128:131], v[96:99]
	v_mfma_f32_16x16x32_bf16 v[116:119], v[144:147], v[132:135], v[116:119]
	v_mfma_f32_16x16x32_bf16 v[100:103], v[148:151], v[132:135], v[100:103]
	v_mfma_f32_16x16x32_bf16 v[124:127], v[144:147], v[136:139], v[124:127]
	v_mfma_f32_16x16x32_bf16 v[104:107], v[148:151], v[136:139], v[104:107]
	v_mfma_f32_16x16x32_bf16 v[112:115], v[144:147], v[140:143], v[112:115]
	v_mfma_f32_16x16x32_bf16 v[108:111], v[148:151], v[140:143], v[108:111]
	ds_read_b128 v[128:131], v80
	ds_read_b128 v[132:135], v80 offset:2304
	ds_read_b128 v[136:139], v80 offset:4608
	ds_read_b128 v[140:143], v80 offset:6912
	ds_read_b128 v[144:147], v81 offset:18432
	ds_read_b128 v[148:151], v81 offset:20736
	s_waitcnt lgkmcnt(1)
	v_mfma_f32_16x16x32_bf16 v[120:123], v[144:147], v[128:131], v[120:123]
	s_waitcnt lgkmcnt(0)
	v_mfma_f32_16x16x32_bf16 v[96:99], v[148:151], v[128:131], v[96:99]
	v_mfma_f32_16x16x32_bf16 v[116:119], v[144:147], v[132:135], v[116:119]
	v_mfma_f32_16x16x32_bf16 v[100:103], v[148:151], v[132:135], v[100:103]
	v_mfma_f32_16x16x32_bf16 v[124:127], v[144:147], v[136:139], v[124:127]
	v_mfma_f32_16x16x32_bf16 v[104:107], v[148:151], v[136:139], v[104:107]
	v_mfma_f32_16x16x32_bf16 v[112:115], v[144:147], v[140:143], v[112:115]
	v_mfma_f32_16x16x32_bf16 v[108:111], v[148:151], v[140:143], v[108:111]
	ds_read_b128 v[128:131], v80 offset:64
	ds_read_b128 v[132:135], v80 offset:2368
	ds_read_b128 v[136:139], v80 offset:4672
	ds_read_b128 v[140:143], v80 offset:6976
	ds_read_b128 v[144:147], v81 offset:18496
	ds_read_b128 v[148:151], v81 offset:20800
	s_waitcnt lgkmcnt(0)
	s_barrier
	s_waitcnt vmcnt(11)
	ds_write_b128 v82, v[0:3]
	s_waitcnt vmcnt(10)
	ds_write_b128 v82, v[4:7] offset:4608
	s_waitcnt vmcnt(9)
	ds_write_b128 v82, v[8:11] offset:9216
	s_waitcnt vmcnt(8)
	ds_write_b128 v82, v[12:15] offset:13824
	s_waitcnt vmcnt(7)
	ds_write_b128 v82, v[16:19] offset:18432
	s_waitcnt vmcnt(6)
	ds_write_b128 v82, v[20:23] offset:23040
	s_waitcnt lgkmcnt(0)
	s_barrier
	global_load_dwordx4 v[0:3], v[84:85], off offset:1792
	global_load_dwordx4 v[4:7], v[86:87], off offset:1792
	global_load_dwordx4 v[8:11], v[88:89], off offset:1792
	global_load_dwordx4 v[12:15], v[90:91], off offset:1792
	global_load_dwordx4 v[16:19], v[92:93], off offset:1792
	global_load_dwordx4 v[20:23], v[94:95], off offset:1792
	v_mfma_f32_16x16x32_bf16 v[120:123], v[144:147], v[128:131], v[120:123]
	v_mfma_f32_16x16x32_bf16 v[96:99], v[148:151], v[128:131], v[96:99]
	v_mfma_f32_16x16x32_bf16 v[116:119], v[144:147], v[132:135], v[116:119]
	v_mfma_f32_16x16x32_bf16 v[100:103], v[148:151], v[132:135], v[100:103]
	v_mfma_f32_16x16x32_bf16 v[124:127], v[144:147], v[136:139], v[124:127]
	v_mfma_f32_16x16x32_bf16 v[104:107], v[148:151], v[136:139], v[104:107]
	v_mfma_f32_16x16x32_bf16 v[112:115], v[144:147], v[140:143], v[112:115]
	v_mfma_f32_16x16x32_bf16 v[108:111], v[148:151], v[140:143], v[108:111]
	ds_read_b128 v[128:131], v80
	ds_read_b128 v[132:135], v80 offset:2304
	ds_read_b128 v[136:139], v80 offset:4608
	ds_read_b128 v[140:143], v80 offset:6912
	ds_read_b128 v[144:147], v81 offset:18432
	ds_read_b128 v[148:151], v81 offset:20736
	s_waitcnt lgkmcnt(1)
	v_mfma_f32_16x16x32_bf16 v[120:123], v[144:147], v[128:131], v[120:123]
	s_waitcnt lgkmcnt(0)
	v_mfma_f32_16x16x32_bf16 v[96:99], v[148:151], v[128:131], v[96:99]
	v_mfma_f32_16x16x32_bf16 v[116:119], v[144:147], v[132:135], v[116:119]
	v_mfma_f32_16x16x32_bf16 v[100:103], v[148:151], v[132:135], v[100:103]
	v_mfma_f32_16x16x32_bf16 v[124:127], v[144:147], v[136:139], v[124:127]
	v_mfma_f32_16x16x32_bf16 v[104:107], v[148:151], v[136:139], v[104:107]
	v_mfma_f32_16x16x32_bf16 v[112:115], v[144:147], v[140:143], v[112:115]
	v_mfma_f32_16x16x32_bf16 v[108:111], v[148:151], v[140:143], v[108:111]
	ds_read_b128 v[128:131], v80 offset:64
	ds_read_b128 v[132:135], v80 offset:2368
	ds_read_b128 v[136:139], v80 offset:4672
	ds_read_b128 v[140:143], v80 offset:6976
	ds_read_b128 v[144:147], v81 offset:18496
	ds_read_b128 v[148:151], v81 offset:20800
	s_waitcnt lgkmcnt(0)
	s_barrier
	s_waitcnt vmcnt(11)
	ds_write_b128 v82, v[36:39]
	s_waitcnt vmcnt(10)
	ds_write_b128 v82, v[40:43] offset:4608
	s_waitcnt vmcnt(9)
	ds_write_b128 v82, v[44:47] offset:9216
	s_waitcnt vmcnt(8)
	ds_write_b128 v82, v[24:27] offset:13824
	s_waitcnt vmcnt(7)
	ds_write_b128 v82, v[28:31] offset:18432
	s_waitcnt vmcnt(6)
	ds_write_b128 v82, v[32:35] offset:23040
	s_waitcnt lgkmcnt(0)
	s_barrier
	global_load_dwordx4 v[24:27], v[84:85], off offset:1920
	global_load_dwordx4 v[28:31], v[86:87], off offset:1920
	global_load_dwordx4 v[32:35], v[88:89], off offset:1920
	global_load_dwordx4 v[36:39], v[90:91], off offset:1920
	global_load_dwordx4 v[40:43], v[92:93], off offset:1920
	global_load_dwordx4 v[44:47], v[94:95], off offset:1920
	v_mfma_f32_16x16x32_bf16 v[120:123], v[144:147], v[128:131], v[120:123]
	v_mfma_f32_16x16x32_bf16 v[96:99], v[148:151], v[128:131], v[96:99]
	v_mfma_f32_16x16x32_bf16 v[116:119], v[144:147], v[132:135], v[116:119]
	v_mfma_f32_16x16x32_bf16 v[100:103], v[148:151], v[132:135], v[100:103]
	v_mfma_f32_16x16x32_bf16 v[124:127], v[144:147], v[136:139], v[124:127]
	v_mfma_f32_16x16x32_bf16 v[104:107], v[148:151], v[136:139], v[104:107]
	ds_read_b128 v[84:87], v80
	ds_read_b128 v[88:91], v80 offset:2304
	ds_read_b128 v[92:95], v80 offset:4608
	ds_read_b128 v[128:131], v80 offset:6912
	ds_read_b128 v[132:135], v81 offset:18432
	ds_read_b128 v[136:139], v81 offset:20736
	v_mfma_f32_16x16x32_bf16 v[112:115], v[144:147], v[140:143], v[112:115]
	v_mfma_f32_16x16x32_bf16 v[108:111], v[148:151], v[140:143], v[108:111]
	s_waitcnt lgkmcnt(1)
	v_mfma_f32_16x16x32_bf16 v[120:123], v[132:135], v[84:87], v[120:123]
	s_waitcnt lgkmcnt(0)
	v_mfma_f32_16x16x32_bf16 v[84:87], v[136:139], v[84:87], v[96:99]
	v_mfma_f32_16x16x32_bf16 v[96:99], v[132:135], v[88:91], v[116:119]
	v_mfma_f32_16x16x32_bf16 v[88:91], v[136:139], v[88:91], v[100:103]
	v_mfma_f32_16x16x32_bf16 v[100:103], v[132:135], v[92:95], v[124:127]
	v_mfma_f32_16x16x32_bf16 v[92:95], v[136:139], v[92:95], v[104:107]
	v_mfma_f32_16x16x32_bf16 v[104:107], v[132:135], v[128:131], v[112:115]
	v_mfma_f32_16x16x32_bf16 v[108:111], v[136:139], v[128:131], v[108:111]
	s_nop 1
	ds_read_b128 v[112:115], v80 offset:64
	ds_read_b128 v[116:119], v80 offset:2368
	ds_read_b128 v[124:127], v80 offset:4672
	ds_read_b128 v[128:131], v80 offset:6976
	ds_read_b128 v[132:135], v81 offset:18496
	ds_read_b128 v[136:139], v81 offset:20800
	s_waitcnt lgkmcnt(0)
	s_barrier
	s_waitcnt vmcnt(11)
	ds_write_b128 v82, v[0:3]
	s_waitcnt vmcnt(10)
	ds_write_b128 v82, v[4:7] offset:4608
	s_waitcnt vmcnt(9)
	ds_write_b128 v82, v[8:11] offset:9216
	s_waitcnt vmcnt(8)
	ds_write_b128 v82, v[12:15] offset:13824
	s_waitcnt vmcnt(7)
	ds_write_b128 v82, v[16:19] offset:18432
	s_waitcnt vmcnt(6)
	ds_write_b128 v82, v[20:23] offset:23040
	s_waitcnt lgkmcnt(0)
	s_barrier
	ds_read_b128 v[0:3], v80
	ds_read_b128 v[4:7], v80 offset:2304
	ds_read_b128 v[8:11], v80 offset:4608
	ds_read_b128 v[12:15], v80 offset:6912
	ds_read_b128 v[16:19], v81 offset:18432
	ds_read_b128 v[20:23], v81 offset:20736
	v_mfma_f32_16x16x32_bf16 v[120:123], v[132:135], v[112:115], v[120:123]
	v_mfma_f32_16x16x32_bf16 v[84:87], v[136:139], v[112:115], v[84:87]
	v_mfma_f32_16x16x32_bf16 v[96:99], v[132:135], v[116:119], v[96:99]
	v_mfma_f32_16x16x32_bf16 v[88:91], v[136:139], v[116:119], v[88:91]
	v_mfma_f32_16x16x32_bf16 v[100:103], v[132:135], v[124:127], v[100:103]
	v_mfma_f32_16x16x32_bf16 v[92:95], v[136:139], v[124:127], v[92:95]
	v_mfma_f32_16x16x32_bf16 v[104:107], v[132:135], v[128:131], v[104:107]
	v_mfma_f32_16x16x32_bf16 v[108:111], v[136:139], v[128:131], v[108:111]
	s_waitcnt lgkmcnt(1)
	v_mfma_f32_16x16x32_bf16 v[112:115], v[16:19], v[0:3], v[120:123]
	s_waitcnt lgkmcnt(0)
	v_mfma_f32_16x16x32_bf16 v[0:3], v[20:23], v[0:3], v[84:87]
	v_mfma_f32_16x16x32_bf16 v[84:87], v[16:19], v[4:7], v[96:99]
	v_mfma_f32_16x16x32_bf16 v[4:7], v[20:23], v[4:7], v[88:91]
	v_mfma_f32_16x16x32_bf16 v[88:91], v[16:19], v[8:11], v[100:103]
	v_mfma_f32_16x16x32_bf16 v[8:11], v[20:23], v[8:11], v[92:95]
	v_mfma_f32_16x16x32_bf16 v[16:19], v[16:19], v[12:15], v[104:107]
	v_mfma_f32_16x16x32_bf16 v[12:15], v[20:23], v[12:15], v[108:111]
	ds_read_b128 v[20:23], v80 offset:64
	ds_read_b128 v[92:95], v80 offset:2368
	ds_read_b128 v[96:99], v80 offset:4672
	ds_read_b128 v[100:103], v80 offset:6976
	ds_read_b128 v[104:107], v81 offset:18496
	ds_read_b128 v[108:111], v81 offset:20800
	s_waitcnt lgkmcnt(0)
	s_barrier
	s_waitcnt vmcnt(5)
	ds_write_b128 v82, v[24:27]
	s_waitcnt vmcnt(4)
	ds_write_b128 v82, v[28:31] offset:4608
	s_waitcnt vmcnt(3)
	ds_write_b128 v82, v[32:35] offset:9216
	s_waitcnt vmcnt(2)
	ds_write_b128 v82, v[36:39] offset:13824
	s_waitcnt vmcnt(1)
	ds_write_b128 v82, v[40:43] offset:18432
	s_waitcnt vmcnt(0)
	ds_write_b128 v82, v[44:47] offset:23040
	s_waitcnt lgkmcnt(0)
	s_barrier
	ds_read_b128 v[24:27], v80
	ds_read_b128 v[28:31], v80 offset:2304
	ds_read_b128 v[32:35], v80 offset:4608
	ds_read_b128 v[36:39], v80 offset:6912
	ds_read_b128 v[40:43], v81 offset:18432
	ds_read_b128 v[44:47], v81 offset:20736
	v_mfma_f32_16x16x32_bf16 v[112:115], v[104:107], v[20:23], v[112:115]
	v_mfma_f32_16x16x32_bf16 v[0:3], v[108:111], v[20:23], v[0:3]
	v_mfma_f32_16x16x32_bf16 v[20:23], v[104:107], v[92:95], v[84:87]
	v_mfma_f32_16x16x32_bf16 v[4:7], v[108:111], v[92:95], v[4:7]
	v_mfma_f32_16x16x32_bf16 v[84:87], v[104:107], v[96:99], v[88:91]
	v_mfma_f32_16x16x32_bf16 v[8:11], v[108:111], v[96:99], v[8:11]
	v_mfma_f32_16x16x32_bf16 v[16:19], v[104:107], v[100:103], v[16:19]
	v_mfma_f32_16x16x32_bf16 v[12:15], v[108:111], v[100:103], v[12:15]
	s_waitcnt lgkmcnt(1)
	v_mfma_f32_16x16x32_bf16 v[88:91], v[40:43], v[24:27], v[112:115]
	s_waitcnt lgkmcnt(0)
	v_mfma_f32_16x16x32_bf16 v[0:3], v[44:47], v[24:27], v[0:3]
	v_mfma_f32_16x16x32_bf16 v[20:23], v[40:43], v[28:31], v[20:23]
	v_mfma_f32_16x16x32_bf16 v[4:7], v[44:47], v[28:31], v[4:7]
	v_mfma_f32_16x16x32_bf16 v[24:27], v[40:43], v[32:35], v[84:87]
	v_mfma_f32_16x16x32_bf16 v[8:11], v[44:47], v[32:35], v[8:11]
	v_mfma_f32_16x16x32_bf16 v[16:19], v[40:43], v[36:39], v[16:19]
	v_mfma_f32_16x16x32_bf16 v[12:15], v[44:47], v[36:39], v[12:15]
	ds_read_b128 v[28:31], v80 offset:64
	ds_read_b128 v[32:35], v80 offset:2368
	ds_read_b128 v[36:39], v80 offset:4672
	ds_read_b128 v[40:43], v80 offset:6976
	ds_read_b128 v[44:47], v81 offset:18496
	ds_read_b128 v[80:83], v81 offset:20800
	s_waitcnt lgkmcnt(1)
	v_mfma_f32_16x16x32_bf16 v[84:87], v[44:47], v[28:31], v[88:91]
	s_waitcnt lgkmcnt(0)
	v_mfma_f32_16x16x32_bf16 v[28:31], v[80:83], v[28:31], v[0:3]
	v_mfma_f32_16x16x32_bf16 v[0:3], v[80:83], v[40:43], v[12:15]
	s_nop 4
	v_mul_f32_e32 v13, 0xbfb8aa3b, v85
	v_mul_f32_e32 v12, 0xbfb8aa3b, v84
	v_exp_f32_e32 v14, v13
	v_mul_f32_e32 v13, 0xbfb8aa3b, v86
	v_exp_f32_e32 v12, v12
	v_exp_f32_e32 v13, v13
	v_mfma_f32_16x16x32_bf16 v[20:23], v[44:47], v[32:35], v[20:23]
	v_mul_f32_e32 v15, 0xbfb8aa3b, v87
	v_exp_f32_e32 v15, v15
	v_mul_f32_e32 v1, 0xbfb8aa3b, v1
	v_mfma_f32_16x16x32_bf16 v[32:35], v[80:83], v[32:35], v[4:7]
	v_mul_f32_e32 v0, 0xbfb8aa3b, v0
	s_nop 2
	v_mul_f32_e32 v21, 0xbfb8aa3b, v21
	v_mul_f32_e32 v20, 0xbfb8aa3b, v20
	v_mfma_f32_16x16x32_bf16 v[4:7], v[44:47], v[40:43], v[16:19]
	v_exp_f32_e32 v20, v20
	v_exp_f32_e32 v0, v0
	s_nop 0
	v_pk_add_f32 v[16:17], v[12:13], 1.0 op_sel_hi:[1,0]
	v_mfma_f32_16x16x32_bf16 v[88:91], v[44:47], v[36:39], v[24:27]
	v_div_scale_f32 v12, s[20:21], v17, v17, 1.0
	v_rcp_f32_e32 v13, v12
	v_mfma_f32_16x16x32_bf16 v[8:11], v[80:83], v[36:39], v[8:11]
	v_mul_f32_e32 v5, 0xbfb8aa3b, v5
	v_mul_f32_e32 v4, 0xbfb8aa3b, v4
	v_fma_f32 v18, -v12, v13, 1.0
	v_fmac_f32_e32 v13, v18, v13
	v_div_scale_f32 v18, vcc, 1.0, v17, 1.0
	v_mul_f32_e32 v19, v18, v13
	v_fma_f32 v24, -v12, v19, v18
	v_fmac_f32_e32 v19, v24, v13
	v_fma_f32 v12, -v12, v19, v18
	v_div_fmas_f32 v12, v12, v13, v19
	v_div_scale_f32 v13, s[20:21], v16, v16, 1.0
	v_div_fixup_f32 v12, v12, v17, 1.0
	v_rcp_f32_e32 v17, v13
	v_mul_f32_e32 v9, 0xbfb8aa3b, v9
	v_mul_f32_e32 v8, 0xbfb8aa3b, v8
	v_exp_f32_e32 v8, v8
	v_fma_f32 v18, -v13, v17, 1.0
	v_fmac_f32_e32 v17, v18, v17
	v_div_scale_f32 v18, vcc, 1.0, v16, 1.0
	v_mul_f32_e32 v19, v18, v17
	v_fma_f32 v24, -v13, v19, v18
	v_fmac_f32_e32 v19, v24, v17
	v_fma_f32 v13, -v13, v19, v18
	v_div_fmas_f32 v13, v13, v17, v19
	v_div_fixup_f32 v13, v13, v16, 1.0
	v_pk_add_f32 v[16:17], v[14:15], 1.0 op_sel_hi:[1,0]
	v_exp_f32_e32 v4, v4
	v_div_scale_f32 v14, s[20:21], v17, v17, 1.0
	v_rcp_f32_e32 v15, v14
	v_mov_b32_e32 v37, v216
	v_fma_f32 v18, -v14, v15, 1.0
	v_fmac_f32_e32 v15, v18, v15
	v_div_scale_f32 v18, vcc, 1.0, v17, 1.0
	v_mul_f32_e32 v19, v18, v15
	v_fma_f32 v24, -v14, v19, v18
	v_fmac_f32_e32 v19, v24, v15
	v_fma_f32 v14, -v14, v19, v18
	v_div_fmas_f32 v14, v14, v15, v19
	v_div_scale_f32 v15, s[20:21], v16, v16, 1.0
	v_div_fixup_f32 v14, v14, v17, 1.0
	v_rcp_f32_e32 v17, v15
	s_nop 0
	v_fma_f32 v18, -v15, v17, 1.0
	v_fmac_f32_e32 v17, v18, v17
	v_div_scale_f32 v18, vcc, 1.0, v16, 1.0
	v_mul_f32_e32 v19, v18, v17
	v_fma_f32 v24, -v15, v19, v18
	v_fmac_f32_e32 v19, v24, v17
	v_fma_f32 v15, -v15, v19, v18
	v_div_fmas_f32 v15, v15, v17, v19
	v_mul_f32_e32 v17, 0xbfb8aa3b, v29
	v_div_fixup_f32 v15, v15, v16, 1.0
	v_mul_f32_e32 v16, 0xbfb8aa3b, v28
	v_exp_f32_e32 v18, v17
	v_mul_f32_e32 v17, 0xbfb8aa3b, v30
	v_exp_f32_e32 v16, v16
	v_exp_f32_e32 v17, v17
	v_mul_f32_e32 v19, 0xbfb8aa3b, v31
	v_exp_f32_e32 v19, v19
	v_pk_add_f32 v[24:25], v[16:17], 1.0 op_sel_hi:[1,0]
	s_nop 0
	v_div_scale_f32 v16, s[20:21], v25, v25, 1.0
	v_rcp_f32_e32 v17, v16
	s_nop 0
	v_fma_f32 v26, -v16, v17, 1.0
	v_fmac_f32_e32 v17, v26, v17
	v_div_scale_f32 v26, vcc, 1.0, v25, 1.0
	v_mul_f32_e32 v27, v26, v17
	v_fma_f32 v28, -v16, v27, v26
	v_fmac_f32_e32 v27, v28, v17
	v_fma_f32 v16, -v16, v27, v26
	v_div_fmas_f32 v16, v16, v17, v27
	v_div_scale_f32 v17, s[20:21], v24, v24, 1.0
	v_div_fixup_f32 v16, v16, v25, 1.0
	v_rcp_f32_e32 v25, v17
	s_nop 0
	v_fma_f32 v26, -v17, v25, 1.0
	v_fmac_f32_e32 v25, v26, v25
	v_div_scale_f32 v26, vcc, 1.0, v24, 1.0
	v_mul_f32_e32 v27, v26, v25
	v_fma_f32 v28, -v17, v27, v26
	v_fmac_f32_e32 v27, v28, v25
	v_fma_f32 v17, -v17, v27, v26
	v_div_fmas_f32 v17, v17, v25, v27
	v_div_fixup_f32 v17, v17, v24, 1.0
	v_pk_add_f32 v[24:25], v[18:19], 1.0 op_sel_hi:[1,0]
	s_nop 0
	v_div_scale_f32 v18, s[20:21], v25, v25, 1.0
	v_rcp_f32_e32 v19, v18
	s_nop 0
	v_fma_f32 v26, -v18, v19, 1.0
	v_fmac_f32_e32 v19, v26, v19
	v_div_scale_f32 v26, vcc, 1.0, v25, 1.0
	v_mul_f32_e32 v27, v26, v19
	v_fma_f32 v28, -v18, v27, v26
	v_fmac_f32_e32 v27, v28, v19
	v_fma_f32 v18, -v18, v27, v26
	v_div_fmas_f32 v18, v18, v19, v27
	v_div_scale_f32 v19, s[20:21], v24, v24, 1.0
	v_div_fixup_f32 v18, v18, v25, 1.0
	v_rcp_f32_e32 v25, v19
	s_nop 0
	v_fma_f32 v26, -v19, v25, 1.0
	v_fmac_f32_e32 v25, v26, v25
	v_div_scale_f32 v26, vcc, 1.0, v24, 1.0
	v_mul_f32_e32 v27, v26, v25
	v_fma_f32 v28, -v19, v27, v26
	v_fmac_f32_e32 v27, v28, v25
	v_fma_f32 v19, -v19, v27, v26
	v_div_fmas_f32 v19, v19, v25, v27
	v_div_fixup_f32 v19, v19, v24, 1.0
	v_exp_f32_e32 v24, v21
	v_mul_f32_e32 v21, 0xbfb8aa3b, v22
	v_exp_f32_e32 v21, v21
	v_mul_f32_e32 v22, 0xbfb8aa3b, v23
	v_exp_f32_e32 v25, v22
	v_pk_add_f32 v[22:23], v[20:21], 1.0 op_sel_hi:[1,0]
	s_nop 0
	v_div_scale_f32 v20, s[20:21], v23, v23, 1.0
	v_rcp_f32_e32 v21, v20
	v_pk_add_f32 v[24:25], v[24:25], 1.0 op_sel_hi:[1,0]
	v_fma_f32 v26, -v20, v21, 1.0
	v_fmac_f32_e32 v21, v26, v21
	v_div_scale_f32 v26, vcc, 1.0, v23, 1.0
	v_mul_f32_e32 v27, v26, v21
	v_fma_f32 v28, -v20, v27, v26
	v_fmac_f32_e32 v27, v28, v21
	v_fma_f32 v20, -v20, v27, v26
	v_div_fmas_f32 v20, v20, v21, v27
	v_div_scale_f32 v21, s[20:21], v22, v22, 1.0
	v_div_fixup_f32 v20, v20, v23, 1.0
	v_rcp_f32_e32 v23, v21
	s_nop 0
	v_fma_f32 v26, -v21, v23, 1.0
	v_fmac_f32_e32 v23, v26, v23
	v_div_scale_f32 v26, vcc, 1.0, v22, 1.0
	v_mul_f32_e32 v27, v26, v23
	v_fma_f32 v28, -v21, v27, v26
	v_fmac_f32_e32 v27, v28, v23
	v_fma_f32 v21, -v21, v27, v26
	v_div_fmas_f32 v21, v21, v23, v27
	v_div_fixup_f32 v21, v21, v22, 1.0
	v_div_scale_f32 v22, s[20:21], v25, v25, 1.0
	v_rcp_f32_e32 v23, v22
	s_nop 0
	v_fma_f32 v26, -v22, v23, 1.0
	v_fmac_f32_e32 v23, v26, v23
	v_div_scale_f32 v26, vcc, 1.0, v25, 1.0
	v_mul_f32_e32 v27, v26, v23
	v_fma_f32 v28, -v22, v27, v26
	v_fmac_f32_e32 v27, v28, v23
	v_fma_f32 v22, -v22, v27, v26
	v_div_fmas_f32 v22, v22, v23, v27
	v_div_scale_f32 v23, s[20:21], v24, v24, 1.0
	v_div_fixup_f32 v22, v22, v25, 1.0
	v_rcp_f32_e32 v25, v23
	s_nop 0
	v_fma_f32 v26, -v23, v25, 1.0
	v_fmac_f32_e32 v25, v26, v25
	v_div_scale_f32 v26, vcc, 1.0, v24, 1.0
	v_mul_f32_e32 v27, v26, v25
	v_fma_f32 v28, -v23, v27, v26
	v_fmac_f32_e32 v27, v28, v25
	v_fma_f32 v23, -v23, v27, v26
	v_div_fmas_f32 v23, v23, v25, v27
	v_mul_f32_e32 v25, 0xbfb8aa3b, v33
	v_div_fixup_f32 v23, v23, v24, 1.0
	v_mul_f32_e32 v24, 0xbfb8aa3b, v32
	v_exp_f32_e32 v26, v25
	v_mul_f32_e32 v25, 0xbfb8aa3b, v34
	v_exp_f32_e32 v24, v24
	v_exp_f32_e32 v25, v25
	v_mul_f32_e32 v27, 0xbfb8aa3b, v35
	v_exp_f32_e32 v27, v27
	v_pk_add_f32 v[28:29], v[24:25], 1.0 op_sel_hi:[1,0]
	s_nop 0
	v_div_scale_f32 v24, s[20:21], v29, v29, 1.0
	v_rcp_f32_e32 v25, v24
	s_nop 0
	v_fma_f32 v30, -v24, v25, 1.0
	v_fmac_f32_e32 v25, v30, v25
	v_div_scale_f32 v30, vcc, 1.0, v29, 1.0
	v_mul_f32_e32 v31, v30, v25
	v_fma_f32 v32, -v24, v31, v30
	v_fmac_f32_e32 v31, v32, v25
	v_fma_f32 v24, -v24, v31, v30
	v_div_fmas_f32 v24, v24, v25, v31
	v_div_scale_f32 v25, s[20:21], v28, v28, 1.0
	v_div_fixup_f32 v24, v24, v29, 1.0
	v_rcp_f32_e32 v29, v25
	s_nop 0
	v_fma_f32 v30, -v25, v29, 1.0
	v_fmac_f32_e32 v29, v30, v29
	v_div_scale_f32 v30, vcc, 1.0, v28, 1.0
	v_mul_f32_e32 v31, v30, v29
	v_fma_f32 v32, -v25, v31, v30
	v_fmac_f32_e32 v31, v32, v29
	v_fma_f32 v25, -v25, v31, v30
	v_div_fmas_f32 v25, v25, v29, v31
	v_div_fixup_f32 v25, v25, v28, 1.0
	v_pk_add_f32 v[28:29], v[26:27], 1.0 op_sel_hi:[1,0]
	s_nop 0
	v_div_scale_f32 v26, s[20:21], v29, v29, 1.0
	v_rcp_f32_e32 v27, v26
	s_nop 0
	v_fma_f32 v30, -v26, v27, 1.0
	v_fmac_f32_e32 v27, v30, v27
	v_div_scale_f32 v30, vcc, 1.0, v29, 1.0
	v_mul_f32_e32 v31, v30, v27
	v_fma_f32 v32, -v26, v31, v30
	v_fmac_f32_e32 v31, v32, v27
	v_fma_f32 v26, -v26, v31, v30
	v_div_fmas_f32 v26, v26, v27, v31
	v_div_scale_f32 v27, s[20:21], v28, v28, 1.0
	v_div_fixup_f32 v26, v26, v29, 1.0
	v_rcp_f32_e32 v29, v27
	s_nop 0
	v_fma_f32 v30, -v27, v29, 1.0
	v_fmac_f32_e32 v29, v30, v29
	v_div_scale_f32 v30, vcc, 1.0, v28, 1.0
	v_mul_f32_e32 v31, v30, v29
	v_fma_f32 v32, -v27, v31, v30
	v_fmac_f32_e32 v31, v32, v29
	v_fma_f32 v27, -v27, v31, v30
	v_div_fmas_f32 v27, v27, v29, v31
	v_mul_f32_e32 v29, 0xbfb8aa3b, v89
	v_div_fixup_f32 v27, v27, v28, 1.0
	v_mul_f32_e32 v28, 0xbfb8aa3b, v88
	v_exp_f32_e32 v30, v29
	v_mul_f32_e32 v29, 0xbfb8aa3b, v90
	v_exp_f32_e32 v28, v28
	v_exp_f32_e32 v29, v29
	v_mul_f32_e32 v31, 0xbfb8aa3b, v91
	v_exp_f32_e32 v31, v31
	v_pk_add_f32 v[32:33], v[28:29], 1.0 op_sel_hi:[1,0]
	s_nop 0
	v_div_scale_f32 v28, s[20:21], v33, v33, 1.0
	v_rcp_f32_e32 v29, v28
	s_nop 0
	v_fma_f32 v34, -v28, v29, 1.0
	v_fmac_f32_e32 v29, v34, v29
	v_div_scale_f32 v34, vcc, 1.0, v33, 1.0
	v_mul_f32_e32 v35, v34, v29
	v_fma_f32 v36, -v28, v35, v34
	v_fmac_f32_e32 v35, v36, v29
	v_fma_f32 v28, -v28, v35, v34
	v_div_fmas_f32 v28, v28, v29, v35
	v_div_scale_f32 v29, s[20:21], v32, v32, 1.0
	v_div_fixup_f32 v28, v28, v33, 1.0
	v_rcp_f32_e32 v33, v29
	s_nop 0
	v_fma_f32 v34, -v29, v33, 1.0
	v_fmac_f32_e32 v33, v34, v33
	v_div_scale_f32 v34, vcc, 1.0, v32, 1.0
	v_mul_f32_e32 v35, v34, v33
	v_fma_f32 v36, -v29, v35, v34
	v_fmac_f32_e32 v35, v36, v33
	v_fma_f32 v29, -v29, v35, v34
	v_div_fmas_f32 v29, v29, v33, v35
	v_div_fixup_f32 v29, v29, v32, 1.0
	v_pk_add_f32 v[32:33], v[30:31], 1.0 op_sel_hi:[1,0]
	s_nop 0
	v_div_scale_f32 v30, s[20:21], v33, v33, 1.0
	v_rcp_f32_e32 v31, v30
	s_nop 0
	v_fma_f32 v34, -v30, v31, 1.0
	v_fmac_f32_e32 v31, v34, v31
	v_div_scale_f32 v34, vcc, 1.0, v33, 1.0
	v_mul_f32_e32 v35, v34, v31
	v_fma_f32 v36, -v30, v35, v34
	v_fmac_f32_e32 v35, v36, v31
	v_fma_f32 v30, -v30, v35, v34
	v_div_fmas_f32 v30, v30, v31, v35
	v_div_scale_f32 v31, s[20:21], v32, v32, 1.0
	v_div_fixup_f32 v30, v30, v33, 1.0
	v_rcp_f32_e32 v33, v31
	s_nop 0
	v_fma_f32 v34, -v31, v33, 1.0
	v_fmac_f32_e32 v33, v34, v33
	v_div_scale_f32 v34, vcc, 1.0, v32, 1.0
	v_mul_f32_e32 v35, v34, v33
	v_fma_f32 v36, -v31, v35, v34
	v_fmac_f32_e32 v35, v36, v33
	v_fma_f32 v31, -v31, v35, v34
	v_div_fmas_f32 v31, v31, v33, v35
	v_div_fixup_f32 v31, v31, v32, 1.0
	v_exp_f32_e32 v32, v9
	v_mul_f32_e32 v9, 0xbfb8aa3b, v10
	v_exp_f32_e32 v9, v9
	v_mul_f32_e32 v10, 0xbfb8aa3b, v11
	v_exp_f32_e32 v33, v10
	v_pk_add_f32 v[10:11], v[8:9], 1.0 op_sel_hi:[1,0]
	s_nop 0
	v_div_scale_f32 v8, s[20:21], v11, v11, 1.0
	v_rcp_f32_e32 v9, v8
	v_pk_add_f32 v[32:33], v[32:33], 1.0 op_sel_hi:[1,0]
	v_fma_f32 v34, -v8, v9, 1.0
	v_fmac_f32_e32 v9, v34, v9
	v_div_scale_f32 v34, vcc, 1.0, v11, 1.0
	v_mul_f32_e32 v35, v34, v9
	v_fma_f32 v36, -v8, v35, v34
	v_fmac_f32_e32 v35, v36, v9
	v_fma_f32 v8, -v8, v35, v34
	v_div_fmas_f32 v8, v8, v9, v35
	v_div_scale_f32 v9, s[20:21], v10, v10, 1.0
	v_div_fixup_f32 v8, v8, v11, 1.0
	v_rcp_f32_e32 v11, v9
	s_nop 0
	v_fma_f32 v34, -v9, v11, 1.0
	v_fmac_f32_e32 v11, v34, v11
	v_div_scale_f32 v34, vcc, 1.0, v10, 1.0
	v_mul_f32_e32 v35, v34, v11
	v_fma_f32 v36, -v9, v35, v34
	v_fmac_f32_e32 v35, v36, v11
	v_fma_f32 v9, -v9, v35, v34
	v_div_fmas_f32 v9, v9, v11, v35
	v_div_fixup_f32 v9, v9, v10, 1.0
	v_div_scale_f32 v10, s[20:21], v33, v33, 1.0
	v_rcp_f32_e32 v11, v10
	s_nop 0
	v_fma_f32 v34, -v10, v11, 1.0
	v_fmac_f32_e32 v11, v34, v11
	v_div_scale_f32 v34, vcc, 1.0, v33, 1.0
	v_mul_f32_e32 v35, v34, v11
	v_fma_f32 v36, -v10, v35, v34
	v_fmac_f32_e32 v35, v36, v11
	v_fma_f32 v10, -v10, v35, v34
	v_div_fmas_f32 v10, v10, v11, v35
	v_div_scale_f32 v11, s[20:21], v32, v32, 1.0
	v_div_fixup_f32 v10, v10, v33, 1.0
	v_rcp_f32_e32 v33, v11
	s_nop 0
	v_fma_f32 v34, -v11, v33, 1.0
	v_fmac_f32_e32 v33, v34, v33
	v_div_scale_f32 v34, vcc, 1.0, v32, 1.0
	v_mul_f32_e32 v35, v34, v33
	v_fma_f32 v36, -v11, v35, v34
	v_fmac_f32_e32 v35, v36, v33
	v_fma_f32 v11, -v11, v35, v34
	v_div_fmas_f32 v11, v11, v33, v35
	v_div_fixup_f32 v11, v11, v32, 1.0
	v_exp_f32_e32 v32, v5
	v_mul_f32_e32 v5, 0xbfb8aa3b, v6
	v_exp_f32_e32 v5, v5
	v_mul_f32_e32 v6, 0xbfb8aa3b, v7
	v_exp_f32_e32 v33, v6
	v_pk_add_f32 v[6:7], v[4:5], 1.0 op_sel_hi:[1,0]
	s_nop 0
	v_div_scale_f32 v4, s[20:21], v7, v7, 1.0
	v_rcp_f32_e32 v5, v4
	v_pk_add_f32 v[32:33], v[32:33], 1.0 op_sel_hi:[1,0]
	v_fma_f32 v34, -v4, v5, 1.0
	v_fmac_f32_e32 v5, v34, v5
	v_div_scale_f32 v34, vcc, 1.0, v7, 1.0
	v_mul_f32_e32 v35, v34, v5
	v_fma_f32 v36, -v4, v35, v34
	v_fmac_f32_e32 v35, v36, v5
	v_fma_f32 v4, -v4, v35, v34
	v_div_fmas_f32 v4, v4, v5, v35
	v_div_scale_f32 v5, s[20:21], v6, v6, 1.0
	v_div_fixup_f32 v4, v4, v7, 1.0
	v_rcp_f32_e32 v7, v5
	s_nop 0
	v_fma_f32 v34, -v5, v7, 1.0
	v_fmac_f32_e32 v7, v34, v7
	v_div_scale_f32 v34, vcc, 1.0, v6, 1.0
	v_mul_f32_e32 v35, v34, v7
	v_fma_f32 v36, -v5, v35, v34
	v_fmac_f32_e32 v35, v36, v7
	v_fma_f32 v5, -v5, v35, v34
	v_div_fmas_f32 v5, v5, v7, v35
	v_div_fixup_f32 v5, v5, v6, 1.0
	v_div_scale_f32 v6, s[20:21], v33, v33, 1.0
	v_rcp_f32_e32 v7, v6
	s_nop 0
	v_fma_f32 v34, -v6, v7, 1.0
	v_fmac_f32_e32 v7, v34, v7
	v_div_scale_f32 v34, vcc, 1.0, v33, 1.0
	v_mul_f32_e32 v35, v34, v7
	v_fma_f32 v36, -v6, v35, v34
	v_fmac_f32_e32 v35, v36, v7
	v_fma_f32 v6, -v6, v35, v34
	v_div_fmas_f32 v6, v6, v7, v35
	v_div_scale_f32 v7, s[20:21], v32, v32, 1.0
	v_div_fixup_f32 v6, v6, v33, 1.0
	v_rcp_f32_e32 v33, v7
	s_nop 0
	v_fma_f32 v34, -v7, v33, 1.0
	v_fmac_f32_e32 v33, v34, v33
	v_div_scale_f32 v34, vcc, 1.0, v32, 1.0
	v_mul_f32_e32 v35, v34, v33
	v_fma_f32 v36, -v7, v35, v34
	v_fmac_f32_e32 v35, v36, v33
	v_fma_f32 v7, -v7, v35, v34
	v_div_fmas_f32 v7, v7, v33, v35
	v_div_fixup_f32 v7, v7, v32, 1.0
	v_exp_f32_e32 v32, v1
	v_mul_f32_e32 v1, 0xbfb8aa3b, v2
	v_exp_f32_e32 v1, v1
	v_mul_f32_e32 v2, 0xbfb8aa3b, v3
	v_exp_f32_e32 v33, v2
	v_pk_add_f32 v[0:1], v[0:1], 1.0 op_sel_hi:[1,0]
	s_nop 0
	v_div_scale_f32 v2, s[20:21], v1, v1, 1.0
	v_rcp_f32_e32 v3, v2
	s_nop 0
	v_fma_f32 v34, -v2, v3, 1.0
	v_fmac_f32_e32 v3, v34, v3
	v_div_scale_f32 v34, vcc, 1.0, v1, 1.0
	v_mul_f32_e32 v35, v34, v3
	v_fma_f32 v36, -v2, v35, v34
	v_fmac_f32_e32 v35, v36, v3
	v_fma_f32 v2, -v2, v35, v34
	v_div_fmas_f32 v2, v2, v3, v35
	v_div_fixup_f32 v2, v2, v1, 1.0
	v_div_scale_f32 v1, s[20:21], v0, v0, 1.0
	v_rcp_f32_e32 v3, v1
	s_nop 0
	v_fma_f32 v34, -v1, v3, 1.0
	v_fmac_f32_e32 v3, v34, v3
	v_div_scale_f32 v34, vcc, 1.0, v0, 1.0
	v_mul_f32_e32 v35, v34, v3
	v_fma_f32 v36, -v1, v35, v34
	v_fmac_f32_e32 v35, v36, v3
	v_fma_f32 v1, -v1, v35, v34
	v_div_fmas_f32 v1, v1, v3, v35
	v_div_fixup_f32 v3, v1, v0, 1.0
	v_pk_add_f32 v[0:1], v[32:33], 1.0 op_sel_hi:[1,0]
	s_nop 0
	v_div_scale_f32 v32, s[20:21], v1, v1, 1.0
	v_rcp_f32_e32 v33, v32
	s_nop 0
	v_fma_f32 v34, -v32, v33, 1.0
	v_fmac_f32_e32 v33, v34, v33
	v_div_scale_f32 v34, vcc, 1.0, v1, 1.0
	v_mul_f32_e32 v35, v34, v33
	v_fma_f32 v36, -v32, v35, v34
	v_fmac_f32_e32 v35, v36, v33
	v_fma_f32 v32, -v32, v35, v34
	v_div_fmas_f32 v32, v32, v33, v35
	v_div_fixup_f32 v32, v32, v1, 1.0
	v_div_scale_f32 v1, s[20:21], v0, v0, 1.0
	v_rcp_f32_e32 v33, v1
	s_add_u32 s20, s50, s8
	s_addc_u32 s21, s51, s9
	v_fma_f32 v34, -v1, v33, 1.0
	v_fmac_f32_e32 v33, v34, v33
	v_div_scale_f32 v34, vcc, 1.0, v0, 1.0
	v_mul_f32_e32 v35, v34, v33
	v_fma_f32 v36, -v1, v35, v34
	v_fmac_f32_e32 v35, v36, v33
	v_fma_f32 v1, -v1, v35, v34
	v_div_fmas_f32 v1, v1, v33, v35
	v_div_fixup_f32 v33, v1, v0, 1.0
	v_ashrrev_i32_e32 v0, 3, v37
	v_ashrrev_i32_e32 v1, 31, v0
	v_lshlrev_b32_e32 v36, 4, v37
	v_lshlrev_b64 v[34:35], 11, v[0:1]
	v_and_b32_e32 v36, 0x70, v36
	v_or_b32_e32 v34, v34, v36
	v_lshl_add_u64 v[46:47], s[20:21], 0, v[34:35]
	v_lshlrev_b64 v[34:35], 9, v[0:1]
	s_add_u32 s20, s50, s12
	v_add_co_u32_e32 v174, vcc, s3, v46
	v_or_b32_e32 v34, v34, v36
	s_addc_u32 s21, s51, s13
	v_addc_co_u32_e32 v175, vcc, 0, v47, vcc
	s_mov_b32 s3, 0xe639000
	v_lshl_add_u64 v[88:89], s[20:21], 0, v[34:35]
	v_mad_u64_u32 v[172:173], s[20:21], v0, s72, v[36:37]
	v_and_b32_e32 v35, 15, v37
	v_lshrrev_b32_e32 v36, 1, v37
	v_add_co_u32_e32 v176, vcc, s3, v46
	v_and_or_b32 v0, v36, s73, v35
	v_and_b32_e32 v34, 48, v37
	v_addc_co_u32_e32 v177, vcc, 0, v47, vcc
	s_mov_b32 s3, 0xe649000
	v_mad_u64_u32 v[0:1], s[20:21], v0, s72, v[34:35]
	v_add_co_u32_e32 v178, vcc, s3, v46
	v_and_or_b32 v1, v36, 32, v35
	s_nop 0
	v_addc_co_u32_e32 v179, vcc, 0, v47, vcc
	s_mov_b32 s3, 0xe659000
	v_mad_u32_u24 v1, v1, s72, v34
	global_load_dwordx4 v[34:37], v[174:175], off
	v_add_co_u32_e32 v46, vcc, s3, v46
	global_load_dwordx4 v[38:41], v[176:177], off
	global_load_dwordx4 v[42:45], v[178:179], off
	v_addc_co_u32_e32 v47, vcc, 0, v47, vcc
	s_mov_b32 s3, 0x6190000
	v_add_co_u32_e32 v180, vcc, s3, v88
	global_load_dwordx4 v[80:83], v[46:47], off
	s_nop 0
	v_addc_co_u32_e32 v181, vcc, 0, v89, vcc
	s_mov_b32 s3, 0x6194000
	global_load_dwordx4 v[84:87], v[180:181], off
	v_add_co_u32_e32 v182, vcc, s3, v88
	s_add_i32 s2, s2, -1
	s_nop 0
	v_addc_co_u32_e32 v183, vcc, 0, v89, vcc
	global_load_dwordx4 v[88:91], v[182:183], off
	global_load_dwordx4 v[92:95], v[182:183], off offset:128
	global_load_dwordx4 v[96:99], v[180:181], off offset:128
	global_load_dwordx4 v[100:103], v[46:47], off offset:128
	global_load_dwordx4 v[104:107], v[178:179], off offset:128
	global_load_dwordx4 v[108:111], v[176:177], off offset:128
	global_load_dwordx4 v[112:115], v[174:175], off offset:128
	s_barrier
	s_waitcnt vmcnt(11)
	ds_write_b128 v172, v[34:37]
	s_waitcnt vmcnt(10)
	ds_write_b128 v172, v[38:41] offset:4608
	s_waitcnt vmcnt(9)
	ds_write_b128 v172, v[42:45] offset:9216
	s_waitcnt vmcnt(8)
	ds_write_b128 v172, v[80:83] offset:13824
	s_waitcnt vmcnt(7)
	ds_write_b128 v172, v[84:87] offset:18432
	s_waitcnt vmcnt(6)
	ds_write_b128 v172, v[88:91] offset:23040
	s_waitcnt lgkmcnt(0)
	s_barrier
	global_load_dwordx4 v[34:37], v[174:175], off offset:256
	global_load_dwordx4 v[38:41], v[176:177], off offset:256
	global_load_dwordx4 v[42:45], v[178:179], off offset:256
	global_load_dwordx4 v[80:83], v[46:47], off offset:256
	global_load_dwordx4 v[84:87], v[180:181], off offset:256
	global_load_dwordx4 v[88:91], v[182:183], off offset:256
	ds_read_b128 v[116:119], v0
	ds_read_b128 v[120:123], v0 offset:2304
	ds_read_b128 v[124:127], v0 offset:4608
	ds_read_b128 v[128:131], v0 offset:6912
	ds_read_b128 v[132:135], v1 offset:18432
	ds_read_b128 v[136:139], v1 offset:20736
	s_waitcnt lgkmcnt(1)
	v_mfma_f32_16x16x32_bf16 v[140:143], v[132:135], v[116:119], 0
	s_add_u32 s8, s8, 0x200
	s_addc_u32 s9, s9, 0
	s_add_u32 s12, s12, 0x80000
	s_waitcnt lgkmcnt(0)
	v_mfma_f32_16x16x32_bf16 v[116:119], v[136:139], v[116:119], 0
	s_addc_u32 s13, s13, 0
	s_add_u32 s14, s14, 0x200000
	s_addc_u32 s15, s15, 0
	v_mfma_f32_16x16x32_bf16 v[144:147], v[132:135], v[120:123], 0
	s_cmp_lg_u32 s2, 0
	v_mfma_f32_16x16x32_bf16 v[120:123], v[136:139], v[120:123], 0
	v_mfma_f32_16x16x32_bf16 v[148:151], v[132:135], v[124:127], 0
	v_mfma_f32_16x16x32_bf16 v[124:127], v[136:139], v[124:127], 0
	v_mfma_f32_16x16x32_bf16 v[132:135], v[132:135], v[128:131], 0
	v_mfma_f32_16x16x32_bf16 v[128:131], v[136:139], v[128:131], 0
	ds_read_b128 v[136:139], v0 offset:64
	ds_read_b128 v[152:155], v0 offset:2368
	ds_read_b128 v[156:159], v0 offset:4672
	ds_read_b128 v[160:163], v0 offset:6976
	ds_read_b128 v[164:167], v1 offset:18496
	ds_read_b128 v[168:171], v1 offset:20800
	s_waitcnt lgkmcnt(0)
	s_barrier
	s_waitcnt vmcnt(6)
	ds_write_b128 v172, v[112:115]
	ds_write_b128 v172, v[108:111] offset:4608
	ds_write_b128 v172, v[104:107] offset:9216
	ds_write_b128 v172, v[100:103] offset:13824
	ds_write_b128 v172, v[96:99] offset:18432
	ds_write_b128 v172, v[92:95] offset:23040
	s_waitcnt lgkmcnt(0)
	s_barrier
	global_load_dwordx4 v[92:95], v[174:175], off offset:384
	global_load_dwordx4 v[96:99], v[176:177], off offset:384
	global_load_dwordx4 v[100:103], v[178:179], off offset:384
	global_load_dwordx4 v[104:107], v[46:47], off offset:384
	global_load_dwordx4 v[108:111], v[180:181], off offset:384
	global_load_dwordx4 v[112:115], v[182:183], off offset:384
	v_mfma_f32_16x16x32_bf16 v[140:143], v[164:167], v[136:139], v[140:143]
	v_mfma_f32_16x16x32_bf16 v[116:119], v[168:171], v[136:139], v[116:119]
	v_mfma_f32_16x16x32_bf16 v[136:139], v[164:167], v[152:155], v[144:147]
	v_mfma_f32_16x16x32_bf16 v[120:123], v[168:171], v[152:155], v[120:123]
	v_mfma_f32_16x16x32_bf16 v[144:147], v[164:167], v[156:159], v[148:151]
	v_mfma_f32_16x16x32_bf16 v[124:127], v[168:171], v[156:159], v[124:127]
	v_mfma_f32_16x16x32_bf16 v[132:135], v[164:167], v[160:163], v[132:135]
	v_mfma_f32_16x16x32_bf16 v[128:131], v[168:171], v[160:163], v[128:131]
	ds_read_b128 v[148:151], v0
	ds_read_b128 v[152:155], v0 offset:2304
	ds_read_b128 v[156:159], v0 offset:4608
	ds_read_b128 v[160:163], v0 offset:6912
	ds_read_b128 v[164:167], v1 offset:18432
	ds_read_b128 v[168:171], v1 offset:20736
	s_waitcnt lgkmcnt(1)
	v_mfma_f32_16x16x32_bf16 v[140:143], v[164:167], v[148:151], v[140:143]
	s_waitcnt lgkmcnt(0)
	v_mfma_f32_16x16x32_bf16 v[116:119], v[168:171], v[148:151], v[116:119]
	v_mfma_f32_16x16x32_bf16 v[136:139], v[164:167], v[152:155], v[136:139]
	v_mfma_f32_16x16x32_bf16 v[120:123], v[168:171], v[152:155], v[120:123]
	v_mfma_f32_16x16x32_bf16 v[144:147], v[164:167], v[156:159], v[144:147]
	v_mfma_f32_16x16x32_bf16 v[124:127], v[168:171], v[156:159], v[124:127]
	v_mfma_f32_16x16x32_bf16 v[132:135], v[164:167], v[160:163], v[132:135]
	v_mfma_f32_16x16x32_bf16 v[128:131], v[168:171], v[160:163], v[128:131]
	ds_read_b128 v[148:151], v0 offset:64
	ds_read_b128 v[152:155], v0 offset:2368
	ds_read_b128 v[156:159], v0 offset:4672
	ds_read_b128 v[160:163], v0 offset:6976
	ds_read_b128 v[164:167], v1 offset:18496
	ds_read_b128 v[168:171], v1 offset:20800
	s_waitcnt lgkmcnt(0)
	s_barrier
	s_waitcnt vmcnt(11)
	ds_write_b128 v172, v[34:37]
	s_waitcnt vmcnt(10)
	ds_write_b128 v172, v[38:41] offset:4608
	s_waitcnt vmcnt(9)
	ds_write_b128 v172, v[42:45] offset:9216
	s_waitcnt vmcnt(8)
	ds_write_b128 v172, v[80:83] offset:13824
	s_waitcnt vmcnt(7)
	ds_write_b128 v172, v[84:87] offset:18432
	s_waitcnt vmcnt(6)
	ds_write_b128 v172, v[88:91] offset:23040
	s_waitcnt lgkmcnt(0)
	s_barrier
	ds_read_b128 v[34:37], v0
	ds_read_b128 v[38:41], v0 offset:2304
	ds_read_b128 v[42:45], v0 offset:4608
	ds_read_b128 v[80:83], v0 offset:6912
	ds_read_b128 v[84:87], v1 offset:18432
	ds_read_b128 v[88:91], v1 offset:20736
	v_mfma_f32_16x16x32_bf16 v[140:143], v[164:167], v[148:151], v[140:143]
	v_mfma_f32_16x16x32_bf16 v[116:119], v[168:171], v[148:151], v[116:119]
	v_mfma_f32_16x16x32_bf16 v[136:139], v[164:167], v[152:155], v[136:139]
	v_mfma_f32_16x16x32_bf16 v[120:123], v[168:171], v[152:155], v[120:123]
	v_mfma_f32_16x16x32_bf16 v[144:147], v[164:167], v[156:159], v[144:147]
	v_mfma_f32_16x16x32_bf16 v[124:127], v[168:171], v[156:159], v[124:127]
	v_mfma_f32_16x16x32_bf16 v[132:135], v[164:167], v[160:163], v[132:135]
	v_mfma_f32_16x16x32_bf16 v[128:131], v[168:171], v[160:163], v[128:131]
	s_waitcnt lgkmcnt(1)
	v_mfma_f32_16x16x32_bf16 v[140:143], v[84:87], v[34:37], v[140:143]
	s_waitcnt lgkmcnt(0)
	v_mfma_f32_16x16x32_bf16 v[34:37], v[88:91], v[34:37], v[116:119]
	v_mfma_f32_16x16x32_bf16 v[116:119], v[84:87], v[38:41], v[136:139]
	v_mfma_f32_16x16x32_bf16 v[38:41], v[88:91], v[38:41], v[120:123]
	v_mfma_f32_16x16x32_bf16 v[120:123], v[84:87], v[42:45], v[144:147]
	v_mfma_f32_16x16x32_bf16 v[42:45], v[88:91], v[42:45], v[124:127]
	v_mfma_f32_16x16x32_bf16 v[84:87], v[84:87], v[80:83], v[132:135]
	v_mfma_f32_16x16x32_bf16 v[80:83], v[88:91], v[80:83], v[128:131]
	ds_read_b128 v[88:91], v0 offset:64
	ds_read_b128 v[124:127], v0 offset:2368
	s_nop 0
	ds_read_b128 v[128:131], v0 offset:4672
	ds_read_b128 v[132:135], v0 offset:6976
	ds_read_b128 v[136:139], v1 offset:18496
	ds_read_b128 v[144:147], v1 offset:20800
	s_waitcnt lgkmcnt(0)
	s_barrier
	s_waitcnt vmcnt(5)
	ds_write_b128 v172, v[92:95]
	s_waitcnt vmcnt(4)
	ds_write_b128 v172, v[96:99] offset:4608
	s_waitcnt vmcnt(3)
	ds_write_b128 v172, v[100:103] offset:9216
	s_waitcnt vmcnt(2)
	ds_write_b128 v172, v[104:107] offset:13824
	s_waitcnt vmcnt(1)
	ds_write_b128 v172, v[108:111] offset:18432
	s_waitcnt vmcnt(0)
	ds_write_b128 v172, v[112:115] offset:23040
	s_waitcnt lgkmcnt(0)
	s_barrier
	ds_read_b128 v[92:95], v0
	ds_read_b128 v[96:99], v0 offset:2304
	ds_read_b128 v[100:103], v0 offset:4608
	ds_read_b128 v[104:107], v0 offset:6912
	ds_read_b128 v[108:111], v1 offset:18432
	ds_read_b128 v[112:115], v1 offset:20736
	v_mfma_f32_16x16x32_bf16 v[140:143], v[136:139], v[88:91], v[140:143]
	v_mfma_f32_16x16x32_bf16 v[34:37], v[144:147], v[88:91], v[34:37]
	v_mfma_f32_16x16x32_bf16 v[88:91], v[136:139], v[124:127], v[116:119]
	v_mfma_f32_16x16x32_bf16 v[38:41], v[144:147], v[124:127], v[38:41]
	v_mfma_f32_16x16x32_bf16 v[116:119], v[136:139], v[128:131], v[120:123]
	v_mfma_f32_16x16x32_bf16 v[42:45], v[144:147], v[128:131], v[42:45]
	v_mfma_f32_16x16x32_bf16 v[84:87], v[136:139], v[132:135], v[84:87]
	v_mfma_f32_16x16x32_bf16 v[80:83], v[144:147], v[132:135], v[80:83]
	s_waitcnt lgkmcnt(1)
	v_mfma_f32_16x16x32_bf16 v[120:123], v[108:111], v[92:95], v[140:143]
	s_waitcnt lgkmcnt(0)
	v_mfma_f32_16x16x32_bf16 v[34:37], v[112:115], v[92:95], v[34:37]
	v_mfma_f32_16x16x32_bf16 v[88:91], v[108:111], v[96:99], v[88:91]
	v_mfma_f32_16x16x32_bf16 v[38:41], v[112:115], v[96:99], v[38:41]
	v_mfma_f32_16x16x32_bf16 v[92:95], v[108:111], v[100:103], v[116:119]
	v_mfma_f32_16x16x32_bf16 v[42:45], v[112:115], v[100:103], v[42:45]
	v_mfma_f32_16x16x32_bf16 v[84:87], v[108:111], v[104:107], v[84:87]
	v_mfma_f32_16x16x32_bf16 v[80:83], v[112:115], v[104:107], v[80:83]
	ds_read_b128 v[96:99], v0 offset:64
	ds_read_b128 v[100:103], v0 offset:2368
	ds_read_b128 v[104:107], v0 offset:4672
	ds_read_b128 v[108:111], v0 offset:6976
	ds_read_b128 v[112:115], v1 offset:18496
	ds_read_b128 v[116:119], v1 offset:20800
	v_and_b32_sdwa v0, v12, v232 dst_sel:DWORD dst_unused:UNUSED_PAD src0_sel:WORD_1 src1_sel:DWORD
	v_and_b32_sdwa v1, v13, v232 dst_sel:DWORD dst_unused:UNUSED_PAD src0_sel:WORD_1 src1_sel:DWORD
	s_waitcnt lgkmcnt(1)
	v_mfma_f32_16x16x32_bf16 v[120:123], v[112:115], v[96:99], v[120:123]
	v_add3_u32 v12, v12, v0, s69
	v_add3_u32 v46, v13, v1, s69
	v_and_b32_sdwa v0, v14, v232 dst_sel:DWORD dst_unused:UNUSED_PAD src0_sel:WORD_1 src1_sel:DWORD
	v_and_b32_sdwa v1, v15, v232 dst_sel:DWORD dst_unused:UNUSED_PAD src0_sel:WORD_1 src1_sel:DWORD
	v_add3_u32 v0, v14, v0, s69
	v_add3_u32 v13, v15, v1, s69
	s_waitcnt lgkmcnt(0)
	v_mfma_f32_16x16x32_bf16 v[34:37], v[116:119], v[96:99], v[34:37]
	v_and_b32_e32 v1, 0xffff0000, v0
	v_and_b32_e32 v0, 0xffff0000, v13
	v_mov_b32_e32 v15, v122
	v_mov_b32_e32 v122, v121
	v_and_b32_e32 v13, 0xffff0000, v12
	v_and_b32_e32 v12, 0xffff0000, v46
	v_mov_b32_e32 v14, v120
	v_pk_fma_f32 v[78:79], v[122:123], v[0:1], v[78:79]
	v_and_b32_sdwa v0, v16, v232 dst_sel:DWORD dst_unused:UNUSED_PAD src0_sel:WORD_1 src1_sel:DWORD
	v_and_b32_sdwa v1, v17, v232 dst_sel:DWORD dst_unused:UNUSED_PAD src0_sel:WORD_1 src1_sel:DWORD
	v_pk_fma_f32 v[76:77], v[14:15], v[12:13], v[76:77]
	v_add3_u32 v12, v16, v0, s69
	v_add3_u32 v14, v17, v1, s69
	v_and_b32_sdwa v0, v18, v232 dst_sel:DWORD dst_unused:UNUSED_PAD src0_sel:WORD_1 src1_sel:DWORD
	v_and_b32_sdwa v1, v19, v232 dst_sel:DWORD dst_unused:UNUSED_PAD src0_sel:WORD_1 src1_sel:DWORD
	v_add3_u32 v0, v18, v0, s69
	v_add3_u32 v13, v19, v1, s69
	v_mfma_f32_16x16x32_bf16 v[88:91], v[112:115], v[100:103], v[88:91]
	v_and_b32_e32 v1, 0xffff0000, v0
	v_and_b32_e32 v0, 0xffff0000, v13
	v_mov_b32_e32 v15, v36
	v_mov_b32_e32 v36, v35
	v_and_b32_e32 v13, 0xffff0000, v12
	v_and_b32_e32 v12, 0xffff0000, v14
	v_mov_b32_e32 v14, v34
	v_pk_fma_f32 v[72:73], v[36:37], v[0:1], v[72:73]
	v_and_b32_sdwa v0, v20, v232 dst_sel:DWORD dst_unused:UNUSED_PAD src0_sel:WORD_1 src1_sel:DWORD
	v_and_b32_sdwa v1, v21, v232 dst_sel:DWORD dst_unused:UNUSED_PAD src0_sel:WORD_1 src1_sel:DWORD
	v_pk_fma_f32 v[74:75], v[14:15], v[12:13], v[74:75]
	v_add3_u32 v12, v20, v0, s69
	v_add3_u32 v14, v21, v1, s69
	v_and_b32_sdwa v0, v22, v232 dst_sel:DWORD dst_unused:UNUSED_PAD src0_sel:WORD_1 src1_sel:DWORD
	v_and_b32_sdwa v1, v23, v232 dst_sel:DWORD dst_unused:UNUSED_PAD src0_sel:WORD_1 src1_sel:DWORD
	v_add3_u32 v0, v22, v0, s69
	v_add3_u32 v13, v23, v1, s69
	v_mfma_f32_16x16x32_bf16 v[38:41], v[116:119], v[100:103], v[38:41]
	v_and_b32_e32 v1, 0xffff0000, v0
	v_and_b32_e32 v0, 0xffff0000, v13
	v_mov_b32_e32 v15, v90
	v_mov_b32_e32 v90, v89
	v_and_b32_e32 v13, 0xffff0000, v12
	v_and_b32_e32 v12, 0xffff0000, v14
	v_mov_b32_e32 v14, v88
	v_pk_fma_f32 v[68:69], v[90:91], v[0:1], v[68:69]
	v_and_b32_sdwa v0, v24, v232 dst_sel:DWORD dst_unused:UNUSED_PAD src0_sel:WORD_1 src1_sel:DWORD
	v_and_b32_sdwa v1, v25, v232 dst_sel:DWORD dst_unused:UNUSED_PAD src0_sel:WORD_1 src1_sel:DWORD
	v_pk_fma_f32 v[70:71], v[14:15], v[12:13], v[70:71]
	v_add3_u32 v12, v24, v0, s69
	v_add3_u32 v14, v25, v1, s69
	v_and_b32_sdwa v0, v26, v232 dst_sel:DWORD dst_unused:UNUSED_PAD src0_sel:WORD_1 src1_sel:DWORD
	v_and_b32_sdwa v1, v27, v232 dst_sel:DWORD dst_unused:UNUSED_PAD src0_sel:WORD_1 src1_sel:DWORD
	v_add3_u32 v0, v26, v0, s69
	v_add3_u32 v13, v27, v1, s69
	v_mfma_f32_16x16x32_bf16 v[92:95], v[112:115], v[104:107], v[92:95]
	v_and_b32_e32 v1, 0xffff0000, v0
	v_and_b32_e32 v0, 0xffff0000, v13
	v_mov_b32_e32 v15, v40
	v_mov_b32_e32 v40, v39
	v_and_b32_e32 v13, 0xffff0000, v12
	v_and_b32_e32 v12, 0xffff0000, v14
	v_mov_b32_e32 v14, v38
	v_pk_fma_f32 v[64:65], v[40:41], v[0:1], v[64:65]
	v_and_b32_sdwa v0, v28, v232 dst_sel:DWORD dst_unused:UNUSED_PAD src0_sel:WORD_1 src1_sel:DWORD
	v_and_b32_sdwa v1, v29, v232 dst_sel:DWORD dst_unused:UNUSED_PAD src0_sel:WORD_1 src1_sel:DWORD
	v_pk_fma_f32 v[66:67], v[14:15], v[12:13], v[66:67]
	v_add3_u32 v12, v28, v0, s69
	v_add3_u32 v14, v29, v1, s69
	v_and_b32_sdwa v0, v30, v232 dst_sel:DWORD dst_unused:UNUSED_PAD src0_sel:WORD_1 src1_sel:DWORD
	v_and_b32_sdwa v1, v31, v232 dst_sel:DWORD dst_unused:UNUSED_PAD src0_sel:WORD_1 src1_sel:DWORD
	v_add3_u32 v0, v30, v0, s69
	v_add3_u32 v13, v31, v1, s69
	v_mfma_f32_16x16x32_bf16 v[42:45], v[116:119], v[104:107], v[42:45]
	v_and_b32_e32 v1, 0xffff0000, v0
	v_and_b32_e32 v0, 0xffff0000, v13
	v_mov_b32_e32 v15, v94
	v_mov_b32_e32 v94, v93
	v_and_b32_e32 v13, 0xffff0000, v12
	v_and_b32_e32 v12, 0xffff0000, v14
	v_mov_b32_e32 v14, v92
	v_pk_fma_f32 v[60:61], v[94:95], v[0:1], v[60:61]
	v_and_b32_sdwa v0, v8, v232 dst_sel:DWORD dst_unused:UNUSED_PAD src0_sel:WORD_1 src1_sel:DWORD
	v_and_b32_sdwa v1, v9, v232 dst_sel:DWORD dst_unused:UNUSED_PAD src0_sel:WORD_1 src1_sel:DWORD
	v_pk_fma_f32 v[62:63], v[14:15], v[12:13], v[62:63]
	v_add3_u32 v8, v8, v0, s69
	v_add3_u32 v12, v9, v1, s69
	v_and_b32_sdwa v0, v10, v232 dst_sel:DWORD dst_unused:UNUSED_PAD src0_sel:WORD_1 src1_sel:DWORD
	v_and_b32_sdwa v1, v11, v232 dst_sel:DWORD dst_unused:UNUSED_PAD src0_sel:WORD_1 src1_sel:DWORD
	v_add3_u32 v0, v10, v0, s69
	v_add3_u32 v9, v11, v1, s69
	v_mfma_f32_16x16x32_bf16 v[84:87], v[112:115], v[108:111], v[84:87]
	v_and_b32_e32 v1, 0xffff0000, v0
	v_and_b32_e32 v0, 0xffff0000, v9
	v_mov_b32_e32 v11, v44
	v_mov_b32_e32 v44, v43
	v_and_b32_e32 v9, 0xffff0000, v8
	v_and_b32_e32 v8, 0xffff0000, v12
	v_mov_b32_e32 v10, v42
	v_pk_fma_f32 v[56:57], v[44:45], v[0:1], v[56:57]
	v_and_b32_sdwa v0, v4, v232 dst_sel:DWORD dst_unused:UNUSED_PAD src0_sel:WORD_1 src1_sel:DWORD
	v_and_b32_sdwa v1, v5, v232 dst_sel:DWORD dst_unused:UNUSED_PAD src0_sel:WORD_1 src1_sel:DWORD
	v_pk_fma_f32 v[58:59], v[10:11], v[8:9], v[58:59]
	v_add3_u32 v4, v4, v0, s69
	v_add3_u32 v8, v5, v1, s69
	v_and_b32_sdwa v0, v6, v232 dst_sel:DWORD dst_unused:UNUSED_PAD src0_sel:WORD_1 src1_sel:DWORD
	v_and_b32_sdwa v1, v7, v232 dst_sel:DWORD dst_unused:UNUSED_PAD src0_sel:WORD_1 src1_sel:DWORD
	v_add3_u32 v0, v6, v0, s69
	v_add3_u32 v5, v7, v1, s69
	v_mfma_f32_16x16x32_bf16 v[80:83], v[116:119], v[108:111], v[80:83]
	v_and_b32_e32 v1, 0xffff0000, v0
	v_and_b32_e32 v0, 0xffff0000, v5
	v_mov_b32_e32 v7, v86
	v_mov_b32_e32 v86, v85
	v_and_b32_e32 v5, 0xffff0000, v4
	v_and_b32_e32 v4, 0xffff0000, v8
	v_mov_b32_e32 v6, v84
	v_pk_fma_f32 v[52:53], v[86:87], v[0:1], v[52:53]
	v_and_b32_sdwa v0, v2, v232 dst_sel:DWORD dst_unused:UNUSED_PAD src0_sel:WORD_1 src1_sel:DWORD
	v_and_b32_sdwa v1, v3, v232 dst_sel:DWORD dst_unused:UNUSED_PAD src0_sel:WORD_1 src1_sel:DWORD
	v_pk_fma_f32 v[54:55], v[6:7], v[4:5], v[54:55]
	v_add3_u32 v2, v2, v0, s69
	v_add3_u32 v4, v3, v1, s69
	v_and_b32_sdwa v0, v32, v232 dst_sel:DWORD dst_unused:UNUSED_PAD src0_sel:WORD_1 src1_sel:DWORD
	v_and_b32_sdwa v1, v33, v232 dst_sel:DWORD dst_unused:UNUSED_PAD src0_sel:WORD_1 src1_sel:DWORD
	v_add3_u32 v0, v32, v0, s69
	v_add3_u32 v3, v33, v1, s69
	v_and_b32_e32 v1, 0xffff0000, v0
	v_and_b32_e32 v0, 0xffff0000, v3
	v_and_b32_e32 v3, 0xffff0000, v2
	v_and_b32_e32 v2, 0xffff0000, v4
	v_mov_b32_e32 v4, v80
	v_mov_b32_e32 v5, v82
	v_mov_b32_e32 v82, v81
	v_pk_fma_f32 v[50:51], v[4:5], v[2:3], v[50:51]
	v_pk_fma_f32 v[48:49], v[82:83], v[0:1], v[48:49]
	s_cbranch_scc1 .LBB0_876
	v_mov_b32_e32 v1, v216
	v_readlane_b32 s2, v255, 4
	v_ashrrev_i32_e32 v0, 1, v1
	v_and_b32_e32 v0, 0xffffffc0, v0
	v_lshl_add_u32 v0, s2, 7, v0
	v_and_or_b32 v0, v1, 15, v0
	v_lshrrev_b32_e32 v2, 1, v1
	v_lshrrev_b32_e32 v1, 2, v1
	v_and_b32_e32 v2, 32, v2
	v_and_b32_e32 v1, 12, v1
	v_or3_b32 v2, v1, v2, s4
	v_ashrrev_i32_e32 v1, 31, v0
	v_and_b32_sdwa v7, v79, v232 dst_sel:DWORD dst_unused:UNUSED_PAD src0_sel:WORD_1 src1_sel:DWORD
	v_and_b32_sdwa v8, v78, v232 dst_sel:DWORD dst_unused:UNUSED_PAD src0_sel:WORD_1 src1_sel:DWORD
	v_lshlrev_b64 v[4:5], 11, v[0:1]
	v_ashrrev_i32_e32 v3, 31, v2
	v_and_b32_sdwa v1, v77, v232 dst_sel:DWORD dst_unused:UNUSED_PAD src0_sel:WORD_1 src1_sel:DWORD
	v_and_b32_sdwa v6, v76, v232 dst_sel:DWORD dst_unused:UNUSED_PAD src0_sel:WORD_1 src1_sel:DWORD
	v_add3_u32 v7, v79, v7, s69
	v_add3_u32 v8, v78, v8, s69
	v_lshl_add_u64 v[4:5], s[28:29], 0, v[4:5]
	v_lshlrev_b64 v[2:3], 1, v[2:3]
	v_add3_u32 v6, v76, v6, s69
	v_add3_u32 v1, v77, v1, s69
	v_and_b32_e32 v7, 0xffff0000, v7
	v_and_b32_e32 v8, 0xffff0000, v8
	v_lshl_add_u64 v[4:5], v[4:5], 0, v[2:3]
	v_or_b32_sdwa v7, v7, v1 dst_sel:DWORD dst_unused:UNUSED_PAD src0_sel:DWORD src1_sel:WORD_1
	v_or_b32_sdwa v6, v8, v6 dst_sel:DWORD dst_unused:UNUSED_PAD src0_sel:DWORD src1_sel:WORD_1
	global_store_dwordx2 v[4:5], v[6:7], off
	v_and_b32_sdwa v7, v73, v232 dst_sel:DWORD dst_unused:UNUSED_PAD src0_sel:WORD_1 src1_sel:DWORD
	v_and_b32_sdwa v8, v72, v232 dst_sel:DWORD dst_unused:UNUSED_PAD src0_sel:WORD_1 src1_sel:DWORD
	v_and_b32_sdwa v1, v75, v232 dst_sel:DWORD dst_unused:UNUSED_PAD src0_sel:WORD_1 src1_sel:DWORD
	v_and_b32_sdwa v6, v74, v232 dst_sel:DWORD dst_unused:UNUSED_PAD src0_sel:WORD_1 src1_sel:DWORD
	v_add3_u32 v7, v73, v7, s69
	v_add3_u32 v8, v72, v8, s69
	v_add3_u32 v6, v74, v6, s69
	v_add3_u32 v1, v75, v1, s69
	v_and_b32_e32 v7, 0xffff0000, v7
	v_and_b32_e32 v8, 0xffff0000, v8
	v_or_b32_sdwa v7, v7, v1 dst_sel:DWORD dst_unused:UNUSED_PAD src0_sel:DWORD src1_sel:WORD_1
	v_or_b32_sdwa v6, v8, v6 dst_sel:DWORD dst_unused:UNUSED_PAD src0_sel:DWORD src1_sel:WORD_1
	global_store_dwordx2 v[4:5], v[6:7], off offset:32
	v_or_b32_e32 v4, 16, v0
	v_ashrrev_i32_e32 v5, 31, v4
	v_and_b32_sdwa v7, v69, v232 dst_sel:DWORD dst_unused:UNUSED_PAD src0_sel:WORD_1 src1_sel:DWORD
	v_and_b32_sdwa v8, v68, v232 dst_sel:DWORD dst_unused:UNUSED_PAD src0_sel:WORD_1 src1_sel:DWORD
	v_lshlrev_b64 v[4:5], 11, v[4:5]
	v_and_b32_sdwa v1, v71, v232 dst_sel:DWORD dst_unused:UNUSED_PAD src0_sel:WORD_1 src1_sel:DWORD
	v_and_b32_sdwa v6, v70, v232 dst_sel:DWORD dst_unused:UNUSED_PAD src0_sel:WORD_1 src1_sel:DWORD
	v_add3_u32 v7, v69, v7, s69
	v_add3_u32 v8, v68, v8, s69
	v_lshl_add_u64 v[4:5], s[28:29], 0, v[4:5]
	v_add3_u32 v6, v70, v6, s69
	v_add3_u32 v1, v71, v1, s69
	v_and_b32_e32 v7, 0xffff0000, v7
	v_and_b32_e32 v8, 0xffff0000, v8
	v_lshl_add_u64 v[4:5], v[4:5], 0, v[2:3]
	v_or_b32_sdwa v7, v7, v1 dst_sel:DWORD dst_unused:UNUSED_PAD src0_sel:DWORD src1_sel:WORD_1
	v_or_b32_sdwa v6, v8, v6 dst_sel:DWORD dst_unused:UNUSED_PAD src0_sel:DWORD src1_sel:WORD_1
	global_store_dwordx2 v[4:5], v[6:7], off
	v_and_b32_sdwa v7, v65, v232 dst_sel:DWORD dst_unused:UNUSED_PAD src0_sel:WORD_1 src1_sel:DWORD
	v_and_b32_sdwa v8, v64, v232 dst_sel:DWORD dst_unused:UNUSED_PAD src0_sel:WORD_1 src1_sel:DWORD
	v_and_b32_sdwa v1, v67, v232 dst_sel:DWORD dst_unused:UNUSED_PAD src0_sel:WORD_1 src1_sel:DWORD
	v_and_b32_sdwa v6, v66, v232 dst_sel:DWORD dst_unused:UNUSED_PAD src0_sel:WORD_1 src1_sel:DWORD
	v_add3_u32 v7, v65, v7, s69
	v_add3_u32 v8, v64, v8, s69
	v_add3_u32 v6, v66, v6, s69
	v_add3_u32 v1, v67, v1, s69
	v_and_b32_e32 v7, 0xffff0000, v7
	v_and_b32_e32 v8, 0xffff0000, v8
	v_or_b32_sdwa v7, v7, v1 dst_sel:DWORD dst_unused:UNUSED_PAD src0_sel:DWORD src1_sel:WORD_1
	v_or_b32_sdwa v6, v8, v6 dst_sel:DWORD dst_unused:UNUSED_PAD src0_sel:DWORD src1_sel:WORD_1
	global_store_dwordx2 v[4:5], v[6:7], off offset:32
	v_or_b32_e32 v4, 32, v0
	v_ashrrev_i32_e32 v5, 31, v4
	v_and_b32_sdwa v7, v61, v232 dst_sel:DWORD dst_unused:UNUSED_PAD src0_sel:WORD_1 src1_sel:DWORD
	v_and_b32_sdwa v8, v60, v232 dst_sel:DWORD dst_unused:UNUSED_PAD src0_sel:WORD_1 src1_sel:DWORD
	v_lshlrev_b64 v[4:5], 11, v[4:5]
	v_and_b32_sdwa v1, v63, v232 dst_sel:DWORD dst_unused:UNUSED_PAD src0_sel:WORD_1 src1_sel:DWORD
	v_and_b32_sdwa v6, v62, v232 dst_sel:DWORD dst_unused:UNUSED_PAD src0_sel:WORD_1 src1_sel:DWORD
	v_add3_u32 v7, v61, v7, s69
	v_add3_u32 v8, v60, v8, s69
	v_lshl_add_u64 v[4:5], s[28:29], 0, v[4:5]
	v_add3_u32 v6, v62, v6, s69
	v_add3_u32 v1, v63, v1, s69
	v_and_b32_e32 v7, 0xffff0000, v7
	v_and_b32_e32 v8, 0xffff0000, v8
	v_lshl_add_u64 v[4:5], v[4:5], 0, v[2:3]
	v_or_b32_sdwa v7, v7, v1 dst_sel:DWORD dst_unused:UNUSED_PAD src0_sel:DWORD src1_sel:WORD_1
	v_or_b32_sdwa v6, v8, v6 dst_sel:DWORD dst_unused:UNUSED_PAD src0_sel:DWORD src1_sel:WORD_1
	global_store_dwordx2 v[4:5], v[6:7], off
	v_and_b32_sdwa v7, v57, v232 dst_sel:DWORD dst_unused:UNUSED_PAD src0_sel:WORD_1 src1_sel:DWORD
	v_and_b32_sdwa v1, v59, v232 dst_sel:DWORD dst_unused:UNUSED_PAD src0_sel:WORD_1 src1_sel:DWORD
	v_add3_u32 v7, v57, v7, s69
	v_add3_u32 v1, v59, v1, s69
	v_and_b32_e32 v7, 0xffff0000, v7
	v_or_b32_e32 v0, 48, v0
	v_and_b32_sdwa v8, v56, v232 dst_sel:DWORD dst_unused:UNUSED_PAD src0_sel:WORD_1 src1_sel:DWORD
	v_or_b32_sdwa v7, v7, v1 dst_sel:DWORD dst_unused:UNUSED_PAD src0_sel:DWORD src1_sel:WORD_1
	v_ashrrev_i32_e32 v1, 31, v0
	v_and_b32_sdwa v6, v58, v232 dst_sel:DWORD dst_unused:UNUSED_PAD src0_sel:WORD_1 src1_sel:DWORD
	v_add3_u32 v8, v56, v8, s69
	v_lshlrev_b64 v[0:1], 11, v[0:1]
	v_add3_u32 v6, v58, v6, s69
	v_and_b32_e32 v8, 0xffff0000, v8
	v_lshl_add_u64 v[0:1], s[28:29], 0, v[0:1]
	v_or_b32_sdwa v6, v8, v6 dst_sel:DWORD dst_unused:UNUSED_PAD src0_sel:DWORD src1_sel:WORD_1
	v_lshl_add_u64 v[0:1], v[0:1], 0, v[2:3]
	v_and_b32_sdwa v3, v54, v232 dst_sel:DWORD dst_unused:UNUSED_PAD src0_sel:WORD_1 src1_sel:DWORD
	global_store_dwordx2 v[4:5], v[6:7], off offset:32
	v_add3_u32 v4, v54, v3, s69
	v_and_b32_sdwa v3, v53, v232 dst_sel:DWORD dst_unused:UNUSED_PAD src0_sel:WORD_1 src1_sel:DWORD
	v_and_b32_sdwa v5, v52, v232 dst_sel:DWORD dst_unused:UNUSED_PAD src0_sel:WORD_1 src1_sel:DWORD
	v_and_b32_sdwa v2, v55, v232 dst_sel:DWORD dst_unused:UNUSED_PAD src0_sel:WORD_1 src1_sel:DWORD
	v_add3_u32 v3, v53, v3, s69
	v_add3_u32 v5, v52, v5, s69
	v_add3_u32 v2, v55, v2, s69
	v_and_b32_e32 v3, 0xffff0000, v3
	v_and_b32_e32 v5, 0xffff0000, v5
	v_or_b32_sdwa v3, v3, v2 dst_sel:DWORD dst_unused:UNUSED_PAD src0_sel:DWORD src1_sel:WORD_1
	v_or_b32_sdwa v2, v5, v4 dst_sel:DWORD dst_unused:UNUSED_PAD src0_sel:DWORD src1_sel:WORD_1
	global_store_dwordx2 v[0:1], v[2:3], off
	v_and_b32_sdwa v3, v50, v232 dst_sel:DWORD dst_unused:UNUSED_PAD src0_sel:WORD_1 src1_sel:DWORD
	v_add3_u32 v4, v50, v3, s69
	v_and_b32_sdwa v3, v49, v232 dst_sel:DWORD dst_unused:UNUSED_PAD src0_sel:WORD_1 src1_sel:DWORD
	v_and_b32_sdwa v5, v48, v232 dst_sel:DWORD dst_unused:UNUSED_PAD src0_sel:WORD_1 src1_sel:DWORD
	v_and_b32_sdwa v2, v51, v232 dst_sel:DWORD dst_unused:UNUSED_PAD src0_sel:WORD_1 src1_sel:DWORD
	v_add3_u32 v3, v49, v3, s69
	v_add3_u32 v5, v48, v5, s69
	v_add3_u32 v2, v51, v2, s69
	v_and_b32_e32 v3, 0xffff0000, v3
	v_and_b32_e32 v5, 0xffff0000, v5
	v_or_b32_sdwa v3, v3, v2 dst_sel:DWORD dst_unused:UNUSED_PAD src0_sel:DWORD src1_sel:WORD_1
	v_or_b32_sdwa v2, v5, v4 dst_sel:DWORD dst_unused:UNUSED_PAD src0_sel:DWORD src1_sel:WORD_1
	v_readlane_b32 s3, v255, 5
	global_store_dwordx2 v[0:1], v[2:3], off offset:32
	s_branch .LBB0_871
.LBB0_879:
	s_add_i32 s4, s4, s33
	v_readlane_b32 s2, v254, 32
	s_cmp_ge_i32 s4, s2
	s_cbranch_scc1 .LBB0_827

.LBB0_882:
	s_andn2_b64 vcc, exec, s[2:3]
	s_cbranch_vccnz .LBB0_879
	v_readlane_b32 s12, v255, 2
	v_readlane_b32 s13, v255, 0
	v_and_b32_e32 v128, 63, v216
	v_lshrrev_b32_e32 v129, 6, v216
	v_lshrrev_b32_e32 v130, 3, v128
	v_and_b32_e32 v131, 7, v128
	v_readfirstlane_b32 s10, v129
	v_lshrrev_b32_e32 v132, 1, v130
	v_lshrrev_b32_e32 v133, 2, v130
	v_xor_b32_e32 v134, v132, v133
	v_xor_b32_e32 v135, 5, v134
	v_xor_b32_e32 v134, v131, v134
	v_xor_b32_e32 v135, v131, v135
	v_lshlrev_b32_e32 v134, 4, v134
	v_lshlrev_b32_e32 v135, 4, v135
	v_lshl_add_u32 v136, v129, 5, v130
	v_mul_u32_u24_e32 v137, 0x800, v136
	v_add_u32_e32 v192, v137, v134
	v_add_u32_e32 v193, v137, v135
	v_add_u32_e32 v193, 0x4000, v193
	v_add_u32_e32 v194, 0x8000, v192
	v_add_u32_e32 v195, 0x8000, v193
	v_and_b32_e32 v138, 15, v128
	v_lshrrev_b32_e32 v139, 4, v128
	v_lshrrev_b32_e32 v140, 1, v138
	v_lshrrev_b32_e32 v141, 2, v138
	v_lshrrev_b32_e32 v142, 3, v138
	v_xor_b32_e32 v141, v141, v142
	v_and_b32_e32 v141, 1, v141
	v_xor_b32_e32 v140, v140, v141
	v_xor_b32_e32 v140, v139, v140
	v_lshlrev_b32_e32 v140, 4, v140
	v_lshl_add_u32 v140, v138, 7, v140
	v_lshrrev_b32_e32 v141, 1, v129
	v_and_b32_e32 v142, 1, v129
	v_lshl_add_u32 v196, v141, 13, v140
	v_xor_b32_e32 v197, 64, v196
	v_lshl_add_u32 v198, v142, 13, v140
	v_xor_b32_e32 v199, 64, v198
	s_lshl_b32 s10, s10, 12
	s_lshl_b32 s5, s12, 18
	s_add_u32 s2, s28, s5
	s_addc_u32 s3, s29, 0
	s_lshl_b32 s5, s13, 18
	s_add_u32 s8, s14, s5
	s_addc_u32 s9, s15, 0
	s_add_u32 m0, s10, 0x0
	s_nop 0
	global_load_lds_dwordx4 v192, s[2:3]
	s_add_u32 m0, s10, 0x400
	s_nop 0
	global_load_lds_dwordx4 v193, s[2:3]
	s_add_u32 m0, s10, 0x800
	s_nop 0
	global_load_lds_dwordx4 v194, s[2:3]
	s_add_u32 m0, s10, 0xc00
	s_nop 0
	global_load_lds_dwordx4 v195, s[2:3]
	s_add_u32 m0, s10, 0x4000
	s_nop 0
	global_load_lds_dwordx4 v192, s[8:9]
	s_add_u32 m0, s10, 0x4400
	s_nop 0
	global_load_lds_dwordx4 v193, s[8:9]
	s_add_u32 m0, s10, 0x4800
	s_nop 0
	global_load_lds_dwordx4 v194, s[8:9]
	s_add_u32 m0, s10, 0x4c00
	s_nop 0
	global_load_lds_dwordx4 v195, s[8:9]
	s_add_u32 s2, s2, 0x80
	s_addc_u32 s3, s3, 0
	s_add_u32 s8, s8, 0x80
	s_addc_u32 s9, s9, 0
	v_mov_b32_e32 v0, 0
	v_mov_b32_e32 v1, 0
	v_mov_b32_e32 v2, 0
	v_mov_b32_e32 v3, 0
	v_mov_b32_e32 v4, 0
	v_mov_b32_e32 v5, 0
	v_mov_b32_e32 v6, 0
	v_mov_b32_e32 v7, 0
	v_mov_b32_e32 v8, 0
	v_mov_b32_e32 v9, 0
	v_mov_b32_e32 v10, 0
	v_mov_b32_e32 v11, 0
	v_mov_b32_e32 v12, 0
	v_mov_b32_e32 v13, 0
	v_mov_b32_e32 v14, 0
	v_mov_b32_e32 v15, 0
	v_mov_b32_e32 v16, 0
	v_mov_b32_e32 v17, 0
	v_mov_b32_e32 v18, 0
	v_mov_b32_e32 v19, 0
	v_mov_b32_e32 v20, 0
	v_mov_b32_e32 v21, 0
	v_mov_b32_e32 v22, 0
	v_mov_b32_e32 v23, 0
	v_mov_b32_e32 v24, 0
	v_mov_b32_e32 v25, 0
	v_mov_b32_e32 v26, 0
	v_mov_b32_e32 v27, 0
	v_mov_b32_e32 v28, 0
	v_mov_b32_e32 v29, 0
	v_mov_b32_e32 v30, 0
	v_mov_b32_e32 v31, 0
	v_mov_b32_e32 v32, 0
	v_mov_b32_e32 v33, 0
	v_mov_b32_e32 v34, 0
	v_mov_b32_e32 v35, 0
	v_mov_b32_e32 v36, 0
	v_mov_b32_e32 v37, 0
	v_mov_b32_e32 v38, 0
	v_mov_b32_e32 v39, 0
	v_mov_b32_e32 v40, 0
	v_mov_b32_e32 v41, 0
	v_mov_b32_e32 v42, 0
	v_mov_b32_e32 v43, 0
	v_mov_b32_e32 v44, 0
	v_mov_b32_e32 v45, 0
	v_mov_b32_e32 v46, 0
	v_mov_b32_e32 v47, 0
	v_mov_b32_e32 v48, 0
	v_mov_b32_e32 v49, 0
	v_mov_b32_e32 v50, 0
	v_mov_b32_e32 v51, 0
	v_mov_b32_e32 v52, 0
	v_mov_b32_e32 v53, 0
	v_mov_b32_e32 v54, 0
	v_mov_b32_e32 v55, 0
	v_mov_b32_e32 v56, 0
	v_mov_b32_e32 v57, 0
	v_mov_b32_e32 v58, 0
	v_mov_b32_e32 v59, 0
	v_mov_b32_e32 v60, 0
	v_mov_b32_e32 v61, 0
	v_mov_b32_e32 v62, 0
	v_mov_b32_e32 v63, 0
	s_waitcnt vmcnt(0)
	s_barrier
	s_add_u32 m0, s10, 0x8000
	ds_read_b128 v[64:67], v196 offset:0
	global_load_lds_dwordx4 v192, s[2:3]
	s_add_u32 m0, s10, 0x8400
	ds_read_b128 v[68:71], v196 offset:2048
	global_load_lds_dwordx4 v193, s[2:3]
	s_add_u32 m0, s10, 0x8800
	ds_read_b128 v[72:75], v196 offset:4096
	global_load_lds_dwordx4 v194, s[2:3]
	s_add_u32 m0, s10, 0x8c00
	ds_read_b128 v[76:79], v196 offset:6144
	global_load_lds_dwordx4 v195, s[2:3]
	s_add_u32 m0, s10, 0xc000
	ds_read_b128 v[96:99], v198 offset:16384
	global_load_lds_dwordx4 v192, s[8:9]
	s_add_u32 m0, s10, 0xc400
	ds_read_b128 v[100:103], v198 offset:18432
	global_load_lds_dwordx4 v193, s[8:9]
	s_add_u32 m0, s10, 0xc800
	ds_read_b128 v[104:107], v198 offset:20480
	global_load_lds_dwordx4 v194, s[8:9]
	s_add_u32 m0, s10, 0xcc00
	ds_read_b128 v[108:111], v198 offset:22528
	global_load_lds_dwordx4 v195, s[8:9]
	s_add_u32 s2, s2, 0x80
	s_addc_u32 s3, s3, 0
	s_add_u32 s8, s8, 0x80
	s_addc_u32 s9, s9, 0
	ds_read_b128 v[80:83], v197 offset:0
	ds_read_b128 v[84:87], v197 offset:2048
	ds_read_b128 v[88:91], v197 offset:4096
	ds_read_b128 v[92:95], v197 offset:6144
	ds_read_b128 v[112:115], v199 offset:16384
	ds_read_b128 v[116:119], v199 offset:18432
	ds_read_b128 v[120:123], v199 offset:20480
	ds_read_b128 v[124:127], v199 offset:22528
	s_waitcnt lgkmcnt(0)
	s_mov_b32 s11, 7
.Lrs2_loop:
	s_waitcnt vmcnt(0)
	s_barrier
	v_mfma_f32_16x16x32_bf16 v[0:3], v[96:99], v[64:67], v[0:3]
	s_add_u32 m0, s10, 0x0
	ds_read_b128 v[128:131], v196 offset:32768
	v_mfma_f32_16x16x32_bf16 v[4:7], v[100:103], v[64:67], v[4:7]
	global_load_lds_dwordx4 v192, s[2:3]
	s_add_u32 m0, s10, 0x400
	v_mfma_f32_16x16x32_bf16 v[8:11], v[104:107], v[64:67], v[8:11]
	global_load_lds_dwordx4 v193, s[2:3]
	s_add_u32 m0, s10, 0x800
	ds_read_b128 v[132:135], v196 offset:34816
	v_mfma_f32_16x16x32_bf16 v[12:15], v[108:111], v[64:67], v[12:15]
	global_load_lds_dwordx4 v194, s[2:3]
	s_add_u32 m0, s10, 0xc00
	v_mfma_f32_16x16x32_bf16 v[16:19], v[96:99], v[68:71], v[16:19]
	global_load_lds_dwordx4 v195, s[2:3]
	s_add_u32 m0, s10, 0x4000
	ds_read_b128 v[136:139], v196 offset:36864
	v_mfma_f32_16x16x32_bf16 v[20:23], v[100:103], v[68:71], v[20:23]
	global_load_lds_dwordx4 v192, s[8:9]
	s_add_u32 m0, s10, 0x4400
	v_mfma_f32_16x16x32_bf16 v[24:27], v[104:107], v[68:71], v[24:27]
	global_load_lds_dwordx4 v193, s[8:9]
	s_add_u32 m0, s10, 0x4800
	ds_read_b128 v[140:143], v196 offset:38912
	v_mfma_f32_16x16x32_bf16 v[28:31], v[108:111], v[68:71], v[28:31]
	global_load_lds_dwordx4 v194, s[8:9]
	s_add_u32 m0, s10, 0x4c00
	v_mfma_f32_16x16x32_bf16 v[32:35], v[96:99], v[72:75], v[32:35]
	global_load_lds_dwordx4 v195, s[8:9]
	ds_read_b128 v[160:163], v198 offset:49152
	v_mfma_f32_16x16x32_bf16 v[36:39], v[100:103], v[72:75], v[36:39]
	s_add_u32 s2, s2, 0x80
	s_addc_u32 s3, s3, 0
	v_mfma_f32_16x16x32_bf16 v[40:43], v[104:107], v[72:75], v[40:43]
	s_add_u32 s8, s8, 0x80
	s_addc_u32 s9, s9, 0
	ds_read_b128 v[164:167], v198 offset:51200
	v_mfma_f32_16x16x32_bf16 v[44:47], v[108:111], v[72:75], v[44:47]
	v_mfma_f32_16x16x32_bf16 v[48:51], v[96:99], v[76:79], v[48:51]
	ds_read_b128 v[168:171], v198 offset:53248
	v_mfma_f32_16x16x32_bf16 v[52:55], v[100:103], v[76:79], v[52:55]
	v_mfma_f32_16x16x32_bf16 v[56:59], v[104:107], v[76:79], v[56:59]
	ds_read_b128 v[172:175], v198 offset:55296
	v_mfma_f32_16x16x32_bf16 v[60:63], v[108:111], v[76:79], v[60:63]
	v_mfma_f32_16x16x32_bf16 v[0:3], v[112:115], v[80:83], v[0:3]
	ds_read_b128 v[144:147], v197 offset:32768
	v_mfma_f32_16x16x32_bf16 v[4:7], v[116:119], v[80:83], v[4:7]
	v_mfma_f32_16x16x32_bf16 v[8:11], v[120:123], v[80:83], v[8:11]
	ds_read_b128 v[148:151], v197 offset:34816
	v_mfma_f32_16x16x32_bf16 v[12:15], v[124:127], v[80:83], v[12:15]
	v_mfma_f32_16x16x32_bf16 v[16:19], v[112:115], v[84:87], v[16:19]
	ds_read_b128 v[152:155], v197 offset:36864
	v_mfma_f32_16x16x32_bf16 v[20:23], v[116:119], v[84:87], v[20:23]
	v_mfma_f32_16x16x32_bf16 v[24:27], v[120:123], v[84:87], v[24:27]
	ds_read_b128 v[156:159], v197 offset:38912
	v_mfma_f32_16x16x32_bf16 v[28:31], v[124:127], v[84:87], v[28:31]
	v_mfma_f32_16x16x32_bf16 v[32:35], v[112:115], v[88:91], v[32:35]
	ds_read_b128 v[176:179], v199 offset:49152
	v_mfma_f32_16x16x32_bf16 v[36:39], v[116:119], v[88:91], v[36:39]
	v_mfma_f32_16x16x32_bf16 v[40:43], v[120:123], v[88:91], v[40:43]
	ds_read_b128 v[180:183], v199 offset:51200
	v_mfma_f32_16x16x32_bf16 v[44:47], v[124:127], v[88:91], v[44:47]
	v_mfma_f32_16x16x32_bf16 v[48:51], v[112:115], v[92:95], v[48:51]
	ds_read_b128 v[184:187], v199 offset:53248
	v_mfma_f32_16x16x32_bf16 v[52:55], v[116:119], v[92:95], v[52:55]
	v_mfma_f32_16x16x32_bf16 v[56:59], v[120:123], v[92:95], v[56:59]
	ds_read_b128 v[188:191], v199 offset:55296
	v_mfma_f32_16x16x32_bf16 v[60:63], v[124:127], v[92:95], v[60:63]
	s_waitcnt lgkmcnt(0)
	s_waitcnt vmcnt(0)
	s_barrier
	v_mfma_f32_16x16x32_bf16 v[0:3], v[160:163], v[128:131], v[0:3]
	s_add_u32 m0, s10, 0x8000
	ds_read_b128 v[64:67], v196 offset:0
	v_mfma_f32_16x16x32_bf16 v[4:7], v[164:167], v[128:131], v[4:7]
	global_load_lds_dwordx4 v192, s[2:3]
	s_add_u32 m0, s10, 0x8400
	v_mfma_f32_16x16x32_bf16 v[8:11], v[168:171], v[128:131], v[8:11]
	global_load_lds_dwordx4 v193, s[2:3]
	s_add_u32 m0, s10, 0x8800
	ds_read_b128 v[68:71], v196 offset:2048
	v_mfma_f32_16x16x32_bf16 v[12:15], v[172:175], v[128:131], v[12:15]
	global_load_lds_dwordx4 v194, s[2:3]
	s_add_u32 m0, s10, 0x8c00
	v_mfma_f32_16x16x32_bf16 v[16:19], v[160:163], v[132:135], v[16:19]
	global_load_lds_dwordx4 v195, s[2:3]
	s_add_u32 m0, s10, 0xc000
	ds_read_b128 v[72:75], v196 offset:4096
	v_mfma_f32_16x16x32_bf16 v[20:23], v[164:167], v[132:135], v[20:23]
	global_load_lds_dwordx4 v192, s[8:9]
	s_add_u32 m0, s10, 0xc400
	v_mfma_f32_16x16x32_bf16 v[24:27], v[168:171], v[132:135], v[24:27]
	global_load_lds_dwordx4 v193, s[8:9]
	s_add_u32 m0, s10, 0xc800
	ds_read_b128 v[76:79], v196 offset:6144
	v_mfma_f32_16x16x32_bf16 v[28:31], v[172:175], v[132:135], v[28:31]
	global_load_lds_dwordx4 v194, s[8:9]
	s_add_u32 m0, s10, 0xcc00
	v_mfma_f32_16x16x32_bf16 v[32:35], v[160:163], v[136:139], v[32:35]
	global_load_lds_dwordx4 v195, s[8:9]
	ds_read_b128 v[96:99], v198 offset:16384
	v_mfma_f32_16x16x32_bf16 v[36:39], v[164:167], v[136:139], v[36:39]
	s_add_u32 s2, s2, 0x80
	s_addc_u32 s3, s3, 0
	v_mfma_f32_16x16x32_bf16 v[40:43], v[168:171], v[136:139], v[40:43]
	s_add_u32 s8, s8, 0x80
	s_addc_u32 s9, s9, 0
	ds_read_b128 v[100:103], v198 offset:18432
	v_mfma_f32_16x16x32_bf16 v[44:47], v[172:175], v[136:139], v[44:47]
	v_mfma_f32_16x16x32_bf16 v[48:51], v[160:163], v[140:143], v[48:51]
	ds_read_b128 v[104:107], v198 offset:20480
	v_mfma_f32_16x16x32_bf16 v[52:55], v[164:167], v[140:143], v[52:55]
	v_mfma_f32_16x16x32_bf16 v[56:59], v[168:171], v[140:143], v[56:59]
	ds_read_b128 v[108:111], v198 offset:22528
	v_mfma_f32_16x16x32_bf16 v[60:63], v[172:175], v[140:143], v[60:63]
	v_mfma_f32_16x16x32_bf16 v[0:3], v[176:179], v[144:147], v[0:3]
	ds_read_b128 v[80:83], v197 offset:0
	v_mfma_f32_16x16x32_bf16 v[4:7], v[180:183], v[144:147], v[4:7]
	v_mfma_f32_16x16x32_bf16 v[8:11], v[184:187], v[144:147], v[8:11]
	ds_read_b128 v[84:87], v197 offset:2048
	v_mfma_f32_16x16x32_bf16 v[12:15], v[188:191], v[144:147], v[12:15]
	v_mfma_f32_16x16x32_bf16 v[16:19], v[176:179], v[148:151], v[16:19]
	ds_read_b128 v[88:91], v197 offset:4096
	v_mfma_f32_16x16x32_bf16 v[20:23], v[180:183], v[148:151], v[20:23]
	v_mfma_f32_16x16x32_bf16 v[24:27], v[184:187], v[148:151], v[24:27]
	ds_read_b128 v[92:95], v197 offset:6144
	v_mfma_f32_16x16x32_bf16 v[28:31], v[188:191], v[148:151], v[28:31]
	v_mfma_f32_16x16x32_bf16 v[32:35], v[176:179], v[152:155], v[32:35]
	ds_read_b128 v[112:115], v199 offset:16384
	v_mfma_f32_16x16x32_bf16 v[36:39], v[180:183], v[152:155], v[36:39]
	v_mfma_f32_16x16x32_bf16 v[40:43], v[184:187], v[152:155], v[40:43]
	ds_read_b128 v[116:119], v199 offset:18432
	v_mfma_f32_16x16x32_bf16 v[44:47], v[188:191], v[152:155], v[44:47]
	v_mfma_f32_16x16x32_bf16 v[48:51], v[176:179], v[156:159], v[48:51]
	ds_read_b128 v[120:123], v199 offset:20480
	v_mfma_f32_16x16x32_bf16 v[52:55], v[180:183], v[156:159], v[52:55]
	v_mfma_f32_16x16x32_bf16 v[56:59], v[184:187], v[156:159], v[56:59]
	ds_read_b128 v[124:127], v199 offset:22528
	v_mfma_f32_16x16x32_bf16 v[60:63], v[188:191], v[156:159], v[60:63]
	s_waitcnt lgkmcnt(0)
	s_sub_u32 s11, s11, 1
	s_cmp_lg_u32 s11, 0
	s_cbranch_scc1 .Lrs2_loop
	s_waitcnt vmcnt(0)
	s_barrier
	v_mfma_f32_16x16x32_bf16 v[0:3], v[96:99], v[64:67], v[0:3]
	ds_read_b128 v[128:131], v196 offset:32768
	v_mfma_f32_16x16x32_bf16 v[4:7], v[100:103], v[64:67], v[4:7]
	v_mfma_f32_16x16x32_bf16 v[8:11], v[104:107], v[64:67], v[8:11]
	ds_read_b128 v[132:135], v196 offset:34816
	v_mfma_f32_16x16x32_bf16 v[12:15], v[108:111], v[64:67], v[12:15]
	v_mfma_f32_16x16x32_bf16 v[16:19], v[96:99], v[68:71], v[16:19]
	ds_read_b128 v[136:139], v196 offset:36864
	v_mfma_f32_16x16x32_bf16 v[20:23], v[100:103], v[68:71], v[20:23]
	v_mfma_f32_16x16x32_bf16 v[24:27], v[104:107], v[68:71], v[24:27]
	ds_read_b128 v[140:143], v196 offset:38912
	v_mfma_f32_16x16x32_bf16 v[28:31], v[108:111], v[68:71], v[28:31]
	v_mfma_f32_16x16x32_bf16 v[32:35], v[96:99], v[72:75], v[32:35]
	ds_read_b128 v[160:163], v198 offset:49152
	v_mfma_f32_16x16x32_bf16 v[36:39], v[100:103], v[72:75], v[36:39]
	v_mfma_f32_16x16x32_bf16 v[40:43], v[104:107], v[72:75], v[40:43]
	ds_read_b128 v[164:167], v198 offset:51200
	v_mfma_f32_16x16x32_bf16 v[44:47], v[108:111], v[72:75], v[44:47]
	v_mfma_f32_16x16x32_bf16 v[48:51], v[96:99], v[76:79], v[48:51]
	ds_read_b128 v[168:171], v198 offset:53248
	v_mfma_f32_16x16x32_bf16 v[52:55], v[100:103], v[76:79], v[52:55]
	v_mfma_f32_16x16x32_bf16 v[56:59], v[104:107], v[76:79], v[56:59]
	ds_read_b128 v[172:175], v198 offset:55296
	v_mfma_f32_16x16x32_bf16 v[60:63], v[108:111], v[76:79], v[60:63]
	v_mfma_f32_16x16x32_bf16 v[0:3], v[112:115], v[80:83], v[0:3]
	ds_read_b128 v[144:147], v197 offset:32768
	v_mfma_f32_16x16x32_bf16 v[4:7], v[116:119], v[80:83], v[4:7]
	v_mfma_f32_16x16x32_bf16 v[8:11], v[120:123], v[80:83], v[8:11]
	ds_read_b128 v[148:151], v197 offset:34816
	v_mfma_f32_16x16x32_bf16 v[12:15], v[124:127], v[80:83], v[12:15]
	v_mfma_f32_16x16x32_bf16 v[16:19], v[112:115], v[84:87], v[16:19]
	ds_read_b128 v[152:155], v197 offset:36864
	v_mfma_f32_16x16x32_bf16 v[20:23], v[116:119], v[84:87], v[20:23]
	v_mfma_f32_16x16x32_bf16 v[24:27], v[120:123], v[84:87], v[24:27]
	ds_read_b128 v[156:159], v197 offset:38912
	v_mfma_f32_16x16x32_bf16 v[28:31], v[124:127], v[84:87], v[28:31]
	v_mfma_f32_16x16x32_bf16 v[32:35], v[112:115], v[88:91], v[32:35]
	ds_read_b128 v[176:179], v199 offset:49152
	v_mfma_f32_16x16x32_bf16 v[36:39], v[116:119], v[88:91], v[36:39]
	v_mfma_f32_16x16x32_bf16 v[40:43], v[120:123], v[88:91], v[40:43]
	ds_read_b128 v[180:183], v199 offset:51200
	v_mfma_f32_16x16x32_bf16 v[44:47], v[124:127], v[88:91], v[44:47]
	v_mfma_f32_16x16x32_bf16 v[48:51], v[112:115], v[92:95], v[48:51]
	ds_read_b128 v[184:187], v199 offset:53248
	v_mfma_f32_16x16x32_bf16 v[52:55], v[116:119], v[92:95], v[52:55]
	v_mfma_f32_16x16x32_bf16 v[56:59], v[120:123], v[92:95], v[56:59]
	ds_read_b128 v[188:191], v199 offset:55296
	v_mfma_f32_16x16x32_bf16 v[60:63], v[124:127], v[92:95], v[60:63]
	s_waitcnt lgkmcnt(0)
	v_readlane_b32 s2, v253, 6
	v_readlane_b32 s3, v253, 7
	s_lshl_b32 s5, s12, 19
	s_lshl_b32 s8, s13, 9
	s_add_u32 s5, s5, s8
	s_add_u32 s2, s2, s5
	s_addc_u32 s3, s3, 0
	v_and_b32_e32 v196, 63, v216
	v_lshrrev_b32_e32 v197, 6, v216
	v_and_b32_e32 v198, 15, v196
	v_lshrrev_b32_e32 v196, 4, v196
	v_lshlrev_b32_e32 v196, 4, v196
	v_lshl_add_u32 v196, v198, 12, v196
	v_and_b32_e32 v198, 1, v197
	v_lshl_add_u32 v196, v198, 8, v196
	v_lshrrev_b32_e32 v197, 1, v197
	v_lshl_add_u32 v192, v197, 18, v196
	v_add_u32_e32 v193, 0x10000, v192
	v_add_u32_e32 v194, 0x20000, v192
	v_add_u32_e32 v195, 0x30000, v192
	s_nop 1
	global_load_dwordx4 v[64:67], v192, s[2:3]
	global_load_dwordx4 v[68:71], v192, s[2:3] offset:64
	global_load_dwordx4 v[72:75], v192, s[2:3] offset:128
	global_load_dwordx4 v[76:79], v192, s[2:3] offset:192
	global_load_dwordx4 v[80:83], v193, s[2:3]
	global_load_dwordx4 v[84:87], v193, s[2:3] offset:64
	global_load_dwordx4 v[88:91], v193, s[2:3] offset:128
	global_load_dwordx4 v[92:95], v193, s[2:3] offset:192
	global_load_dwordx4 v[96:99], v194, s[2:3]
	global_load_dwordx4 v[100:103], v194, s[2:3] offset:64
	global_load_dwordx4 v[104:107], v194, s[2:3] offset:128
	global_load_dwordx4 v[108:111], v194, s[2:3] offset:192
	global_load_dwordx4 v[112:115], v195, s[2:3]
	global_load_dwordx4 v[116:119], v195, s[2:3] offset:64
	global_load_dwordx4 v[120:123], v195, s[2:3] offset:128
	global_load_dwordx4 v[124:127], v195, s[2:3] offset:192
	v_mfma_f32_16x16x32_bf16 v[0:3], v[160:163], v[128:131], v[0:3]
	v_mfma_f32_16x16x32_bf16 v[4:7], v[164:167], v[128:131], v[4:7]
	v_mfma_f32_16x16x32_bf16 v[8:11], v[168:171], v[128:131], v[8:11]
	v_mfma_f32_16x16x32_bf16 v[12:15], v[172:175], v[128:131], v[12:15]
	v_mfma_f32_16x16x32_bf16 v[16:19], v[160:163], v[132:135], v[16:19]
	v_mfma_f32_16x16x32_bf16 v[20:23], v[164:167], v[132:135], v[20:23]
	v_mfma_f32_16x16x32_bf16 v[24:27], v[168:171], v[132:135], v[24:27]
	v_mfma_f32_16x16x32_bf16 v[28:31], v[172:175], v[132:135], v[28:31]
	v_mfma_f32_16x16x32_bf16 v[32:35], v[160:163], v[136:139], v[32:35]
	v_mfma_f32_16x16x32_bf16 v[36:39], v[164:167], v[136:139], v[36:39]
	v_mfma_f32_16x16x32_bf16 v[40:43], v[168:171], v[136:139], v[40:43]
	v_mfma_f32_16x16x32_bf16 v[44:47], v[172:175], v[136:139], v[44:47]
	v_mfma_f32_16x16x32_bf16 v[48:51], v[160:163], v[140:143], v[48:51]
	v_mfma_f32_16x16x32_bf16 v[52:55], v[164:167], v[140:143], v[52:55]
	v_mfma_f32_16x16x32_bf16 v[56:59], v[168:171], v[140:143], v[56:59]
	v_mfma_f32_16x16x32_bf16 v[60:63], v[172:175], v[140:143], v[60:63]
	v_mfma_f32_16x16x32_bf16 v[0:3], v[176:179], v[144:147], v[0:3]
	v_mfma_f32_16x16x32_bf16 v[4:7], v[180:183], v[144:147], v[4:7]
	v_mfma_f32_16x16x32_bf16 v[8:11], v[184:187], v[144:147], v[8:11]
	v_mfma_f32_16x16x32_bf16 v[12:15], v[188:191], v[144:147], v[12:15]
	v_mfma_f32_16x16x32_bf16 v[16:19], v[176:179], v[148:151], v[16:19]
	v_mfma_f32_16x16x32_bf16 v[20:23], v[180:183], v[148:151], v[20:23]
	v_mfma_f32_16x16x32_bf16 v[24:27], v[184:187], v[148:151], v[24:27]
	v_mfma_f32_16x16x32_bf16 v[28:31], v[188:191], v[148:151], v[28:31]
	v_mfma_f32_16x16x32_bf16 v[32:35], v[176:179], v[152:155], v[32:35]
	v_mfma_f32_16x16x32_bf16 v[36:39], v[180:183], v[152:155], v[36:39]
	v_mfma_f32_16x16x32_bf16 v[40:43], v[184:187], v[152:155], v[40:43]
	v_mfma_f32_16x16x32_bf16 v[44:47], v[188:191], v[152:155], v[44:47]
	v_mfma_f32_16x16x32_bf16 v[48:51], v[176:179], v[156:159], v[48:51]
	v_mfma_f32_16x16x32_bf16 v[52:55], v[180:183], v[156:159], v[52:55]
	v_mfma_f32_16x16x32_bf16 v[56:59], v[184:187], v[156:159], v[56:59]
	v_mfma_f32_16x16x32_bf16 v[60:63], v[188:191], v[156:159], v[60:63]
	s_nop 7
	s_nop 7
	s_waitcnt vmcnt(15)
	v_pk_add_f32 v[66:67], v[2:3], v[66:67]
	v_pk_add_f32 v[64:65], v[0:1], v[64:65]
	global_store_dwordx4 v192, v[64:67], s[2:3]
	s_waitcnt vmcnt(15)
	v_pk_add_f32 v[70:71], v[6:7], v[70:71]
	v_pk_add_f32 v[68:69], v[4:5], v[68:69]
	global_store_dwordx4 v192, v[68:71], s[2:3] offset:64
	s_waitcnt vmcnt(15)
	v_pk_add_f32 v[74:75], v[10:11], v[74:75]
	v_pk_add_f32 v[72:73], v[8:9], v[72:73]
	global_store_dwordx4 v192, v[72:75], s[2:3] offset:128
	s_waitcnt vmcnt(15)
	v_pk_add_f32 v[78:79], v[14:15], v[78:79]
	v_pk_add_f32 v[76:77], v[12:13], v[76:77]
	global_store_dwordx4 v192, v[76:79], s[2:3] offset:192
	s_waitcnt vmcnt(15)
	v_pk_add_f32 v[82:83], v[18:19], v[82:83]
	v_pk_add_f32 v[80:81], v[16:17], v[80:81]
	global_store_dwordx4 v193, v[80:83], s[2:3]
	s_waitcnt vmcnt(15)
	v_pk_add_f32 v[86:87], v[22:23], v[86:87]
	v_pk_add_f32 v[84:85], v[20:21], v[84:85]
	global_store_dwordx4 v193, v[84:87], s[2:3] offset:64
	s_waitcnt vmcnt(15)
	v_pk_add_f32 v[90:91], v[26:27], v[90:91]
	v_pk_add_f32 v[88:89], v[24:25], v[88:89]
	global_store_dwordx4 v193, v[88:91], s[2:3] offset:128
	s_waitcnt vmcnt(15)
	v_pk_add_f32 v[94:95], v[30:31], v[94:95]
	v_pk_add_f32 v[92:93], v[28:29], v[92:93]
	global_store_dwordx4 v193, v[92:95], s[2:3] offset:192
	s_waitcnt vmcnt(15)
	v_pk_add_f32 v[98:99], v[34:35], v[98:99]
	v_pk_add_f32 v[96:97], v[32:33], v[96:97]
	global_store_dwordx4 v194, v[96:99], s[2:3]
	s_waitcnt vmcnt(15)
	v_pk_add_f32 v[102:103], v[38:39], v[102:103]
	v_pk_add_f32 v[100:101], v[36:37], v[100:101]
	global_store_dwordx4 v194, v[100:103], s[2:3] offset:64
	s_waitcnt vmcnt(15)
	v_pk_add_f32 v[106:107], v[42:43], v[106:107]
	v_pk_add_f32 v[104:105], v[40:41], v[104:105]
	global_store_dwordx4 v194, v[104:107], s[2:3] offset:128
	s_waitcnt vmcnt(15)
	v_pk_add_f32 v[110:111], v[46:47], v[110:111]
	v_pk_add_f32 v[108:109], v[44:45], v[108:109]
	global_store_dwordx4 v194, v[108:111], s[2:3] offset:192
	s_waitcnt vmcnt(15)
	v_pk_add_f32 v[114:115], v[50:51], v[114:115]
	v_pk_add_f32 v[112:113], v[48:49], v[112:113]
	global_store_dwordx4 v195, v[112:115], s[2:3]
	s_waitcnt vmcnt(15)
	v_pk_add_f32 v[118:119], v[54:55], v[118:119]
	v_pk_add_f32 v[116:117], v[52:53], v[116:117]
	global_store_dwordx4 v195, v[116:119], s[2:3] offset:64
	s_waitcnt vmcnt(15)
	v_pk_add_f32 v[122:123], v[58:59], v[122:123]
	v_pk_add_f32 v[120:121], v[56:57], v[120:121]
	global_store_dwordx4 v195, v[120:123], s[2:3] offset:128
	s_waitcnt vmcnt(15)
	v_pk_add_f32 v[126:127], v[62:63], v[126:127]
	v_pk_add_f32 v[124:125], v[60:61], v[124:125]
	global_store_dwordx4 v195, v[124:127], s[2:3] offset:192
	s_branch .LBB0_879

.LBB0_899:
	s_cmpk_gt_u32 s9, 0x3bf
	s_cselect_b64 s[2:3], -1, 0
	s_and_b64 vcc, exec, s[2:3]
	s_barrier
	s_waitcnt vmcnt(9)
	ds_write_b128 v192, v[124:127]
	ds_write_b128 v192, v[120:123] offset:4608
	ds_write_b128 v192, v[128:131] offset:9216
	s_waitcnt vmcnt(7)
	ds_write_b128 v192, v[132:135] offset:13824
	ds_write_b128 v192, v[136:139] offset:18432
	s_waitcnt vmcnt(6)
	ds_write_b128 v192, v[140:143] offset:23040
	s_waitcnt vmcnt(5)
	ds_write_b128 v192, v[144:147] offset:27648
	s_waitcnt vmcnt(4)
	ds_write_b128 v192, v[148:151] offset:32256
	s_waitcnt vmcnt(3)
	ds_write_b128 v192, v[152:155] offset:36864
	s_waitcnt vmcnt(2)
	ds_write_b128 v192, v[156:159] offset:41472
	s_waitcnt vmcnt(1)
	ds_write_b128 v192, v[160:163] offset:46080
	s_waitcnt vmcnt(0)
	ds_write_b128 v192, v[164:167] offset:50688
	s_waitcnt lgkmcnt(0)
	s_barrier
	s_cbranch_vccnz .LBB0_898
	v_lshl_add_u64 v[128:129], v[196:197], 0, v[200:201]
	v_add_co_u32_e32 v120, vcc, 0x7650000, v128
	v_lshl_add_u64 v[160:161], v[198:199], 0, v[200:201]
	s_nop 0
	v_addc_co_u32_e32 v121, vcc, 0, v129, vcc
	v_add_co_u32_e32 v122, vcc, 0x7660000, v128
	s_nop 1
	v_addc_co_u32_e32 v123, vcc, 0, v129, vcc
	v_add_co_u32_e32 v130, vcc, 0x7670000, v128
	global_load_dwordx4 v[124:127], v[120:121], off offset:128
	s_nop 0
	global_load_dwordx4 v[120:123], v[122:123], off offset:128
	v_addc_co_u32_e32 v131, vcc, 0, v129, vcc
	v_add_co_u32_e32 v132, vcc, 0x7680000, v128
	s_nop 1
	v_addc_co_u32_e32 v133, vcc, 0, v129, vcc
	v_add_co_u32_e32 v136, vcc, 0x65d0000, v160
	global_load_dwordx4 v[128:131], v[130:131], off offset:128
	s_nop 0
	global_load_dwordx4 v[132:135], v[132:133], off offset:128
	v_addc_co_u32_e32 v137, vcc, 0, v161, vcc
	v_add_co_u32_e32 v140, vcc, 0x65e0000, v160
	s_nop 1
	v_addc_co_u32_e32 v141, vcc, 0, v161, vcc
	v_add_co_u32_e32 v144, vcc, 0x65f0000, v160
	global_load_dwordx4 v[136:139], v[136:137], off offset:128
	s_nop 0
	global_load_dwordx4 v[140:143], v[140:141], off offset:128
	v_addc_co_u32_e32 v145, vcc, 0, v161, vcc
	v_add_co_u32_e32 v148, vcc, 0x6600000, v160
	s_nop 1
	v_addc_co_u32_e32 v149, vcc, 0, v161, vcc
	v_add_co_u32_e32 v152, vcc, 0x6610000, v160
	global_load_dwordx4 v[144:147], v[144:145], off offset:128
	s_nop 0
	global_load_dwordx4 v[148:151], v[148:149], off offset:128
	v_addc_co_u32_e32 v153, vcc, 0, v161, vcc
	v_add_co_u32_e32 v156, vcc, 0x6620000, v160
	s_nop 1
	v_addc_co_u32_e32 v157, vcc, 0, v161, vcc
	v_add_co_u32_e32 v162, vcc, 0x6630000, v160
	global_load_dwordx4 v[152:155], v[152:153], off offset:128
	s_nop 0
	global_load_dwordx4 v[156:159], v[156:157], off offset:128
	v_addc_co_u32_e32 v163, vcc, 0, v161, vcc
	v_add_co_u32_e32 v164, vcc, 0x6640000, v160
	s_nop 1
	v_addc_co_u32_e32 v165, vcc, 0, v161, vcc
	global_load_dwordx4 v[160:163], v[162:163], off offset:128
	s_nop 0
	global_load_dwordx4 v[164:167], v[164:165], off offset:128
	s_branch .LBB0_898
.LBB0_902:
	s_add_i32 s4, s4, s33
	v_readlane_b32 s2, v254, 32
	s_cmp_ge_i32 s4, s2
	s_cbranch_scc1 .LBB0_862

.LBB0_905:
	s_andn2_b64 vcc, exec, s[2:3]
	s_cbranch_vccnz .LBB0_902
	v_readlane_b32 s12, v255, 31
	v_readlane_b32 s13, v255, 32
	v_and_b32_e32 v128, 63, v216
	v_lshrrev_b32_e32 v129, 6, v216
	v_lshrrev_b32_e32 v130, 3, v128
	v_and_b32_e32 v131, 7, v128
	v_readfirstlane_b32 s10, v129
	v_lshrrev_b32_e32 v132, 1, v130
	v_lshrrev_b32_e32 v133, 2, v130
	v_xor_b32_e32 v134, v132, v133
	v_xor_b32_e32 v135, 5, v134
	v_xor_b32_e32 v134, v131, v134
	v_xor_b32_e32 v135, v131, v135
	v_lshlrev_b32_e32 v134, 4, v134
	v_lshlrev_b32_e32 v135, 4, v135
	v_lshl_add_u32 v136, v129, 5, v130
	v_mul_u32_u24_e32 v137, 0x1600, v136
	v_add_u32_e32 v192, v137, v134
	v_add_u32_e32 v193, v137, v135
	v_add_u32_e32 v193, 0xb000, v193
	v_add_u32_e32 v194, 0x16000, v192
	v_add_u32_e32 v195, 0x16000, v193
	v_and_b32_e32 v138, 15, v128
	v_lshrrev_b32_e32 v139, 4, v128
	v_lshrrev_b32_e32 v140, 1, v138
	v_lshrrev_b32_e32 v141, 2, v138
	v_lshrrev_b32_e32 v142, 3, v138
	v_xor_b32_e32 v141, v141, v142
	v_and_b32_e32 v141, 1, v141
	v_xor_b32_e32 v140, v140, v141
	v_xor_b32_e32 v140, v139, v140
	v_lshlrev_b32_e32 v140, 4, v140
	v_lshl_add_u32 v140, v138, 7, v140
	v_lshrrev_b32_e32 v141, 1, v129
	v_and_b32_e32 v142, 1, v129
	v_lshl_add_u32 v196, v141, 13, v140
	v_xor_b32_e32 v197, 64, v196
	v_lshl_add_u32 v198, v142, 13, v140
	v_xor_b32_e32 v199, 64, v198
	s_lshl_b32 s10, s10, 12
	s_mul_hi_u32 s11, s12, 0xb0000
	s_mul_i32 s5, s12, 0xb0000
	s_add_u32 s2, s28, s5
	s_addc_u32 s3, s29, s11
	v_readlane_b32 s8, v253, 23
	v_readlane_b32 s9, v253, 24
	s_mul_hi_u32 s11, s13, 0xb0000
	s_mul_i32 s5, s13, 0xb0000
	s_add_u32 s8, s8, s5
	s_addc_u32 s9, s9, s11
	s_add_u32 m0, s10, 0x0
	s_nop 0
	global_load_lds_dwordx4 v192, s[2:3]
	s_add_u32 m0, s10, 0x400
	s_nop 0
	global_load_lds_dwordx4 v193, s[2:3]
	s_add_u32 m0, s10, 0x800
	s_nop 0
	global_load_lds_dwordx4 v194, s[2:3]
	s_add_u32 m0, s10, 0xc00
	s_nop 0
	global_load_lds_dwordx4 v195, s[2:3]
	s_add_u32 m0, s10, 0x4000
	s_nop 0
	global_load_lds_dwordx4 v192, s[8:9]
	s_add_u32 m0, s10, 0x4400
	s_nop 0
	global_load_lds_dwordx4 v193, s[8:9]
	s_add_u32 m0, s10, 0x4800
	s_nop 0
	global_load_lds_dwordx4 v194, s[8:9]
	s_add_u32 m0, s10, 0x4c00
	s_nop 0
	global_load_lds_dwordx4 v195, s[8:9]
	s_add_u32 s2, s2, 0x80
	s_addc_u32 s3, s3, 0
	s_add_u32 s8, s8, 0x80
	s_addc_u32 s9, s9, 0
	v_mov_b32_e32 v0, 0
	v_mov_b32_e32 v1, 0
	v_mov_b32_e32 v2, 0
	v_mov_b32_e32 v3, 0
	v_mov_b32_e32 v4, 0
	v_mov_b32_e32 v5, 0
	v_mov_b32_e32 v6, 0
	v_mov_b32_e32 v7, 0
	v_mov_b32_e32 v8, 0
	v_mov_b32_e32 v9, 0
	v_mov_b32_e32 v10, 0
	v_mov_b32_e32 v11, 0
	v_mov_b32_e32 v12, 0
	v_mov_b32_e32 v13, 0
	v_mov_b32_e32 v14, 0
	v_mov_b32_e32 v15, 0
	v_mov_b32_e32 v16, 0
	v_mov_b32_e32 v17, 0
	v_mov_b32_e32 v18, 0
	v_mov_b32_e32 v19, 0
	v_mov_b32_e32 v20, 0
	v_mov_b32_e32 v21, 0
	v_mov_b32_e32 v22, 0
	v_mov_b32_e32 v23, 0
	v_mov_b32_e32 v24, 0
	v_mov_b32_e32 v25, 0
	v_mov_b32_e32 v26, 0
	v_mov_b32_e32 v27, 0
	v_mov_b32_e32 v28, 0
	v_mov_b32_e32 v29, 0
	v_mov_b32_e32 v30, 0
	v_mov_b32_e32 v31, 0
	v_mov_b32_e32 v32, 0
	v_mov_b32_e32 v33, 0
	v_mov_b32_e32 v34, 0
	v_mov_b32_e32 v35, 0
	v_mov_b32_e32 v36, 0
	v_mov_b32_e32 v37, 0
	v_mov_b32_e32 v38, 0
	v_mov_b32_e32 v39, 0
	v_mov_b32_e32 v40, 0
	v_mov_b32_e32 v41, 0
	v_mov_b32_e32 v42, 0
	v_mov_b32_e32 v43, 0
	v_mov_b32_e32 v44, 0
	v_mov_b32_e32 v45, 0
	v_mov_b32_e32 v46, 0
	v_mov_b32_e32 v47, 0
	v_mov_b32_e32 v48, 0
	v_mov_b32_e32 v49, 0
	v_mov_b32_e32 v50, 0
	v_mov_b32_e32 v51, 0
	v_mov_b32_e32 v52, 0
	v_mov_b32_e32 v53, 0
	v_mov_b32_e32 v54, 0
	v_mov_b32_e32 v55, 0
	v_mov_b32_e32 v56, 0
	v_mov_b32_e32 v57, 0
	v_mov_b32_e32 v58, 0
	v_mov_b32_e32 v59, 0
	v_mov_b32_e32 v60, 0
	v_mov_b32_e32 v61, 0
	v_mov_b32_e32 v62, 0
	v_mov_b32_e32 v63, 0
	s_waitcnt vmcnt(0)
	s_barrier
	s_add_u32 m0, s10, 0x8000
	ds_read_b128 v[64:67], v196 offset:0
	global_load_lds_dwordx4 v192, s[2:3]
	s_add_u32 m0, s10, 0x8400
	ds_read_b128 v[68:71], v196 offset:2048
	global_load_lds_dwordx4 v193, s[2:3]
	s_add_u32 m0, s10, 0x8800
	ds_read_b128 v[72:75], v196 offset:4096
	global_load_lds_dwordx4 v194, s[2:3]
	s_add_u32 m0, s10, 0x8c00
	ds_read_b128 v[76:79], v196 offset:6144
	global_load_lds_dwordx4 v195, s[2:3]
	s_add_u32 m0, s10, 0xc000
	ds_read_b128 v[96:99], v198 offset:16384
	global_load_lds_dwordx4 v192, s[8:9]
	s_add_u32 m0, s10, 0xc400
	ds_read_b128 v[100:103], v198 offset:18432
	global_load_lds_dwordx4 v193, s[8:9]
	s_add_u32 m0, s10, 0xc800
	ds_read_b128 v[104:107], v198 offset:20480
	global_load_lds_dwordx4 v194, s[8:9]
	s_add_u32 m0, s10, 0xcc00
	ds_read_b128 v[108:111], v198 offset:22528
	global_load_lds_dwordx4 v195, s[8:9]
	s_add_u32 s2, s2, 0x80
	s_addc_u32 s3, s3, 0
	s_add_u32 s8, s8, 0x80
	s_addc_u32 s9, s9, 0
	ds_read_b128 v[80:83], v197 offset:0
	ds_read_b128 v[84:87], v197 offset:2048
	ds_read_b128 v[88:91], v197 offset:4096
	ds_read_b128 v[92:95], v197 offset:6144
	ds_read_b128 v[112:115], v199 offset:16384
	ds_read_b128 v[116:119], v199 offset:18432
	ds_read_b128 v[120:123], v199 offset:20480
	ds_read_b128 v[124:127], v199 offset:22528
	s_waitcnt lgkmcnt(0)
	s_mov_b32 s11, 21
.Lrs3_loop:
	s_waitcnt vmcnt(0)
	s_barrier
	v_mfma_f32_16x16x32_bf16 v[0:3], v[96:99], v[64:67], v[0:3]
	s_add_u32 m0, s10, 0x0
	ds_read_b128 v[128:131], v196 offset:32768
	v_mfma_f32_16x16x32_bf16 v[4:7], v[100:103], v[64:67], v[4:7]
	global_load_lds_dwordx4 v192, s[2:3]
	s_add_u32 m0, s10, 0x400
	v_mfma_f32_16x16x32_bf16 v[8:11], v[104:107], v[64:67], v[8:11]
	global_load_lds_dwordx4 v193, s[2:3]
	s_add_u32 m0, s10, 0x800
	ds_read_b128 v[132:135], v196 offset:34816
	v_mfma_f32_16x16x32_bf16 v[12:15], v[108:111], v[64:67], v[12:15]
	global_load_lds_dwordx4 v194, s[2:3]
	s_add_u32 m0, s10, 0xc00
	v_mfma_f32_16x16x32_bf16 v[16:19], v[96:99], v[68:71], v[16:19]
	global_load_lds_dwordx4 v195, s[2:3]
	s_add_u32 m0, s10, 0x4000
	ds_read_b128 v[136:139], v196 offset:36864
	v_mfma_f32_16x16x32_bf16 v[20:23], v[100:103], v[68:71], v[20:23]
	global_load_lds_dwordx4 v192, s[8:9]
	s_add_u32 m0, s10, 0x4400
	v_mfma_f32_16x16x32_bf16 v[24:27], v[104:107], v[68:71], v[24:27]
	global_load_lds_dwordx4 v193, s[8:9]
	s_add_u32 m0, s10, 0x4800
	ds_read_b128 v[140:143], v196 offset:38912
	v_mfma_f32_16x16x32_bf16 v[28:31], v[108:111], v[68:71], v[28:31]
	global_load_lds_dwordx4 v194, s[8:9]
	s_add_u32 m0, s10, 0x4c00
	v_mfma_f32_16x16x32_bf16 v[32:35], v[96:99], v[72:75], v[32:35]
	global_load_lds_dwordx4 v195, s[8:9]
	ds_read_b128 v[160:163], v198 offset:49152
	v_mfma_f32_16x16x32_bf16 v[36:39], v[100:103], v[72:75], v[36:39]
	s_add_u32 s2, s2, 0x80
	s_addc_u32 s3, s3, 0
	v_mfma_f32_16x16x32_bf16 v[40:43], v[104:107], v[72:75], v[40:43]
	s_add_u32 s8, s8, 0x80
	s_addc_u32 s9, s9, 0
	ds_read_b128 v[164:167], v198 offset:51200
	v_mfma_f32_16x16x32_bf16 v[44:47], v[108:111], v[72:75], v[44:47]
	v_mfma_f32_16x16x32_bf16 v[48:51], v[96:99], v[76:79], v[48:51]
	ds_read_b128 v[168:171], v198 offset:53248
	v_mfma_f32_16x16x32_bf16 v[52:55], v[100:103], v[76:79], v[52:55]
	v_mfma_f32_16x16x32_bf16 v[56:59], v[104:107], v[76:79], v[56:59]
	ds_read_b128 v[172:175], v198 offset:55296
	v_mfma_f32_16x16x32_bf16 v[60:63], v[108:111], v[76:79], v[60:63]
	v_mfma_f32_16x16x32_bf16 v[0:3], v[112:115], v[80:83], v[0:3]
	ds_read_b128 v[144:147], v197 offset:32768
	v_mfma_f32_16x16x32_bf16 v[4:7], v[116:119], v[80:83], v[4:7]
	v_mfma_f32_16x16x32_bf16 v[8:11], v[120:123], v[80:83], v[8:11]
	ds_read_b128 v[148:151], v197 offset:34816
	v_mfma_f32_16x16x32_bf16 v[12:15], v[124:127], v[80:83], v[12:15]
	v_mfma_f32_16x16x32_bf16 v[16:19], v[112:115], v[84:87], v[16:19]
	ds_read_b128 v[152:155], v197 offset:36864
	v_mfma_f32_16x16x32_bf16 v[20:23], v[116:119], v[84:87], v[20:23]
	v_mfma_f32_16x16x32_bf16 v[24:27], v[120:123], v[84:87], v[24:27]
	ds_read_b128 v[156:159], v197 offset:38912
	v_mfma_f32_16x16x32_bf16 v[28:31], v[124:127], v[84:87], v[28:31]
	v_mfma_f32_16x16x32_bf16 v[32:35], v[112:115], v[88:91], v[32:35]
	ds_read_b128 v[176:179], v199 offset:49152
	v_mfma_f32_16x16x32_bf16 v[36:39], v[116:119], v[88:91], v[36:39]
	v_mfma_f32_16x16x32_bf16 v[40:43], v[120:123], v[88:91], v[40:43]
	ds_read_b128 v[180:183], v199 offset:51200
	v_mfma_f32_16x16x32_bf16 v[44:47], v[124:127], v[88:91], v[44:47]
	v_mfma_f32_16x16x32_bf16 v[48:51], v[112:115], v[92:95], v[48:51]
	ds_read_b128 v[184:187], v199 offset:53248
	v_mfma_f32_16x16x32_bf16 v[52:55], v[116:119], v[92:95], v[52:55]
	v_mfma_f32_16x16x32_bf16 v[56:59], v[120:123], v[92:95], v[56:59]
	ds_read_b128 v[188:191], v199 offset:55296
	v_mfma_f32_16x16x32_bf16 v[60:63], v[124:127], v[92:95], v[60:63]
	s_waitcnt lgkmcnt(0)
	s_waitcnt vmcnt(0)
	s_barrier
	v_mfma_f32_16x16x32_bf16 v[0:3], v[160:163], v[128:131], v[0:3]
	s_add_u32 m0, s10, 0x8000
	ds_read_b128 v[64:67], v196 offset:0
	v_mfma_f32_16x16x32_bf16 v[4:7], v[164:167], v[128:131], v[4:7]
	global_load_lds_dwordx4 v192, s[2:3]
	s_add_u32 m0, s10, 0x8400
	v_mfma_f32_16x16x32_bf16 v[8:11], v[168:171], v[128:131], v[8:11]
	global_load_lds_dwordx4 v193, s[2:3]
	s_add_u32 m0, s10, 0x8800
	ds_read_b128 v[68:71], v196 offset:2048
	v_mfma_f32_16x16x32_bf16 v[12:15], v[172:175], v[128:131], v[12:15]
	global_load_lds_dwordx4 v194, s[2:3]
	s_add_u32 m0, s10, 0x8c00
	v_mfma_f32_16x16x32_bf16 v[16:19], v[160:163], v[132:135], v[16:19]
	global_load_lds_dwordx4 v195, s[2:3]
	s_add_u32 m0, s10, 0xc000
	ds_read_b128 v[72:75], v196 offset:4096
	v_mfma_f32_16x16x32_bf16 v[20:23], v[164:167], v[132:135], v[20:23]
	global_load_lds_dwordx4 v192, s[8:9]
	s_add_u32 m0, s10, 0xc400
	v_mfma_f32_16x16x32_bf16 v[24:27], v[168:171], v[132:135], v[24:27]
	global_load_lds_dwordx4 v193, s[8:9]
	s_add_u32 m0, s10, 0xc800
	ds_read_b128 v[76:79], v196 offset:6144
	v_mfma_f32_16x16x32_bf16 v[28:31], v[172:175], v[132:135], v[28:31]
	global_load_lds_dwordx4 v194, s[8:9]
	s_add_u32 m0, s10, 0xcc00
	v_mfma_f32_16x16x32_bf16 v[32:35], v[160:163], v[136:139], v[32:35]
	global_load_lds_dwordx4 v195, s[8:9]
	ds_read_b128 v[96:99], v198 offset:16384
	v_mfma_f32_16x16x32_bf16 v[36:39], v[164:167], v[136:139], v[36:39]
	s_add_u32 s2, s2, 0x80
	s_addc_u32 s3, s3, 0
	v_mfma_f32_16x16x32_bf16 v[40:43], v[168:171], v[136:139], v[40:43]
	s_add_u32 s8, s8, 0x80
	s_addc_u32 s9, s9, 0
	ds_read_b128 v[100:103], v198 offset:18432
	v_mfma_f32_16x16x32_bf16 v[44:47], v[172:175], v[136:139], v[44:47]
	v_mfma_f32_16x16x32_bf16 v[48:51], v[160:163], v[140:143], v[48:51]
	ds_read_b128 v[104:107], v198 offset:20480
	v_mfma_f32_16x16x32_bf16 v[52:55], v[164:167], v[140:143], v[52:55]
	v_mfma_f32_16x16x32_bf16 v[56:59], v[168:171], v[140:143], v[56:59]
	ds_read_b128 v[108:111], v198 offset:22528
	v_mfma_f32_16x16x32_bf16 v[60:63], v[172:175], v[140:143], v[60:63]
	v_mfma_f32_16x16x32_bf16 v[0:3], v[176:179], v[144:147], v[0:3]
	ds_read_b128 v[80:83], v197 offset:0
	v_mfma_f32_16x16x32_bf16 v[4:7], v[180:183], v[144:147], v[4:7]
	v_mfma_f32_16x16x32_bf16 v[8:11], v[184:187], v[144:147], v[8:11]
	ds_read_b128 v[84:87], v197 offset:2048
	v_mfma_f32_16x16x32_bf16 v[12:15], v[188:191], v[144:147], v[12:15]
	v_mfma_f32_16x16x32_bf16 v[16:19], v[176:179], v[148:151], v[16:19]
	ds_read_b128 v[88:91], v197 offset:4096
	v_mfma_f32_16x16x32_bf16 v[20:23], v[180:183], v[148:151], v[20:23]
	v_mfma_f32_16x16x32_bf16 v[24:27], v[184:187], v[148:151], v[24:27]
	ds_read_b128 v[92:95], v197 offset:6144
	v_mfma_f32_16x16x32_bf16 v[28:31], v[188:191], v[148:151], v[28:31]
	v_mfma_f32_16x16x32_bf16 v[32:35], v[176:179], v[152:155], v[32:35]
	ds_read_b128 v[112:115], v199 offset:16384
	v_mfma_f32_16x16x32_bf16 v[36:39], v[180:183], v[152:155], v[36:39]
	v_mfma_f32_16x16x32_bf16 v[40:43], v[184:187], v[152:155], v[40:43]
	ds_read_b128 v[116:119], v199 offset:18432
	v_mfma_f32_16x16x32_bf16 v[44:47], v[188:191], v[152:155], v[44:47]
	v_mfma_f32_16x16x32_bf16 v[48:51], v[176:179], v[156:159], v[48:51]
	ds_read_b128 v[120:123], v199 offset:20480
	v_mfma_f32_16x16x32_bf16 v[52:55], v[180:183], v[156:159], v[52:55]
	v_mfma_f32_16x16x32_bf16 v[56:59], v[184:187], v[156:159], v[56:59]
	ds_read_b128 v[124:127], v199 offset:22528
	v_mfma_f32_16x16x32_bf16 v[60:63], v[188:191], v[156:159], v[60:63]
	s_waitcnt lgkmcnt(0)
	s_sub_u32 s11, s11, 1
	s_cmp_lg_u32 s11, 0
	s_cbranch_scc1 .Lrs3_loop
	s_waitcnt vmcnt(0)
	s_barrier
	v_mfma_f32_16x16x32_bf16 v[0:3], v[96:99], v[64:67], v[0:3]
	ds_read_b128 v[128:131], v196 offset:32768
	v_mfma_f32_16x16x32_bf16 v[4:7], v[100:103], v[64:67], v[4:7]
	v_mfma_f32_16x16x32_bf16 v[8:11], v[104:107], v[64:67], v[8:11]
	ds_read_b128 v[132:135], v196 offset:34816
	v_mfma_f32_16x16x32_bf16 v[12:15], v[108:111], v[64:67], v[12:15]
	v_mfma_f32_16x16x32_bf16 v[16:19], v[96:99], v[68:71], v[16:19]
	ds_read_b128 v[136:139], v196 offset:36864
	v_mfma_f32_16x16x32_bf16 v[20:23], v[100:103], v[68:71], v[20:23]
	v_mfma_f32_16x16x32_bf16 v[24:27], v[104:107], v[68:71], v[24:27]
	ds_read_b128 v[140:143], v196 offset:38912
	v_mfma_f32_16x16x32_bf16 v[28:31], v[108:111], v[68:71], v[28:31]
	v_mfma_f32_16x16x32_bf16 v[32:35], v[96:99], v[72:75], v[32:35]
	ds_read_b128 v[160:163], v198 offset:49152
	v_mfma_f32_16x16x32_bf16 v[36:39], v[100:103], v[72:75], v[36:39]
	v_mfma_f32_16x16x32_bf16 v[40:43], v[104:107], v[72:75], v[40:43]
	ds_read_b128 v[164:167], v198 offset:51200
	v_mfma_f32_16x16x32_bf16 v[44:47], v[108:111], v[72:75], v[44:47]
	v_mfma_f32_16x16x32_bf16 v[48:51], v[96:99], v[76:79], v[48:51]
	ds_read_b128 v[168:171], v198 offset:53248
	v_mfma_f32_16x16x32_bf16 v[52:55], v[100:103], v[76:79], v[52:55]
	v_mfma_f32_16x16x32_bf16 v[56:59], v[104:107], v[76:79], v[56:59]
	ds_read_b128 v[172:175], v198 offset:55296
	v_mfma_f32_16x16x32_bf16 v[60:63], v[108:111], v[76:79], v[60:63]
	v_mfma_f32_16x16x32_bf16 v[0:3], v[112:115], v[80:83], v[0:3]
	ds_read_b128 v[144:147], v197 offset:32768
	v_mfma_f32_16x16x32_bf16 v[4:7], v[116:119], v[80:83], v[4:7]
	v_mfma_f32_16x16x32_bf16 v[8:11], v[120:123], v[80:83], v[8:11]
	ds_read_b128 v[148:151], v197 offset:34816
	v_mfma_f32_16x16x32_bf16 v[12:15], v[124:127], v[80:83], v[12:15]
	v_mfma_f32_16x16x32_bf16 v[16:19], v[112:115], v[84:87], v[16:19]
	ds_read_b128 v[152:155], v197 offset:36864
	v_mfma_f32_16x16x32_bf16 v[20:23], v[116:119], v[84:87], v[20:23]
	v_mfma_f32_16x16x32_bf16 v[24:27], v[120:123], v[84:87], v[24:27]
	ds_read_b128 v[156:159], v197 offset:38912
	v_mfma_f32_16x16x32_bf16 v[28:31], v[124:127], v[84:87], v[28:31]
	v_mfma_f32_16x16x32_bf16 v[32:35], v[112:115], v[88:91], v[32:35]
	ds_read_b128 v[176:179], v199 offset:49152
	v_mfma_f32_16x16x32_bf16 v[36:39], v[116:119], v[88:91], v[36:39]
	v_mfma_f32_16x16x32_bf16 v[40:43], v[120:123], v[88:91], v[40:43]
	ds_read_b128 v[180:183], v199 offset:51200
	v_mfma_f32_16x16x32_bf16 v[44:47], v[124:127], v[88:91], v[44:47]
	v_mfma_f32_16x16x32_bf16 v[48:51], v[112:115], v[92:95], v[48:51]
	ds_read_b128 v[184:187], v199 offset:53248
	v_mfma_f32_16x16x32_bf16 v[52:55], v[116:119], v[92:95], v[52:55]
	v_mfma_f32_16x16x32_bf16 v[56:59], v[120:123], v[92:95], v[56:59]
	ds_read_b128 v[188:191], v199 offset:55296
	v_mfma_f32_16x16x32_bf16 v[60:63], v[124:127], v[92:95], v[60:63]
	s_waitcnt lgkmcnt(0)
	v_readlane_b32 s2, v253, 6
	v_readlane_b32 s3, v253, 7
	s_lshl_b32 s5, s12, 19
	s_lshl_b32 s8, s13, 9
	s_add_u32 s5, s5, s8
	s_add_u32 s2, s2, s5
	s_addc_u32 s3, s3, 0
	v_and_b32_e32 v196, 63, v216
	v_lshrrev_b32_e32 v197, 6, v216
	v_and_b32_e32 v198, 15, v196
	v_lshrrev_b32_e32 v196, 4, v196
	v_lshlrev_b32_e32 v196, 4, v196
	v_lshl_add_u32 v196, v198, 12, v196
	v_and_b32_e32 v198, 1, v197
	v_lshl_add_u32 v196, v198, 8, v196
	v_lshrrev_b32_e32 v197, 1, v197
	v_lshl_add_u32 v192, v197, 18, v196
	v_add_u32_e32 v193, 0x10000, v192
	v_add_u32_e32 v194, 0x20000, v192
	v_add_u32_e32 v195, 0x30000, v192
	s_nop 1
	global_load_dwordx4 v[64:67], v192, s[2:3]
	global_load_dwordx4 v[68:71], v192, s[2:3] offset:64
	global_load_dwordx4 v[72:75], v192, s[2:3] offset:128
	global_load_dwordx4 v[76:79], v192, s[2:3] offset:192
	global_load_dwordx4 v[80:83], v193, s[2:3]
	global_load_dwordx4 v[84:87], v193, s[2:3] offset:64
	global_load_dwordx4 v[88:91], v193, s[2:3] offset:128
	global_load_dwordx4 v[92:95], v193, s[2:3] offset:192
	global_load_dwordx4 v[96:99], v194, s[2:3]
	global_load_dwordx4 v[100:103], v194, s[2:3] offset:64
	global_load_dwordx4 v[104:107], v194, s[2:3] offset:128
	global_load_dwordx4 v[108:111], v194, s[2:3] offset:192
	global_load_dwordx4 v[112:115], v195, s[2:3]
	global_load_dwordx4 v[116:119], v195, s[2:3] offset:64
	global_load_dwordx4 v[120:123], v195, s[2:3] offset:128
	global_load_dwordx4 v[124:127], v195, s[2:3] offset:192
	v_mfma_f32_16x16x32_bf16 v[0:3], v[160:163], v[128:131], v[0:3]
	v_mfma_f32_16x16x32_bf16 v[4:7], v[164:167], v[128:131], v[4:7]
	v_mfma_f32_16x16x32_bf16 v[8:11], v[168:171], v[128:131], v[8:11]
	v_mfma_f32_16x16x32_bf16 v[12:15], v[172:175], v[128:131], v[12:15]
	v_mfma_f32_16x16x32_bf16 v[16:19], v[160:163], v[132:135], v[16:19]
	v_mfma_f32_16x16x32_bf16 v[20:23], v[164:167], v[132:135], v[20:23]
	v_mfma_f32_16x16x32_bf16 v[24:27], v[168:171], v[132:135], v[24:27]
	v_mfma_f32_16x16x32_bf16 v[28:31], v[172:175], v[132:135], v[28:31]
	v_mfma_f32_16x16x32_bf16 v[32:35], v[160:163], v[136:139], v[32:35]
	v_mfma_f32_16x16x32_bf16 v[36:39], v[164:167], v[136:139], v[36:39]
	v_mfma_f32_16x16x32_bf16 v[40:43], v[168:171], v[136:139], v[40:43]
	v_mfma_f32_16x16x32_bf16 v[44:47], v[172:175], v[136:139], v[44:47]
	v_mfma_f32_16x16x32_bf16 v[48:51], v[160:163], v[140:143], v[48:51]
	v_mfma_f32_16x16x32_bf16 v[52:55], v[164:167], v[140:143], v[52:55]
	v_mfma_f32_16x16x32_bf16 v[56:59], v[168:171], v[140:143], v[56:59]
	v_mfma_f32_16x16x32_bf16 v[60:63], v[172:175], v[140:143], v[60:63]
	v_mfma_f32_16x16x32_bf16 v[0:3], v[176:179], v[144:147], v[0:3]
	v_mfma_f32_16x16x32_bf16 v[4:7], v[180:183], v[144:147], v[4:7]
	v_mfma_f32_16x16x32_bf16 v[8:11], v[184:187], v[144:147], v[8:11]
	v_mfma_f32_16x16x32_bf16 v[12:15], v[188:191], v[144:147], v[12:15]
	v_mfma_f32_16x16x32_bf16 v[16:19], v[176:179], v[148:151], v[16:19]
	v_mfma_f32_16x16x32_bf16 v[20:23], v[180:183], v[148:151], v[20:23]
	v_mfma_f32_16x16x32_bf16 v[24:27], v[184:187], v[148:151], v[24:27]
	v_mfma_f32_16x16x32_bf16 v[28:31], v[188:191], v[148:151], v[28:31]
	v_mfma_f32_16x16x32_bf16 v[32:35], v[176:179], v[152:155], v[32:35]
	v_mfma_f32_16x16x32_bf16 v[36:39], v[180:183], v[152:155], v[36:39]
	v_mfma_f32_16x16x32_bf16 v[40:43], v[184:187], v[152:155], v[40:43]
	v_mfma_f32_16x16x32_bf16 v[44:47], v[188:191], v[152:155], v[44:47]
	v_mfma_f32_16x16x32_bf16 v[48:51], v[176:179], v[156:159], v[48:51]
	v_mfma_f32_16x16x32_bf16 v[52:55], v[180:183], v[156:159], v[52:55]
	v_mfma_f32_16x16x32_bf16 v[56:59], v[184:187], v[156:159], v[56:59]
	v_mfma_f32_16x16x32_bf16 v[60:63], v[188:191], v[156:159], v[60:63]
	s_nop 7
	s_nop 7
	s_waitcnt vmcnt(15)
	v_pk_fma_f32 v[66:67], v[2:3], 0.5, v[66:67] op_sel_hi:[1,0,1]
	v_pk_fma_f32 v[64:65], v[0:1], 0.5, v[64:65] op_sel_hi:[1,0,1]
	global_store_dwordx4 v192, v[64:67], s[2:3]
	s_waitcnt vmcnt(15)
	v_pk_fma_f32 v[70:71], v[6:7], 0.5, v[70:71] op_sel_hi:[1,0,1]
	v_pk_fma_f32 v[68:69], v[4:5], 0.5, v[68:69] op_sel_hi:[1,0,1]
	global_store_dwordx4 v192, v[68:71], s[2:3] offset:64
	s_waitcnt vmcnt(15)
	v_pk_fma_f32 v[74:75], v[10:11], 0.5, v[74:75] op_sel_hi:[1,0,1]
	v_pk_fma_f32 v[72:73], v[8:9], 0.5, v[72:73] op_sel_hi:[1,0,1]
	global_store_dwordx4 v192, v[72:75], s[2:3] offset:128
	s_waitcnt vmcnt(15)
	v_pk_fma_f32 v[78:79], v[14:15], 0.5, v[78:79] op_sel_hi:[1,0,1]
	v_pk_fma_f32 v[76:77], v[12:13], 0.5, v[76:77] op_sel_hi:[1,0,1]
	global_store_dwordx4 v192, v[76:79], s[2:3] offset:192
	s_waitcnt vmcnt(15)
	v_pk_fma_f32 v[82:83], v[18:19], 0.5, v[82:83] op_sel_hi:[1,0,1]
	v_pk_fma_f32 v[80:81], v[16:17], 0.5, v[80:81] op_sel_hi:[1,0,1]
	global_store_dwordx4 v193, v[80:83], s[2:3]
	s_waitcnt vmcnt(15)
	v_pk_fma_f32 v[86:87], v[22:23], 0.5, v[86:87] op_sel_hi:[1,0,1]
	v_pk_fma_f32 v[84:85], v[20:21], 0.5, v[84:85] op_sel_hi:[1,0,1]
	global_store_dwordx4 v193, v[84:87], s[2:3] offset:64
	s_waitcnt vmcnt(15)
	v_pk_fma_f32 v[90:91], v[26:27], 0.5, v[90:91] op_sel_hi:[1,0,1]
	v_pk_fma_f32 v[88:89], v[24:25], 0.5, v[88:89] op_sel_hi:[1,0,1]
	global_store_dwordx4 v193, v[88:91], s[2:3] offset:128
	s_waitcnt vmcnt(15)
	v_pk_fma_f32 v[94:95], v[30:31], 0.5, v[94:95] op_sel_hi:[1,0,1]
	v_pk_fma_f32 v[92:93], v[28:29], 0.5, v[92:93] op_sel_hi:[1,0,1]
	global_store_dwordx4 v193, v[92:95], s[2:3] offset:192
	s_waitcnt vmcnt(15)
	v_pk_fma_f32 v[98:99], v[34:35], 0.5, v[98:99] op_sel_hi:[1,0,1]
	v_pk_fma_f32 v[96:97], v[32:33], 0.5, v[96:97] op_sel_hi:[1,0,1]
	global_store_dwordx4 v194, v[96:99], s[2:3]
	s_waitcnt vmcnt(15)
	v_pk_fma_f32 v[102:103], v[38:39], 0.5, v[102:103] op_sel_hi:[1,0,1]
	v_pk_fma_f32 v[100:101], v[36:37], 0.5, v[100:101] op_sel_hi:[1,0,1]
	global_store_dwordx4 v194, v[100:103], s[2:3] offset:64
	s_waitcnt vmcnt(15)
	v_pk_fma_f32 v[106:107], v[42:43], 0.5, v[106:107] op_sel_hi:[1,0,1]
	v_pk_fma_f32 v[104:105], v[40:41], 0.5, v[104:105] op_sel_hi:[1,0,1]
	global_store_dwordx4 v194, v[104:107], s[2:3] offset:128
	s_waitcnt vmcnt(15)
	v_pk_fma_f32 v[110:111], v[46:47], 0.5, v[110:111] op_sel_hi:[1,0,1]
	v_pk_fma_f32 v[108:109], v[44:45], 0.5, v[108:109] op_sel_hi:[1,0,1]
	global_store_dwordx4 v194, v[108:111], s[2:3] offset:192
	s_waitcnt vmcnt(15)
	v_pk_fma_f32 v[114:115], v[50:51], 0.5, v[114:115] op_sel_hi:[1,0,1]
	v_pk_fma_f32 v[112:113], v[48:49], 0.5, v[112:113] op_sel_hi:[1,0,1]
	global_store_dwordx4 v195, v[112:115], s[2:3]
	s_waitcnt vmcnt(15)
	v_pk_fma_f32 v[118:119], v[54:55], 0.5, v[118:119] op_sel_hi:[1,0,1]
	v_pk_fma_f32 v[116:117], v[52:53], 0.5, v[116:117] op_sel_hi:[1,0,1]
	global_store_dwordx4 v195, v[116:119], s[2:3] offset:64
	s_waitcnt vmcnt(15)
	v_pk_fma_f32 v[122:123], v[58:59], 0.5, v[122:123] op_sel_hi:[1,0,1]
	v_pk_fma_f32 v[120:121], v[56:57], 0.5, v[120:121] op_sel_hi:[1,0,1]
	global_store_dwordx4 v195, v[120:123], s[2:3] offset:128
	s_waitcnt vmcnt(15)
	v_pk_fma_f32 v[126:127], v[62:63], 0.5, v[126:127] op_sel_hi:[1,0,1]
	v_pk_fma_f32 v[124:125], v[60:61], 0.5, v[124:125] op_sel_hi:[1,0,1]
	global_store_dwordx4 v195, v[124:127], s[2:3] offset:192
	s_branch .LBB0_902

	.amdhsa_kernel _Z4mega1P
		.amdhsa_group_segment_fixed_size 65536
		.amdhsa_private_segment_fixed_size 0
		.amdhsa_kernarg_size 640
		.amdhsa_user_sgpr_count 2
		.amdhsa_user_sgpr_dispatch_ptr 0
		.amdhsa_user_sgpr_queue_ptr 0
		.amdhsa_user_sgpr_kernarg_segment_ptr 1
		.amdhsa_user_sgpr_dispatch_id 0
		.amdhsa_user_sgpr_kernarg_preload_length 0
		.amdhsa_user_sgpr_kernarg_preload_offset 0
		.amdhsa_user_sgpr_private_segment_size 0
		.amdhsa_uses_dynamic_stack 0
		.amdhsa_enable_private_segment 0
		.amdhsa_system_sgpr_workgroup_id_x 1
		.amdhsa_system_sgpr_workgroup_id_y 0
		.amdhsa_system_sgpr_workgroup_id_z 0
		.amdhsa_system_sgpr_workgroup_info 0
		.amdhsa_system_vgpr_workitem_id 2
		.amdhsa_next_free_vgpr 256
		.amdhsa_next_free_sgpr 102
		.amdhsa_accum_offset 256
		.amdhsa_reserve_vcc 1
		.amdhsa_float_round_mode_32 0
		.amdhsa_float_round_mode_16_64 0
		.amdhsa_float_denorm_mode_32 3
		.amdhsa_float_denorm_mode_16_64 3
		.amdhsa_dx10_clamp 1
		.amdhsa_ieee_mode 1
		.amdhsa_fp16_overflow 0
		.amdhsa_tg_split 0
		.amdhsa_exception_fp_ieee_invalid_op 0
		.amdhsa_exception_fp_denorm_src 0
		.amdhsa_exception_fp_ieee_div_zero 0
		.amdhsa_exception_fp_ieee_overflow 0
		.amdhsa_exception_fp_ieee_underflow 0
		.amdhsa_exception_fp_ieee_inexact 0
		.amdhsa_exception_int_div_zero 0
	.end_amdhsa_kernel

amdhsa.kernels:
  - .agpr_count:     0
    .args:
      - .offset:         0
        .size:           384
        .value_kind:     by_value
      - .offset:         384
        .size:           4
        .value_kind:     hidden_block_count_x
      - .offset:         388
        .size:           4
        .value_kind:     hidden_block_count_y
      - .offset:         392
        .size:           4
        .value_kind:     hidden_block_count_z
      - .offset:         396
        .size:           2
        .value_kind:     hidden_group_size_x
      - .offset:         398
        .size:           2
        .value_kind:     hidden_group_size_y
      - .offset:         400
        .size:           2
        .value_kind:     hidden_group_size_z
      - .offset:         402
        .size:           2
        .value_kind:     hidden_remainder_x
      - .offset:         404
        .size:           2
        .value_kind:     hidden_remainder_y
      - .offset:         406
        .size:           2
        .value_kind:     hidden_remainder_z
      - .offset:         424
        .size:           8
        .value_kind:     hidden_global_offset_x
      - .offset:         432
        .size:           8
        .value_kind:     hidden_global_offset_y
      - .offset:         440
        .size:           8
        .value_kind:     hidden_global_offset_z
      - .offset:         448
        .size:           2
        .value_kind:     hidden_grid_dims
      - .offset:         472
        .size:           8
        .value_kind:     hidden_multigrid_sync_arg
    .group_segment_fixed_size: 65536
    .kernarg_segment_align: 8
    .kernarg_segment_size: 640
    .language:       OpenCL C
    .language_version:
      - 2
      - 0
    .max_flat_workgroup_size: 256
    .name:           _Z4mega1P
    .private_segment_fixed_size: 0
    .sgpr_count:     108
    .sgpr_spill_count: 273
    .symbol:         _Z4mega1P.kd
    .uniform_work_group_size: 1
    .uses_dynamic_stack: false
    .vgpr_count:     256
    .vgpr_spill_count: 0
    .wavefront_size: 64
